# K-loops: in the 6-DMA load segments the first LDS-DMA address add moves behind the ds_reads so the segment opens with LDS reads
# speedup vs baseline: 1.0084x; 1.0084x over previous
; #define PG8_STAGE(bufoff, gbase, voff) do { _Pragma("unroll") for (int _i = 0; _i < 2; ++_i) \
;         __builtin_amdgcn_global_load_lds((const unsigned*)((const char*)(gbase) + (voff)[_i]), (PG8_LAS unsigned*)(lds + (bufoff) + ldsw + _i * 8192), 16, 0, 0); } while (0)
; #define PG8_LDA(dst, b, h) do { _Pragma("unroll") for (int m = 0; m < 4; ++m) _Pragma("unroll") for (int k = 0; k < 2; ++k) dst[m][k] = *(const PG8_LAS bf16x8*)(lds + PG8_SA(b, h) + aoff + m * 2048 + k * 1024); } while (0)
; #define PG8_LDB(dst, b, h) do { _Pragma("unroll") for (int n = 0; n < 2; ++n) _Pragma("unroll") for (int k = 0; k < 2; ++k) dst[n][k] = *(const PG8_LAS bf16x8*)(lds + PG8_SB(b, h) + boff + n * 2048 + k * 1024); } while (0)
; #define PG8_MMA(ai, bj, At, Bt) do { __builtin_amdgcn_s_setprio(1); _Pragma("unroll") for (int m = 0; m < 4; ++m) _Pragma("unroll") for (int n = 0; n < 2; ++n) _Pragma("unroll") for (int k = 0; k < 2; ++k) \
;         acc[ai][bj][m][n] = __builtin_amdgcn_mfma_f32_16x16x32_bf16(Bt[n][k], At[m][k], acc[ai][bj][m][n], 0, 0, 0); __builtin_amdgcn_s_setprio(0); } while (0)
; #define PG8_WAIT_V(n) asm volatile("s_waitcnt vmcnt(" #n ")" ::: "memory")
; #define PG8_WAIT_L(n) asm volatile("s_waitcnt lgkmcnt(" #n ")" ::: "memory")
; #define PG8_BAR __builtin_amdgcn_s_barrier()
; #define PG8_SCHED __builtin_amdgcn_sched_barrier(0)
;     ...
;             const char* a1 = cA + (size_t)(t + 1) * kstep;
;             const char* a2 = last ? nA : cA + (size_t)(t + 2) * kstep; const char* b2 = last ? nB : cB + (size_t)(t + 2) * kstep;
;             const char* a3 = a2 + kstep; const char* b3 = b2 + kstep;
;             if (last && has_next) S.a_ready(nxt);
;             if constexpr (SP2) {
;             PG8_LDB(B0, 0, 0); PG8_LDB(B1, 0, 1); PG8_SCHED; PG8_LDA(At, 0, 0); PG8_STAGE(PG8_SA(1, 1), a1 + hstepA, voffA);
;             PG8_WAIT_V(8); PG8_WAIT_L(0); PG8_BAR; PG8_MMA(0, 0, At, B0); PG8_MMA(0, 1, At, B1); PG8_BAR; PG8_SCHED;
;             PG8_LDA(At, 0, 1); PG8_STAGE(PG8_SB(0, 0), b2, voffB); PG8_STAGE(PG8_SB(0, 1), b2 + hstepB, voffB); PG8_STAGE(PG8_SA(0, 0), a2, voffA);
.LBB0_228:
	ds_read_b128 v[128:131], v201
	ds_read_b128 v[132:135], v201 offset:1024
	ds_read_b128 v[136:139], v201 offset:2048
	ds_read_b128 v[140:143], v201 offset:3072
	ds_read_b128 v[144:147], v205
	ds_read_b128 v[148:151], v205 offset:1024
	ds_read_b128 v[152:155], v205 offset:2048
	ds_read_b128 v[156:159], v205 offset:3072
	s_add_u32 s34, s28, 0xfffc0080
	s_addc_u32 s35, s29, -1
	s_cmp_eq_u32 s63, 12
	s_cselect_b32 s41, s42, s35
	s_cselect_b32 s40, s43, s34
	s_cselect_b32 s35, s44, s53
	s_cselect_b32 s34, s45, s51
	v_lshl_add_u64 v[192:193], s[28:29], 0, v[184:185]
	s_add_i32 m0, s61, 0xc000
	ds_read_b128 v[160:163], v207
	ds_read_b128 v[164:167], v207 offset:1024
	ds_read_b128 v[210:213], v207 offset:2048
	ds_read_b128 v[214:217], v207 offset:3072
	ds_read_b128 v[218:221], v207 offset:4096
	ds_read_b128 v[222:225], v207 offset:5120
	ds_read_b128 v[226:229], v207 offset:6144
	ds_read_b128 v[234:237], v207 offset:7168
	global_load_lds_dwordx4 v[192:193], off
	v_lshl_add_u64 v[192:193], s[28:29], 0, v[186:187]
	s_add_i32 m0, s61, 0xe000
	s_nop 0
	global_load_lds_dwordx4 v[192:193], off
	s_waitcnt vmcnt(8)
	s_waitcnt lgkmcnt(0)
	s_barrier
	s_setprio 1
	s_waitcnt lgkmcnt(0)
	v_mfma_f32_16x16x32_bf16 v[124:127], v[128:131], v[160:163], v[124:127]
	v_mfma_f32_16x16x32_bf16 v[120:123], v[136:139], v[160:163], v[120:123]
	v_mfma_f32_16x16x32_bf16 v[108:111], v[128:131], v[210:213], v[108:111]
	v_mfma_f32_16x16x32_bf16 v[104:107], v[136:139], v[210:213], v[104:107]
	v_mfma_f32_16x16x32_bf16 v[92:95], v[128:131], v[218:221], v[92:95]
	v_mfma_f32_16x16x32_bf16 v[88:91], v[136:139], v[218:221], v[88:91]
	v_mfma_f32_16x16x32_bf16 v[76:79], v[128:131], v[226:229], v[76:79]
	v_mfma_f32_16x16x32_bf16 v[72:75], v[136:139], v[226:229], v[72:75]
	v_mfma_f32_16x16x32_bf16 v[124:127], v[132:135], v[164:167], v[124:127]
	v_mfma_f32_16x16x32_bf16 v[120:123], v[140:143], v[164:167], v[120:123]
	v_mfma_f32_16x16x32_bf16 v[108:111], v[132:135], v[214:217], v[108:111]
	v_mfma_f32_16x16x32_bf16 v[104:107], v[140:143], v[214:217], v[104:107]
	v_mfma_f32_16x16x32_bf16 v[92:95], v[132:135], v[222:225], v[92:95]
	v_mfma_f32_16x16x32_bf16 v[88:91], v[140:143], v[222:225], v[88:91]
	v_mfma_f32_16x16x32_bf16 v[76:79], v[132:135], v[234:237], v[76:79]
	v_mfma_f32_16x16x32_bf16 v[72:75], v[140:143], v[234:237], v[72:75]
	s_setprio 0
	s_setprio 1
	v_mfma_f32_16x16x32_bf16 v[116:119], v[144:147], v[160:163], v[116:119]
	v_mfma_f32_16x16x32_bf16 v[112:115], v[152:155], v[160:163], v[112:115]
	v_mfma_f32_16x16x32_bf16 v[100:103], v[144:147], v[210:213], v[100:103]
	v_mfma_f32_16x16x32_bf16 v[96:99], v[152:155], v[210:213], v[96:99]
	v_mfma_f32_16x16x32_bf16 v[84:87], v[144:147], v[218:221], v[84:87]
	v_mfma_f32_16x16x32_bf16 v[80:83], v[152:155], v[218:221], v[80:83]
	v_mfma_f32_16x16x32_bf16 v[68:71], v[144:147], v[226:229], v[68:71]
	v_mfma_f32_16x16x32_bf16 v[64:67], v[152:155], v[226:229], v[64:67]
	v_mfma_f32_16x16x32_bf16 v[116:119], v[148:151], v[164:167], v[116:119]
	v_mfma_f32_16x16x32_bf16 v[112:115], v[156:159], v[164:167], v[112:115]
	v_mfma_f32_16x16x32_bf16 v[100:103], v[148:151], v[214:217], v[100:103]
	v_mfma_f32_16x16x32_bf16 v[96:99], v[156:159], v[214:217], v[96:99]
	v_mfma_f32_16x16x32_bf16 v[84:87], v[148:151], v[222:225], v[84:87]
	v_mfma_f32_16x16x32_bf16 v[80:83], v[156:159], v[222:225], v[80:83]
	v_mfma_f32_16x16x32_bf16 v[68:71], v[148:151], v[234:237], v[68:71]
	v_mfma_f32_16x16x32_bf16 v[64:67], v[156:159], v[234:237], v[64:67]
	s_setprio 0
	s_barrier
	s_add_i32 s85, s79, s65
	s_mov_b32 m0, s85
	ds_read_b128 v[160:163], v207 offset:16384
	ds_read_b128 v[164:167], v207 offset:17408
	ds_read_b128 v[210:213], v207 offset:18432
	ds_read_b128 v[214:217], v207 offset:19456
	ds_read_b128 v[218:221], v207 offset:20480
	ds_read_b128 v[222:225], v207 offset:21504
	ds_read_b128 v[226:229], v207 offset:22528
	ds_read_b128 v[234:237], v207 offset:23552
	v_lshl_add_u64 v[192:193], s[34:35], 0, v[176:177]
	global_load_lds_dwordx4 v[192:193], off
	s_add_i32 m0, s85, 0x2000
	s_add_u32 s86, s34, 0x40000
	v_lshl_add_u64 v[202:203], s[34:35], 0, v[180:181]
	s_addc_u32 s87, s35, 0
	s_add_i32 s85, s80, s65
	global_load_lds_dwordx4 v[202:203], off
	v_lshl_add_u64 v[230:231], s[86:87], 0, v[176:177]
	s_mov_b32 m0, s85
	v_lshl_add_u64 v[238:239], s[40:41], 0, v[178:179]
	global_load_lds_dwordx4 v[230:231], off
	v_lshl_add_u64 v[230:231], s[86:87], 0, v[180:181]
	s_add_i32 m0, s85, 0x2000
	s_nop 0
	global_load_lds_dwordx4 v[230:231], off
	v_lshl_add_u64 v[230:231], s[40:41], 0, v[174:175]
	s_mov_b32 m0, s61
	s_nop 0
	global_load_lds_dwordx4 v[230:231], off
	s_mov_b32 m0, s66
	s_nop 0
	global_load_lds_dwordx4 v[238:239], off
	s_waitcnt vmcnt(8)
	s_waitcnt lgkmcnt(0)
	s_barrier
; #define PG8_STAGE(bufoff, gbase, voff) do { _Pragma("unroll") for (int _i = 0; _i < 2; ++_i) \
;         __builtin_amdgcn_global_load_lds((const unsigned*)((const char*)(gbase) + (voff)[_i]), (PG8_LAS unsigned*)(lds + (bufoff) + ldsw + _i * 8192), 16, 0, 0); } while (0)
; #define PG8_LDA(dst, b, h) do { _Pragma("unroll") for (int m = 0; m < 4; ++m) _Pragma("unroll") for (int k = 0; k < 2; ++k) dst[m][k] = *(const PG8_LAS bf16x8*)(lds + PG8_SA(b, h) + aoff + m * 2048 + k * 1024); } while (0)
; #define PG8_LDB(dst, b, h) do { _Pragma("unroll") for (int n = 0; n < 2; ++n) _Pragma("unroll") for (int k = 0; k < 2; ++k) dst[n][k] = *(const PG8_LAS bf16x8*)(lds + PG8_SB(b, h) + boff + n * 2048 + k * 1024); } while (0)
; #define PG8_MMA(ai, bj, At, Bt) do { __builtin_amdgcn_s_setprio(1); _Pragma("unroll") for (int m = 0; m < 4; ++m) _Pragma("unroll") for (int n = 0; n < 2; ++n) _Pragma("unroll") for (int k = 0; k < 2; ++k) \
;         acc[ai][bj][m][n] = __builtin_amdgcn_mfma_f32_16x16x32_bf16(Bt[n][k], At[m][k], acc[ai][bj][m][n], 0, 0, 0); __builtin_amdgcn_s_setprio(0); } while (0)
; #define PG8_WAIT_V(n) asm volatile("s_waitcnt vmcnt(" #n ")" ::: "memory")
; #define PG8_WAIT_L(n) asm volatile("s_waitcnt lgkmcnt(" #n ")" ::: "memory")
; #define PG8_BAR __builtin_amdgcn_s_barrier()
; #define PG8_SCHED __builtin_amdgcn_sched_barrier(0)
;     ...
;             PG8_LDA(At, 0, 1); PG8_STAGE(PG8_SB(0, 0), b2, voffB); PG8_STAGE(PG8_SB(0, 1), b2 + hstepB, voffB); PG8_STAGE(PG8_SA(0, 0), a2, voffA);
;             PG8_WAIT_V(8); PG8_WAIT_L(0); PG8_BAR; PG8_MMA(1, 0, At, B0); PG8_MMA(1, 1, At, B1); PG8_BAR; PG8_SCHED;
;             PG8_LDB(B0, 1, 0); PG8_LDB(B1, 1, 1); PG8_SCHED; PG8_LDA(At, 1, 0); PG8_STAGE(PG8_SA(0, 1), a2 + hstepA, voffA);
;             PG8_WAIT_V(8); PG8_WAIT_L(0); PG8_BAR; PG8_MMA(0, 0, At, B0); PG8_MMA(0, 1, At, B1); PG8_BAR; PG8_SCHED;
	s_setprio 1
	s_waitcnt lgkmcnt(0)
	v_mfma_f32_16x16x32_bf16 v[60:63], v[128:131], v[160:163], v[60:63]
	v_mfma_f32_16x16x32_bf16 v[56:59], v[136:139], v[160:163], v[56:59]
	v_mfma_f32_16x16x32_bf16 v[44:47], v[128:131], v[210:213], v[44:47]
	v_mfma_f32_16x16x32_bf16 v[40:43], v[136:139], v[210:213], v[40:43]
	v_mfma_f32_16x16x32_bf16 v[28:31], v[128:131], v[218:221], v[28:31]
	v_mfma_f32_16x16x32_bf16 v[24:27], v[136:139], v[218:221], v[24:27]
	v_mfma_f32_16x16x32_bf16 v[12:15], v[128:131], v[226:229], v[12:15]
	v_mfma_f32_16x16x32_bf16 v[8:11], v[136:139], v[226:229], v[8:11]
	v_mfma_f32_16x16x32_bf16 v[60:63], v[132:135], v[164:167], v[60:63]
	v_mfma_f32_16x16x32_bf16 v[56:59], v[140:143], v[164:167], v[56:59]
	v_mfma_f32_16x16x32_bf16 v[44:47], v[132:135], v[214:217], v[44:47]
	v_mfma_f32_16x16x32_bf16 v[40:43], v[140:143], v[214:217], v[40:43]
	v_mfma_f32_16x16x32_bf16 v[28:31], v[132:135], v[222:225], v[28:31]
	v_mfma_f32_16x16x32_bf16 v[24:27], v[140:143], v[222:225], v[24:27]
	v_mfma_f32_16x16x32_bf16 v[12:15], v[132:135], v[234:237], v[12:15]
	v_mfma_f32_16x16x32_bf16 v[8:11], v[140:143], v[234:237], v[8:11]
	s_setprio 0
	s_setprio 1
	v_mfma_f32_16x16x32_bf16 v[52:55], v[144:147], v[160:163], v[52:55]
	v_mfma_f32_16x16x32_bf16 v[48:51], v[152:155], v[160:163], v[48:51]
	v_mfma_f32_16x16x32_bf16 v[36:39], v[144:147], v[210:213], v[36:39]
	v_mfma_f32_16x16x32_bf16 v[32:35], v[152:155], v[210:213], v[32:35]
	v_mfma_f32_16x16x32_bf16 v[20:23], v[144:147], v[218:221], v[20:23]
	v_mfma_f32_16x16x32_bf16 v[16:19], v[152:155], v[218:221], v[16:19]
	v_mfma_f32_16x16x32_bf16 v[4:7], v[144:147], v[226:229], v[4:7]
	v_mfma_f32_16x16x32_bf16 v[0:3], v[152:155], v[226:229], v[0:3]
	v_mfma_f32_16x16x32_bf16 v[52:55], v[148:151], v[164:167], v[52:55]
	v_mfma_f32_16x16x32_bf16 v[48:51], v[156:159], v[164:167], v[48:51]
	v_mfma_f32_16x16x32_bf16 v[36:39], v[148:151], v[214:217], v[36:39]
	v_mfma_f32_16x16x32_bf16 v[32:35], v[156:159], v[214:217], v[32:35]
	v_mfma_f32_16x16x32_bf16 v[20:23], v[148:151], v[222:225], v[20:23]
	v_mfma_f32_16x16x32_bf16 v[16:19], v[156:159], v[222:225], v[16:19]
	v_mfma_f32_16x16x32_bf16 v[4:7], v[148:151], v[234:237], v[4:7]
	v_mfma_f32_16x16x32_bf16 v[0:3], v[156:159], v[234:237], v[0:3]
	s_setprio 0
	s_barrier
	s_add_i32 s85, 0, 0x18000
	s_add_i32 s86, 0, 0x1c000
	v_add_u32_e32 v140, s85, v199
	v_add_u32_e32 v156, s86, v199
	ds_read_b128 v[128:131], v140
	ds_read_b128 v[132:135], v140 offset:1024
	ds_read_b128 v[136:139], v140 offset:2048
	ds_read_b128 v[140:143], v140 offset:3072
	ds_read_b128 v[144:147], v156
	ds_read_b128 v[148:151], v156 offset:1024
	ds_read_b128 v[152:155], v156 offset:2048
	ds_read_b128 v[156:159], v156 offset:3072
	s_add_u32 s40, s40, 0x40000
	s_addc_u32 s41, s41, 0
	s_mov_b32 m0, s67
	v_lshl_add_u64 v[240:241], s[40:41], 0, v[174:175]
	ds_read_b128 v[160:163], v207 offset:32768
	ds_read_b128 v[164:167], v207 offset:33792
	ds_read_b128 v[210:213], v207 offset:34816
	ds_read_b128 v[214:217], v207 offset:35840
	ds_read_b128 v[218:221], v207 offset:36864
	ds_read_b128 v[222:225], v207 offset:37888
	ds_read_b128 v[226:229], v207 offset:38912
	ds_read_b128 v[234:237], v207 offset:39936
	global_load_lds_dwordx4 v[240:241], off
	v_lshl_add_u64 v[240:241], s[40:41], 0, v[178:179]
	s_mov_b32 m0, s68
	s_nop 0
	global_load_lds_dwordx4 v[240:241], off
	s_waitcnt vmcnt(8)
	s_waitcnt lgkmcnt(0)
	s_barrier
	s_setprio 1
	s_waitcnt lgkmcnt(0)
	v_mfma_f32_16x16x32_bf16 v[124:127], v[128:131], v[160:163], v[124:127]
	v_mfma_f32_16x16x32_bf16 v[120:123], v[136:139], v[160:163], v[120:123]
	v_mfma_f32_16x16x32_bf16 v[108:111], v[128:131], v[210:213], v[108:111]
	v_mfma_f32_16x16x32_bf16 v[104:107], v[136:139], v[210:213], v[104:107]
	v_mfma_f32_16x16x32_bf16 v[92:95], v[128:131], v[218:221], v[92:95]
	v_mfma_f32_16x16x32_bf16 v[88:91], v[136:139], v[218:221], v[88:91]
	v_mfma_f32_16x16x32_bf16 v[76:79], v[128:131], v[226:229], v[76:79]
	v_mfma_f32_16x16x32_bf16 v[72:75], v[136:139], v[226:229], v[72:75]
	v_mfma_f32_16x16x32_bf16 v[124:127], v[132:135], v[164:167], v[124:127]
	v_mfma_f32_16x16x32_bf16 v[120:123], v[140:143], v[164:167], v[120:123]
	v_mfma_f32_16x16x32_bf16 v[108:111], v[132:135], v[214:217], v[108:111]
	v_mfma_f32_16x16x32_bf16 v[104:107], v[140:143], v[214:217], v[104:107]
	v_mfma_f32_16x16x32_bf16 v[92:95], v[132:135], v[222:225], v[92:95]
	v_mfma_f32_16x16x32_bf16 v[88:91], v[140:143], v[222:225], v[88:91]
	v_mfma_f32_16x16x32_bf16 v[76:79], v[132:135], v[234:237], v[76:79]
	v_mfma_f32_16x16x32_bf16 v[72:75], v[140:143], v[234:237], v[72:75]
	s_setprio 0
	s_setprio 1
	v_mfma_f32_16x16x32_bf16 v[116:119], v[144:147], v[160:163], v[116:119]
	v_mfma_f32_16x16x32_bf16 v[112:115], v[152:155], v[160:163], v[112:115]
	v_mfma_f32_16x16x32_bf16 v[100:103], v[144:147], v[210:213], v[100:103]
	v_mfma_f32_16x16x32_bf16 v[96:99], v[152:155], v[210:213], v[96:99]
	v_mfma_f32_16x16x32_bf16 v[84:87], v[144:147], v[218:221], v[84:87]
	v_mfma_f32_16x16x32_bf16 v[80:83], v[152:155], v[218:221], v[80:83]
	v_mfma_f32_16x16x32_bf16 v[68:71], v[144:147], v[226:229], v[68:71]
	v_mfma_f32_16x16x32_bf16 v[64:67], v[152:155], v[226:229], v[64:67]
	v_mfma_f32_16x16x32_bf16 v[116:119], v[148:151], v[164:167], v[116:119]
	v_mfma_f32_16x16x32_bf16 v[112:115], v[156:159], v[164:167], v[112:115]
	v_mfma_f32_16x16x32_bf16 v[100:103], v[148:151], v[214:217], v[100:103]
	v_mfma_f32_16x16x32_bf16 v[96:99], v[156:159], v[214:217], v[96:99]
	v_mfma_f32_16x16x32_bf16 v[84:87], v[148:151], v[222:225], v[84:87]
	v_mfma_f32_16x16x32_bf16 v[80:83], v[156:159], v[222:225], v[80:83]
	v_mfma_f32_16x16x32_bf16 v[68:71], v[148:151], v[234:237], v[68:71]
	v_mfma_f32_16x16x32_bf16 v[64:67], v[156:159], v[234:237], v[64:67]
	s_setprio 0
	s_barrier
; #define PG8_STAGE(bufoff, gbase, voff) do { _Pragma("unroll") for (int _i = 0; _i < 2; ++_i) \
;         __builtin_amdgcn_global_load_lds((const unsigned*)((const char*)(gbase) + (voff)[_i]), (PG8_LAS unsigned*)(lds + (bufoff) + ldsw + _i * 8192), 16, 0, 0); } while (0)
; #define PG8_LDA(dst, b, h) do { _Pragma("unroll") for (int m = 0; m < 4; ++m) _Pragma("unroll") for (int k = 0; k < 2; ++k) dst[m][k] = *(const PG8_LAS bf16x8*)(lds + PG8_SA(b, h) + aoff + m * 2048 + k * 1024); } while (0)
; #define PG8_MMA(ai, bj, At, Bt) do { __builtin_amdgcn_s_setprio(1); _Pragma("unroll") for (int m = 0; m < 4; ++m) _Pragma("unroll") for (int n = 0; n < 2; ++n) _Pragma("unroll") for (int k = 0; k < 2; ++k) \
;         acc[ai][bj][m][n] = __builtin_amdgcn_mfma_f32_16x16x32_bf16(Bt[n][k], At[m][k], acc[ai][bj][m][n], 0, 0, 0); __builtin_amdgcn_s_setprio(0); } while (0)
; #define PG8_WAIT_V(n) asm volatile("s_waitcnt vmcnt(" #n ")" ::: "memory")
; #define PG8_WAIT_L(n) asm volatile("s_waitcnt lgkmcnt(" #n ")" ::: "memory")
; #define PG8_BAR __builtin_amdgcn_s_barrier()
; #define PG8_SCHED __builtin_amdgcn_sched_barrier(0)
;     ...
;             PG8_LDA(At, 1, 1); PG8_STAGE(PG8_SB(1, 0), b3, voffB); PG8_STAGE(PG8_SB(1, 1), b3 + hstepB, voffB); PG8_STAGE(PG8_SA(1, 0), a3, voffA);
;             PG8_WAIT_V(8); PG8_WAIT_L(0); PG8_BAR; PG8_MMA(1, 0, At, B0); PG8_MMA(1, 1, At, B1); PG8_BAR; PG8_SCHED;
;     ...
;         if constexpr (ALIGN_EPI) { if (wr == 0) PG8_BAR; }
	s_add_i32 s40, s85, s65
	s_mov_b32 m0, s40
	ds_read_b128 v[160:163], v207 offset:49152
	ds_read_b128 v[164:167], v207 offset:50176
	ds_read_b128 v[210:213], v207 offset:51200
	ds_read_b128 v[214:217], v207 offset:52224
	ds_read_b128 v[218:221], v207 offset:53248
	ds_read_b128 v[222:225], v207 offset:54272
	ds_read_b128 v[226:229], v207 offset:55296
	ds_read_b128 v[234:237], v207 offset:56320
	v_lshl_add_u64 v[192:193], v[192:193], 0, s[26:27]
	global_load_lds_dwordx4 v[192:193], off
	s_add_i32 m0, s40, 0x2000
	s_add_u32 s34, s34, 0x40080
	v_lshl_add_u64 v[192:193], v[202:203], 0, s[26:27]
	s_addc_u32 s35, s35, 0
	s_add_i32 s40, s86, s65
	global_load_lds_dwordx4 v[192:193], off
	v_lshl_add_u64 v[192:193], s[34:35], 0, v[176:177]
	s_mov_b32 m0, s40
	s_nop 0
	global_load_lds_dwordx4 v[192:193], off
	v_lshl_add_u64 v[192:193], s[34:35], 0, v[180:181]
	s_add_i32 m0, s40, 0x2000
	s_nop 0
	global_load_lds_dwordx4 v[192:193], off
	v_lshl_add_u64 v[192:193], v[230:231], 0, s[26:27]
	s_mov_b32 m0, s76
	s_nop 0
	global_load_lds_dwordx4 v[192:193], off
	v_lshl_add_u64 v[192:193], v[238:239], 0, s[26:27]
	s_mov_b32 m0, s77
	s_nop 0
	global_load_lds_dwordx4 v[192:193], off
	s_waitcnt vmcnt(8)
	s_waitcnt lgkmcnt(0)
	s_barrier
	s_setprio 1
	s_waitcnt lgkmcnt(0)
	v_mfma_f32_16x16x32_bf16 v[60:63], v[128:131], v[160:163], v[60:63]
	v_mfma_f32_16x16x32_bf16 v[56:59], v[136:139], v[160:163], v[56:59]
	v_mfma_f32_16x16x32_bf16 v[44:47], v[128:131], v[210:213], v[44:47]
	v_mfma_f32_16x16x32_bf16 v[40:43], v[136:139], v[210:213], v[40:43]
	v_mfma_f32_16x16x32_bf16 v[28:31], v[128:131], v[218:221], v[28:31]
	v_mfma_f32_16x16x32_bf16 v[24:27], v[136:139], v[218:221], v[24:27]
	v_mfma_f32_16x16x32_bf16 v[12:15], v[128:131], v[226:229], v[12:15]
	v_mfma_f32_16x16x32_bf16 v[8:11], v[136:139], v[226:229], v[8:11]
	v_mfma_f32_16x16x32_bf16 v[60:63], v[132:135], v[164:167], v[60:63]
	v_mfma_f32_16x16x32_bf16 v[56:59], v[140:143], v[164:167], v[56:59]
	v_mfma_f32_16x16x32_bf16 v[44:47], v[132:135], v[214:217], v[44:47]
	v_mfma_f32_16x16x32_bf16 v[40:43], v[140:143], v[214:217], v[40:43]
	v_mfma_f32_16x16x32_bf16 v[28:31], v[132:135], v[222:225], v[28:31]
	v_mfma_f32_16x16x32_bf16 v[24:27], v[140:143], v[222:225], v[24:27]
	v_mfma_f32_16x16x32_bf16 v[12:15], v[132:135], v[234:237], v[12:15]
	v_mfma_f32_16x16x32_bf16 v[8:11], v[140:143], v[234:237], v[8:11]
	s_setprio 0
	s_setprio 1
	v_mfma_f32_16x16x32_bf16 v[52:55], v[144:147], v[160:163], v[52:55]
	v_mfma_f32_16x16x32_bf16 v[48:51], v[152:155], v[160:163], v[48:51]
	v_mfma_f32_16x16x32_bf16 v[36:39], v[144:147], v[210:213], v[36:39]
	v_mfma_f32_16x16x32_bf16 v[32:35], v[152:155], v[210:213], v[32:35]
	v_mfma_f32_16x16x32_bf16 v[20:23], v[144:147], v[218:221], v[20:23]
	v_mfma_f32_16x16x32_bf16 v[16:19], v[152:155], v[218:221], v[16:19]
	v_mfma_f32_16x16x32_bf16 v[4:7], v[144:147], v[226:229], v[4:7]
	v_mfma_f32_16x16x32_bf16 v[0:3], v[152:155], v[226:229], v[0:3]
	v_mfma_f32_16x16x32_bf16 v[52:55], v[148:151], v[164:167], v[52:55]
	v_mfma_f32_16x16x32_bf16 v[48:51], v[156:159], v[164:167], v[48:51]
	v_mfma_f32_16x16x32_bf16 v[36:39], v[148:151], v[214:217], v[36:39]
	v_mfma_f32_16x16x32_bf16 v[32:35], v[156:159], v[214:217], v[32:35]
	v_mfma_f32_16x16x32_bf16 v[20:23], v[148:151], v[222:225], v[20:23]
	v_mfma_f32_16x16x32_bf16 v[16:19], v[156:159], v[222:225], v[16:19]
	v_mfma_f32_16x16x32_bf16 v[4:7], v[148:151], v[234:237], v[4:7]
	v_mfma_f32_16x16x32_bf16 v[0:3], v[156:159], v[234:237], v[0:3]
	s_setprio 0
	s_barrier
	s_add_i32 s63, s63, 2
	s_add_u32 s28, s28, 0x100
	s_addc_u32 s29, s29, 0
	s_add_u32 s51, s51, 0x100
	s_addc_u32 s53, s53, 0
	s_cmp_gt_u32 s63, 13
	s_cbranch_scc0 .LBB0_228
	s_and_b64 vcc, exec, s[36:37]
	s_cbranch_vccz .LBB0_231
	s_barrier

; #define PG8_STAGE(bufoff, gbase, voff) do { _Pragma("unroll") for (int _i = 0; _i < 2; ++_i) \
;         __builtin_amdgcn_global_load_lds((const unsigned*)((const char*)(gbase) + (voff)[_i]), (PG8_LAS unsigned*)(lds + (bufoff) + ldsw + _i * 8192), 16, 0, 0); } while (0)
; #define PG8_LDA(dst, b, h) do { _Pragma("unroll") for (int m = 0; m < 4; ++m) _Pragma("unroll") for (int k = 0; k < 2; ++k) dst[m][k] = *(const PG8_LAS bf16x8*)(lds + PG8_SA(b, h) + aoff + m * 2048 + k * 1024); } while (0)
; #define PG8_LDB(dst, b, h) do { _Pragma("unroll") for (int n = 0; n < 2; ++n) _Pragma("unroll") for (int k = 0; k < 2; ++k) dst[n][k] = *(const PG8_LAS bf16x8*)(lds + PG8_SB(b, h) + boff + n * 2048 + k * 1024); } while (0)
; #define PG8_MMA(ai, bj, At, Bt) do { __builtin_amdgcn_s_setprio(1); _Pragma("unroll") for (int m = 0; m < 4; ++m) _Pragma("unroll") for (int n = 0; n < 2; ++n) _Pragma("unroll") for (int k = 0; k < 2; ++k) \
;         acc[ai][bj][m][n] = __builtin_amdgcn_mfma_f32_16x16x32_bf16(Bt[n][k], At[m][k], acc[ai][bj][m][n], 0, 0, 0); __builtin_amdgcn_s_setprio(0); } while (0)
; #define PG8_WAIT_V(n) asm volatile("s_waitcnt vmcnt(" #n ")" ::: "memory")
; #define PG8_WAIT_L(n) asm volatile("s_waitcnt lgkmcnt(" #n ")" ::: "memory")
; #define PG8_BAR __builtin_amdgcn_s_barrier()
; #define PG8_SCHED __builtin_amdgcn_sched_barrier(0)
;     ...
;             const char* a1 = cA + (size_t)(t + 1) * kstep;
;             const char* a2 = last ? nA : cA + (size_t)(t + 2) * kstep; const char* b2 = last ? nB : cB + (size_t)(t + 2) * kstep;
;             const char* a3 = a2 + kstep; const char* b3 = b2 + kstep;
;             if (last && has_next) S.a_ready(nxt);
;             if constexpr (SP2) {
;             PG8_LDB(B0, 0, 0); PG8_LDB(B1, 0, 1); PG8_SCHED; PG8_LDA(At, 0, 0); PG8_STAGE(PG8_SA(1, 1), a1 + hstepA, voffA);
;             PG8_WAIT_V(8); PG8_WAIT_L(0); PG8_BAR; PG8_MMA(0, 0, At, B0); PG8_MMA(0, 1, At, B1); PG8_BAR; PG8_SCHED;
;             PG8_LDA(At, 0, 1); PG8_STAGE(PG8_SB(0, 0), b2, voffB); PG8_STAGE(PG8_SB(0, 1), b2 + hstepB, voffB); PG8_STAGE(PG8_SA(0, 0), a2, voffA);
.LBB0_396:
	ds_read_b128 v[128:131], v163
	ds_read_b128 v[132:135], v163 offset:1024
	ds_read_b128 v[152:155], v163 offset:2048
	ds_read_b128 v[156:159], v163 offset:3072
	ds_read_b128 v[168:171], v164
	ds_read_b128 v[172:175], v164 offset:1024
	ds_read_b128 v[176:179], v164 offset:2048
	ds_read_b128 v[180:183], v164 offset:3072
	s_add_u32 s34, s28, 0xfffc0080
	s_addc_u32 s35, s29, -1
	s_cmp_eq_u32 s72, 12
	s_cselect_b32 s41, s37, s35
	s_cselect_b32 s40, s68, s34
	s_cselect_b32 s35, s27, s71
	s_cselect_b32 s34, s69, s70
	v_lshl_add_u64 v[160:161], s[28:29], 0, v[144:145]
	s_add_i32 m0, s49, 0xc000
	ds_read_b128 v[184:187], v165
	ds_read_b128 v[188:191], v165 offset:1024
	ds_read_b128 v[192:195], v165 offset:2048
	ds_read_b128 v[196:199], v165 offset:3072
	ds_read_b128 v[200:203], v165 offset:4096
	ds_read_b128 v[204:207], v165 offset:5120
	ds_read_b128 v[208:211], v165 offset:6144
	ds_read_b128 v[212:215], v165 offset:7168
	global_load_lds_dwordx4 v[160:161], off
	v_lshl_add_u64 v[160:161], s[28:29], 0, v[146:147]
	s_add_i32 m0, s49, 0xe000
	s_nop 0
	global_load_lds_dwordx4 v[160:161], off
	s_waitcnt vmcnt(8)
	s_waitcnt lgkmcnt(0)
	s_barrier
	s_setprio 1
	s_waitcnt lgkmcnt(0)
	v_mfma_f32_16x16x32_bf16 v[124:127], v[128:131], v[184:187], v[124:127]
	v_mfma_f32_16x16x32_bf16 v[120:123], v[152:155], v[184:187], v[120:123]
	v_mfma_f32_16x16x32_bf16 v[108:111], v[128:131], v[192:195], v[108:111]
	v_mfma_f32_16x16x32_bf16 v[104:107], v[152:155], v[192:195], v[104:107]
	v_mfma_f32_16x16x32_bf16 v[92:95], v[128:131], v[200:203], v[92:95]
	v_mfma_f32_16x16x32_bf16 v[88:91], v[152:155], v[200:203], v[88:91]
	v_mfma_f32_16x16x32_bf16 v[76:79], v[128:131], v[208:211], v[76:79]
	v_mfma_f32_16x16x32_bf16 v[72:75], v[152:155], v[208:211], v[72:75]
	v_mfma_f32_16x16x32_bf16 v[124:127], v[132:135], v[188:191], v[124:127]
	v_mfma_f32_16x16x32_bf16 v[120:123], v[156:159], v[188:191], v[120:123]
	v_mfma_f32_16x16x32_bf16 v[108:111], v[132:135], v[196:199], v[108:111]
	v_mfma_f32_16x16x32_bf16 v[104:107], v[156:159], v[196:199], v[104:107]
	v_mfma_f32_16x16x32_bf16 v[92:95], v[132:135], v[204:207], v[92:95]
	v_mfma_f32_16x16x32_bf16 v[88:91], v[156:159], v[204:207], v[88:91]
	v_mfma_f32_16x16x32_bf16 v[76:79], v[132:135], v[212:215], v[76:79]
	v_mfma_f32_16x16x32_bf16 v[72:75], v[156:159], v[212:215], v[72:75]
	s_setprio 0
	s_setprio 1
	v_mfma_f32_16x16x32_bf16 v[116:119], v[168:171], v[184:187], v[116:119]
	v_mfma_f32_16x16x32_bf16 v[112:115], v[176:179], v[184:187], v[112:115]
	v_mfma_f32_16x16x32_bf16 v[100:103], v[168:171], v[192:195], v[100:103]
	v_mfma_f32_16x16x32_bf16 v[96:99], v[176:179], v[192:195], v[96:99]
	v_mfma_f32_16x16x32_bf16 v[84:87], v[168:171], v[200:203], v[84:87]
	v_mfma_f32_16x16x32_bf16 v[80:83], v[176:179], v[200:203], v[80:83]
	v_mfma_f32_16x16x32_bf16 v[68:71], v[168:171], v[208:211], v[68:71]
	v_mfma_f32_16x16x32_bf16 v[64:67], v[176:179], v[208:211], v[64:67]
	v_mfma_f32_16x16x32_bf16 v[116:119], v[172:175], v[188:191], v[116:119]
	v_mfma_f32_16x16x32_bf16 v[112:115], v[180:183], v[188:191], v[112:115]
	v_mfma_f32_16x16x32_bf16 v[100:103], v[172:175], v[196:199], v[100:103]
	v_mfma_f32_16x16x32_bf16 v[96:99], v[180:183], v[196:199], v[96:99]
	v_mfma_f32_16x16x32_bf16 v[84:87], v[172:175], v[204:207], v[84:87]
	v_mfma_f32_16x16x32_bf16 v[80:83], v[180:183], v[204:207], v[80:83]
	v_mfma_f32_16x16x32_bf16 v[68:71], v[172:175], v[212:215], v[68:71]
	v_mfma_f32_16x16x32_bf16 v[64:67], v[180:183], v[212:215], v[64:67]
	s_setprio 0
	s_barrier
	s_add_i32 s73, s62, s52
	s_mov_b32 m0, s73
	ds_read_b128 v[184:187], v165 offset:16384
	ds_read_b128 v[188:191], v165 offset:17408
	ds_read_b128 v[192:195], v165 offset:18432
	ds_read_b128 v[196:199], v165 offset:19456
	ds_read_b128 v[200:203], v165 offset:20480
	ds_read_b128 v[204:207], v165 offset:21504
	ds_read_b128 v[208:211], v165 offset:22528
	ds_read_b128 v[212:215], v165 offset:23552
	v_lshl_add_u64 v[160:161], s[34:35], 0, v[138:139]
	global_load_lds_dwordx4 v[160:161], off
	s_add_i32 m0, s73, 0x2000
	s_add_u32 s74, s34, 0x40000
	v_lshl_add_u64 v[216:217], s[34:35], 0, v[142:143]
	s_addc_u32 s75, s35, 0
	s_add_i32 s73, s63, s52
	global_load_lds_dwordx4 v[216:217], off
	v_lshl_add_u64 v[218:219], s[74:75], 0, v[138:139]
	s_mov_b32 m0, s73
	v_lshl_add_u64 v[220:221], s[40:41], 0, v[140:141]
	global_load_lds_dwordx4 v[218:219], off
	v_lshl_add_u64 v[218:219], s[74:75], 0, v[142:143]
	s_add_i32 m0, s73, 0x2000
	s_nop 0
	global_load_lds_dwordx4 v[218:219], off
	v_lshl_add_u64 v[218:219], s[40:41], 0, v[136:137]
	s_mov_b32 m0, s49
	s_nop 0
	global_load_lds_dwordx4 v[218:219], off
	s_mov_b32 m0, s51
	s_nop 0
	global_load_lds_dwordx4 v[220:221], off
	s_waitcnt vmcnt(8)
	s_waitcnt lgkmcnt(0)
	s_barrier
; #define PG8_STAGE(bufoff, gbase, voff) do { _Pragma("unroll") for (int _i = 0; _i < 2; ++_i) \
;         __builtin_amdgcn_global_load_lds((const unsigned*)((const char*)(gbase) + (voff)[_i]), (PG8_LAS unsigned*)(lds + (bufoff) + ldsw + _i * 8192), 16, 0, 0); } while (0)
; #define PG8_LDA(dst, b, h) do { _Pragma("unroll") for (int m = 0; m < 4; ++m) _Pragma("unroll") for (int k = 0; k < 2; ++k) dst[m][k] = *(const PG8_LAS bf16x8*)(lds + PG8_SA(b, h) + aoff + m * 2048 + k * 1024); } while (0)
; #define PG8_LDB(dst, b, h) do { _Pragma("unroll") for (int n = 0; n < 2; ++n) _Pragma("unroll") for (int k = 0; k < 2; ++k) dst[n][k] = *(const PG8_LAS bf16x8*)(lds + PG8_SB(b, h) + boff + n * 2048 + k * 1024); } while (0)
; #define PG8_MMA(ai, bj, At, Bt) do { __builtin_amdgcn_s_setprio(1); _Pragma("unroll") for (int m = 0; m < 4; ++m) _Pragma("unroll") for (int n = 0; n < 2; ++n) _Pragma("unroll") for (int k = 0; k < 2; ++k) \
;         acc[ai][bj][m][n] = __builtin_amdgcn_mfma_f32_16x16x32_bf16(Bt[n][k], At[m][k], acc[ai][bj][m][n], 0, 0, 0); __builtin_amdgcn_s_setprio(0); } while (0)
; #define PG8_WAIT_V(n) asm volatile("s_waitcnt vmcnt(" #n ")" ::: "memory")
; #define PG8_WAIT_L(n) asm volatile("s_waitcnt lgkmcnt(" #n ")" ::: "memory")
; #define PG8_BAR __builtin_amdgcn_s_barrier()
; #define PG8_SCHED __builtin_amdgcn_sched_barrier(0)
;     ...
;             PG8_LDA(At, 0, 1); PG8_STAGE(PG8_SB(0, 0), b2, voffB); PG8_STAGE(PG8_SB(0, 1), b2 + hstepB, voffB); PG8_STAGE(PG8_SA(0, 0), a2, voffA);
;             PG8_WAIT_V(8); PG8_WAIT_L(0); PG8_BAR; PG8_MMA(1, 0, At, B0); PG8_MMA(1, 1, At, B1); PG8_BAR; PG8_SCHED;
;             PG8_LDB(B0, 1, 0); PG8_LDB(B1, 1, 1); PG8_SCHED; PG8_LDA(At, 1, 0); PG8_STAGE(PG8_SA(0, 1), a2 + hstepA, voffA);
;             PG8_WAIT_V(8); PG8_WAIT_L(0); PG8_BAR; PG8_MMA(0, 0, At, B0); PG8_MMA(0, 1, At, B1); PG8_BAR; PG8_SCHED;
	s_setprio 1
	s_waitcnt lgkmcnt(0)
	v_mfma_f32_16x16x32_bf16 v[60:63], v[128:131], v[184:187], v[60:63]
	v_mfma_f32_16x16x32_bf16 v[56:59], v[152:155], v[184:187], v[56:59]
	v_mfma_f32_16x16x32_bf16 v[44:47], v[128:131], v[192:195], v[44:47]
	v_mfma_f32_16x16x32_bf16 v[40:43], v[152:155], v[192:195], v[40:43]
	v_mfma_f32_16x16x32_bf16 v[28:31], v[128:131], v[200:203], v[28:31]
	v_mfma_f32_16x16x32_bf16 v[24:27], v[152:155], v[200:203], v[24:27]
	v_mfma_f32_16x16x32_bf16 v[12:15], v[128:131], v[208:211], v[12:15]
	v_mfma_f32_16x16x32_bf16 v[8:11], v[152:155], v[208:211], v[8:11]
	v_mfma_f32_16x16x32_bf16 v[60:63], v[132:135], v[188:191], v[60:63]
	v_mfma_f32_16x16x32_bf16 v[56:59], v[156:159], v[188:191], v[56:59]
	v_mfma_f32_16x16x32_bf16 v[44:47], v[132:135], v[196:199], v[44:47]
	v_mfma_f32_16x16x32_bf16 v[40:43], v[156:159], v[196:199], v[40:43]
	v_mfma_f32_16x16x32_bf16 v[28:31], v[132:135], v[204:207], v[28:31]
	v_mfma_f32_16x16x32_bf16 v[24:27], v[156:159], v[204:207], v[24:27]
	v_mfma_f32_16x16x32_bf16 v[12:15], v[132:135], v[212:215], v[12:15]
	v_mfma_f32_16x16x32_bf16 v[8:11], v[156:159], v[212:215], v[8:11]
	s_setprio 0
	s_setprio 1
	v_mfma_f32_16x16x32_bf16 v[52:55], v[168:171], v[184:187], v[52:55]
	v_mfma_f32_16x16x32_bf16 v[48:51], v[176:179], v[184:187], v[48:51]
	v_mfma_f32_16x16x32_bf16 v[36:39], v[168:171], v[192:195], v[36:39]
	v_mfma_f32_16x16x32_bf16 v[32:35], v[176:179], v[192:195], v[32:35]
	v_mfma_f32_16x16x32_bf16 v[20:23], v[168:171], v[200:203], v[20:23]
	v_mfma_f32_16x16x32_bf16 v[16:19], v[176:179], v[200:203], v[16:19]
	v_mfma_f32_16x16x32_bf16 v[4:7], v[168:171], v[208:211], v[4:7]
	v_mfma_f32_16x16x32_bf16 v[0:3], v[176:179], v[208:211], v[0:3]
	v_mfma_f32_16x16x32_bf16 v[52:55], v[172:175], v[188:191], v[52:55]
	v_mfma_f32_16x16x32_bf16 v[48:51], v[180:183], v[188:191], v[48:51]
	v_mfma_f32_16x16x32_bf16 v[36:39], v[172:175], v[196:199], v[36:39]
	v_mfma_f32_16x16x32_bf16 v[32:35], v[180:183], v[196:199], v[32:35]
	v_mfma_f32_16x16x32_bf16 v[20:23], v[172:175], v[204:207], v[20:23]
	v_mfma_f32_16x16x32_bf16 v[16:19], v[180:183], v[204:207], v[16:19]
	v_mfma_f32_16x16x32_bf16 v[4:7], v[172:175], v[212:215], v[4:7]
	v_mfma_f32_16x16x32_bf16 v[0:3], v[180:183], v[212:215], v[0:3]
	s_setprio 0
	s_barrier
	s_add_i32 s73, 0, 0x18000
	s_add_i32 s74, 0, 0x1c000
	v_add_u32_e32 v156, s73, v162
	v_add_u32_e32 v167, s74, v162
	ds_read_b128 v[128:131], v156
	ds_read_b128 v[132:135], v156 offset:1024
	ds_read_b128 v[152:155], v156 offset:2048
	ds_read_b128 v[156:159], v156 offset:3072
	ds_read_b128 v[168:171], v167
	ds_read_b128 v[172:175], v167 offset:1024
	ds_read_b128 v[176:179], v167 offset:2048
	ds_read_b128 v[180:183], v167 offset:3072
	s_add_u32 s40, s40, 0x40000
	s_addc_u32 s41, s41, 0
	s_mov_b32 m0, s53
	v_lshl_add_u64 v[222:223], s[40:41], 0, v[136:137]
	ds_read_b128 v[184:187], v165 offset:32768
	ds_read_b128 v[188:191], v165 offset:33792
	ds_read_b128 v[192:195], v165 offset:34816
	ds_read_b128 v[196:199], v165 offset:35840
	ds_read_b128 v[200:203], v165 offset:36864
	ds_read_b128 v[204:207], v165 offset:37888
	ds_read_b128 v[208:211], v165 offset:38912
	ds_read_b128 v[212:215], v165 offset:39936
	global_load_lds_dwordx4 v[222:223], off
	v_lshl_add_u64 v[222:223], s[40:41], 0, v[140:141]
	s_mov_b32 m0, s54
	s_nop 0
	global_load_lds_dwordx4 v[222:223], off
	s_waitcnt vmcnt(8)
	s_waitcnt lgkmcnt(0)
	s_barrier
	s_setprio 1
	s_waitcnt lgkmcnt(0)
	v_mfma_f32_16x16x32_bf16 v[124:127], v[128:131], v[184:187], v[124:127]
	v_mfma_f32_16x16x32_bf16 v[120:123], v[152:155], v[184:187], v[120:123]
	v_mfma_f32_16x16x32_bf16 v[108:111], v[128:131], v[192:195], v[108:111]
	v_mfma_f32_16x16x32_bf16 v[104:107], v[152:155], v[192:195], v[104:107]
	v_mfma_f32_16x16x32_bf16 v[92:95], v[128:131], v[200:203], v[92:95]
	v_mfma_f32_16x16x32_bf16 v[88:91], v[152:155], v[200:203], v[88:91]
	v_mfma_f32_16x16x32_bf16 v[76:79], v[128:131], v[208:211], v[76:79]
	v_mfma_f32_16x16x32_bf16 v[72:75], v[152:155], v[208:211], v[72:75]
	v_mfma_f32_16x16x32_bf16 v[124:127], v[132:135], v[188:191], v[124:127]
	v_mfma_f32_16x16x32_bf16 v[120:123], v[156:159], v[188:191], v[120:123]
	v_mfma_f32_16x16x32_bf16 v[108:111], v[132:135], v[196:199], v[108:111]
	v_mfma_f32_16x16x32_bf16 v[104:107], v[156:159], v[196:199], v[104:107]
	v_mfma_f32_16x16x32_bf16 v[92:95], v[132:135], v[204:207], v[92:95]
	v_mfma_f32_16x16x32_bf16 v[88:91], v[156:159], v[204:207], v[88:91]
	v_mfma_f32_16x16x32_bf16 v[76:79], v[132:135], v[212:215], v[76:79]
	v_mfma_f32_16x16x32_bf16 v[72:75], v[156:159], v[212:215], v[72:75]
	s_setprio 0
	s_setprio 1
	v_mfma_f32_16x16x32_bf16 v[116:119], v[168:171], v[184:187], v[116:119]
	v_mfma_f32_16x16x32_bf16 v[112:115], v[176:179], v[184:187], v[112:115]
	v_mfma_f32_16x16x32_bf16 v[100:103], v[168:171], v[192:195], v[100:103]
	v_mfma_f32_16x16x32_bf16 v[96:99], v[176:179], v[192:195], v[96:99]
	v_mfma_f32_16x16x32_bf16 v[84:87], v[168:171], v[200:203], v[84:87]
	v_mfma_f32_16x16x32_bf16 v[80:83], v[176:179], v[200:203], v[80:83]
	v_mfma_f32_16x16x32_bf16 v[68:71], v[168:171], v[208:211], v[68:71]
	v_mfma_f32_16x16x32_bf16 v[64:67], v[176:179], v[208:211], v[64:67]
	v_mfma_f32_16x16x32_bf16 v[116:119], v[172:175], v[188:191], v[116:119]
	v_mfma_f32_16x16x32_bf16 v[112:115], v[180:183], v[188:191], v[112:115]
	v_mfma_f32_16x16x32_bf16 v[100:103], v[172:175], v[196:199], v[100:103]
	v_mfma_f32_16x16x32_bf16 v[96:99], v[180:183], v[196:199], v[96:99]
	v_mfma_f32_16x16x32_bf16 v[84:87], v[172:175], v[204:207], v[84:87]
	v_mfma_f32_16x16x32_bf16 v[80:83], v[180:183], v[204:207], v[80:83]
	v_mfma_f32_16x16x32_bf16 v[68:71], v[172:175], v[212:215], v[68:71]
	v_mfma_f32_16x16x32_bf16 v[64:67], v[180:183], v[212:215], v[64:67]
	s_setprio 0
	s_barrier
; #define PG8_STAGE(bufoff, gbase, voff) do { _Pragma("unroll") for (int _i = 0; _i < 2; ++_i) \
;         __builtin_amdgcn_global_load_lds((const unsigned*)((const char*)(gbase) + (voff)[_i]), (PG8_LAS unsigned*)(lds + (bufoff) + ldsw + _i * 8192), 16, 0, 0); } while (0)
; #define PG8_LDA(dst, b, h) do { _Pragma("unroll") for (int m = 0; m < 4; ++m) _Pragma("unroll") for (int k = 0; k < 2; ++k) dst[m][k] = *(const PG8_LAS bf16x8*)(lds + PG8_SA(b, h) + aoff + m * 2048 + k * 1024); } while (0)
; #define PG8_MMA(ai, bj, At, Bt) do { __builtin_amdgcn_s_setprio(1); _Pragma("unroll") for (int m = 0; m < 4; ++m) _Pragma("unroll") for (int n = 0; n < 2; ++n) _Pragma("unroll") for (int k = 0; k < 2; ++k) \
;         acc[ai][bj][m][n] = __builtin_amdgcn_mfma_f32_16x16x32_bf16(Bt[n][k], At[m][k], acc[ai][bj][m][n], 0, 0, 0); __builtin_amdgcn_s_setprio(0); } while (0)
; #define PG8_WAIT_V(n) asm volatile("s_waitcnt vmcnt(" #n ")" ::: "memory")
; #define PG8_WAIT_L(n) asm volatile("s_waitcnt lgkmcnt(" #n ")" ::: "memory")
; #define PG8_BAR __builtin_amdgcn_s_barrier()
; #define PG8_SCHED __builtin_amdgcn_sched_barrier(0)
;     ...
;             PG8_LDA(At, 1, 1); PG8_STAGE(PG8_SB(1, 0), b3, voffB); PG8_STAGE(PG8_SB(1, 1), b3 + hstepB, voffB); PG8_STAGE(PG8_SA(1, 0), a3, voffA);
;             PG8_WAIT_V(8); PG8_WAIT_L(0); PG8_BAR; PG8_MMA(1, 0, At, B0); PG8_MMA(1, 1, At, B1); PG8_BAR; PG8_SCHED;
;     ...
;         if constexpr (ALIGN_EPI) { if (wr == 0) PG8_BAR; }
	s_add_i32 s40, s73, s52
	s_mov_b32 m0, s40
	ds_read_b128 v[184:187], v165 offset:49152
	ds_read_b128 v[188:191], v165 offset:50176
	ds_read_b128 v[192:195], v165 offset:51200
	ds_read_b128 v[196:199], v165 offset:52224
	ds_read_b128 v[200:203], v165 offset:53248
	ds_read_b128 v[204:207], v165 offset:54272
	ds_read_b128 v[208:211], v165 offset:55296
	ds_read_b128 v[212:215], v165 offset:56320
	v_lshl_add_u64 v[160:161], v[160:161], 0, s[16:17]
	global_load_lds_dwordx4 v[160:161], off
	s_add_i32 m0, s40, 0x2000
	s_add_u32 s34, s34, 0x40080
	v_lshl_add_u64 v[160:161], v[216:217], 0, s[16:17]
	s_addc_u32 s35, s35, 0
	s_add_i32 s40, s74, s52
	global_load_lds_dwordx4 v[160:161], off
	v_lshl_add_u64 v[160:161], s[34:35], 0, v[138:139]
	s_mov_b32 m0, s40
	s_nop 0
	global_load_lds_dwordx4 v[160:161], off
	v_lshl_add_u64 v[160:161], s[34:35], 0, v[142:143]
	s_add_i32 m0, s40, 0x2000
	s_nop 0
	global_load_lds_dwordx4 v[160:161], off
	v_lshl_add_u64 v[160:161], v[218:219], 0, s[16:17]
	s_mov_b32 m0, s58
	s_nop 0
	global_load_lds_dwordx4 v[160:161], off
	v_lshl_add_u64 v[160:161], v[220:221], 0, s[16:17]
	s_mov_b32 m0, s59
	s_nop 0
	global_load_lds_dwordx4 v[160:161], off
	s_waitcnt vmcnt(8)
	s_waitcnt lgkmcnt(0)
	s_barrier
	s_setprio 1
	s_waitcnt lgkmcnt(0)
	v_mfma_f32_16x16x32_bf16 v[60:63], v[128:131], v[184:187], v[60:63]
	v_mfma_f32_16x16x32_bf16 v[56:59], v[152:155], v[184:187], v[56:59]
	v_mfma_f32_16x16x32_bf16 v[44:47], v[128:131], v[192:195], v[44:47]
	v_mfma_f32_16x16x32_bf16 v[40:43], v[152:155], v[192:195], v[40:43]
	v_mfma_f32_16x16x32_bf16 v[28:31], v[128:131], v[200:203], v[28:31]
	v_mfma_f32_16x16x32_bf16 v[24:27], v[152:155], v[200:203], v[24:27]
	v_mfma_f32_16x16x32_bf16 v[12:15], v[128:131], v[208:211], v[12:15]
	v_mfma_f32_16x16x32_bf16 v[8:11], v[152:155], v[208:211], v[8:11]
	v_mfma_f32_16x16x32_bf16 v[60:63], v[132:135], v[188:191], v[60:63]
	v_mfma_f32_16x16x32_bf16 v[56:59], v[156:159], v[188:191], v[56:59]
	v_mfma_f32_16x16x32_bf16 v[44:47], v[132:135], v[196:199], v[44:47]
	v_mfma_f32_16x16x32_bf16 v[40:43], v[156:159], v[196:199], v[40:43]
	v_mfma_f32_16x16x32_bf16 v[28:31], v[132:135], v[204:207], v[28:31]
	v_mfma_f32_16x16x32_bf16 v[24:27], v[156:159], v[204:207], v[24:27]
	v_mfma_f32_16x16x32_bf16 v[12:15], v[132:135], v[212:215], v[12:15]
	v_mfma_f32_16x16x32_bf16 v[8:11], v[156:159], v[212:215], v[8:11]
	s_setprio 0
	s_setprio 1
	v_mfma_f32_16x16x32_bf16 v[52:55], v[168:171], v[184:187], v[52:55]
	v_mfma_f32_16x16x32_bf16 v[48:51], v[176:179], v[184:187], v[48:51]
	v_mfma_f32_16x16x32_bf16 v[36:39], v[168:171], v[192:195], v[36:39]
	v_mfma_f32_16x16x32_bf16 v[32:35], v[176:179], v[192:195], v[32:35]
	v_mfma_f32_16x16x32_bf16 v[20:23], v[168:171], v[200:203], v[20:23]
	v_mfma_f32_16x16x32_bf16 v[16:19], v[176:179], v[200:203], v[16:19]
	v_mfma_f32_16x16x32_bf16 v[4:7], v[168:171], v[208:211], v[4:7]
	v_mfma_f32_16x16x32_bf16 v[0:3], v[176:179], v[208:211], v[0:3]
	v_mfma_f32_16x16x32_bf16 v[52:55], v[172:175], v[188:191], v[52:55]
	v_mfma_f32_16x16x32_bf16 v[48:51], v[180:183], v[188:191], v[48:51]
	v_mfma_f32_16x16x32_bf16 v[36:39], v[172:175], v[196:199], v[36:39]
	v_mfma_f32_16x16x32_bf16 v[32:35], v[180:183], v[196:199], v[32:35]
	v_mfma_f32_16x16x32_bf16 v[20:23], v[172:175], v[204:207], v[20:23]
	v_mfma_f32_16x16x32_bf16 v[16:19], v[180:183], v[204:207], v[16:19]
	v_mfma_f32_16x16x32_bf16 v[4:7], v[172:175], v[212:215], v[4:7]
	v_mfma_f32_16x16x32_bf16 v[0:3], v[180:183], v[212:215], v[0:3]
	s_setprio 0
	s_barrier
	s_add_i32 s72, s72, 2
	s_add_u32 s28, s28, 0x100
	s_addc_u32 s29, s29, 0
	s_add_u32 s70, s70, 0x100
	s_addc_u32 s71, s71, 0
	s_cmp_gt_u32 s72, 13
	s_cbranch_scc0 .LBB0_396
	s_and_b64 vcc, exec, s[18:19]
	s_cbranch_vccz .LBB0_399
	s_barrier

; #define PG8_STAGE(bufoff, gbase, voff) do { _Pragma("unroll") for (int _i = 0; _i < 2; ++_i) \
;         __builtin_amdgcn_global_load_lds((const unsigned*)((const char*)(gbase) + (voff)[_i]), (PG8_LAS unsigned*)(lds + (bufoff) + ldsw + _i * 8192), 16, 0, 0); } while (0)
; #define PG8_LDA(dst, b, h) do { _Pragma("unroll") for (int m = 0; m < 4; ++m) _Pragma("unroll") for (int k = 0; k < 2; ++k) dst[m][k] = *(const PG8_LAS bf16x8*)(lds + PG8_SA(b, h) + aoff + m * 2048 + k * 1024); } while (0)
; #define PG8_LDB(dst, b, h) do { _Pragma("unroll") for (int n = 0; n < 2; ++n) _Pragma("unroll") for (int k = 0; k < 2; ++k) dst[n][k] = *(const PG8_LAS bf16x8*)(lds + PG8_SB(b, h) + boff + n * 2048 + k * 1024); } while (0)
; #define PG8_MMA(ai, bj, At, Bt) do { __builtin_amdgcn_s_setprio(1); _Pragma("unroll") for (int m = 0; m < 4; ++m) _Pragma("unroll") for (int n = 0; n < 2; ++n) _Pragma("unroll") for (int k = 0; k < 2; ++k) \
;         acc[ai][bj][m][n] = __builtin_amdgcn_mfma_f32_16x16x32_bf16(Bt[n][k], At[m][k], acc[ai][bj][m][n], 0, 0, 0); __builtin_amdgcn_s_setprio(0); } while (0)
; #define PG8_WAIT_V(n) asm volatile("s_waitcnt vmcnt(" #n ")" ::: "memory")
; #define PG8_WAIT_L(n) asm volatile("s_waitcnt lgkmcnt(" #n ")" ::: "memory")
; #define PG8_BAR __builtin_amdgcn_s_barrier()
; #define PG8_SCHED __builtin_amdgcn_sched_barrier(0)
;     ...
;             const char* a1 = cA + (size_t)(t + 1) * kstep;
;             const char* a2 = last ? nA : cA + (size_t)(t + 2) * kstep; const char* b2 = last ? nB : cB + (size_t)(t + 2) * kstep;
;             const char* a3 = a2 + kstep; const char* b3 = b2 + kstep;
;             if (last && has_next) S.a_ready(nxt);
;             if constexpr (SP2) {
;             PG8_LDB(B0, 0, 0); PG8_LDB(B1, 0, 1); PG8_SCHED; PG8_LDA(At, 0, 0); PG8_STAGE(PG8_SA(1, 1), a1 + hstepA, voffA);
;             PG8_WAIT_V(8); PG8_WAIT_L(0); PG8_BAR; PG8_MMA(0, 0, At, B0); PG8_MMA(0, 1, At, B1); PG8_BAR; PG8_SCHED;
;             PG8_LDA(At, 0, 1); PG8_STAGE(PG8_SB(0, 0), b2, voffB); PG8_STAGE(PG8_SB(0, 1), b2 + hstepB, voffB); PG8_STAGE(PG8_SA(0, 0), a2, voffA);
.LBB0_632:
	s_add_u32 s28, s8, 0xfffe0080
	s_addc_u32 s29, s9, -1
	s_add_i32 s48, 0, 0x10000
	s_cmp_eq_u32 s86, 2
	s_cselect_b32 s35, s23, s29
	s_cselect_b32 s34, s37, s28
	s_cselect_b32 s29, s25, s85
	s_cselect_b32 s28, s24, s69
	s_add_i32 s61, 0, 0x14000
	v_add_u32_e32 v142, s48, v1
	v_add_u32_e32 v158, s61, v1
	ds_read_b128 v[130:133], v142
	ds_read_b128 v[134:137], v142 offset:1024
	ds_read_b128 v[138:141], v142 offset:2048
	ds_read_b128 v[142:145], v142 offset:3072
	ds_read_b128 v[146:149], v158
	ds_read_b128 v[150:153], v158 offset:1024
	ds_read_b128 v[154:157], v158 offset:2048
	ds_read_b128 v[158:161], v158 offset:3072
	v_lshl_add_u64 v[188:189], s[8:9], 0, v[170:171]
	s_add_i32 m0, s43, 0xc000
	ds_read_b128 v[174:177], v190
	ds_read_b128 v[180:183], v190 offset:1024
	ds_read_b128 v[184:187], v190 offset:2048
	ds_read_b128 v[192:195], v190 offset:3072
	ds_read_b128 v[196:199], v190 offset:4096
	ds_read_b128 v[200:203], v190 offset:5120
	ds_read_b128 v[204:207], v190 offset:6144
	ds_read_b128 v[210:213], v190 offset:7168
	global_load_lds_dwordx4 v[188:189], off
	v_lshl_add_u64 v[188:189], s[8:9], 0, v[172:173]
	s_add_i32 m0, s43, 0xe000
	s_nop 0
	global_load_lds_dwordx4 v[188:189], off
	s_waitcnt vmcnt(8)
	s_waitcnt lgkmcnt(0)
	s_barrier
	s_setprio 1
	s_waitcnt lgkmcnt(0)
	v_mfma_f32_16x16x32_bf16 v[126:129], v[130:133], v[174:177], v[126:129]
	v_mfma_f32_16x16x32_bf16 v[122:125], v[138:141], v[174:177], v[122:125]
	v_mfma_f32_16x16x32_bf16 v[110:113], v[130:133], v[184:187], v[110:113]
	v_mfma_f32_16x16x32_bf16 v[106:109], v[138:141], v[184:187], v[106:109]
	v_mfma_f32_16x16x32_bf16 v[94:97], v[130:133], v[196:199], v[94:97]
	v_mfma_f32_16x16x32_bf16 v[90:93], v[138:141], v[196:199], v[90:93]
	v_mfma_f32_16x16x32_bf16 v[78:81], v[130:133], v[204:207], v[78:81]
	v_mfma_f32_16x16x32_bf16 v[74:77], v[138:141], v[204:207], v[74:77]
	v_mfma_f32_16x16x32_bf16 v[126:129], v[134:137], v[180:183], v[126:129]
	v_mfma_f32_16x16x32_bf16 v[122:125], v[142:145], v[180:183], v[122:125]
	v_mfma_f32_16x16x32_bf16 v[110:113], v[134:137], v[192:195], v[110:113]
	v_mfma_f32_16x16x32_bf16 v[106:109], v[142:145], v[192:195], v[106:109]
	v_mfma_f32_16x16x32_bf16 v[94:97], v[134:137], v[200:203], v[94:97]
	v_mfma_f32_16x16x32_bf16 v[90:93], v[142:145], v[200:203], v[90:93]
	v_mfma_f32_16x16x32_bf16 v[78:81], v[134:137], v[210:213], v[78:81]
	v_mfma_f32_16x16x32_bf16 v[74:77], v[142:145], v[210:213], v[74:77]
	s_setprio 0
	s_setprio 1
	v_mfma_f32_16x16x32_bf16 v[118:121], v[146:149], v[174:177], v[118:121]
	v_mfma_f32_16x16x32_bf16 v[114:117], v[154:157], v[174:177], v[114:117]
	v_mfma_f32_16x16x32_bf16 v[102:105], v[146:149], v[184:187], v[102:105]
	v_mfma_f32_16x16x32_bf16 v[98:101], v[154:157], v[184:187], v[98:101]
	v_mfma_f32_16x16x32_bf16 v[86:89], v[146:149], v[196:199], v[86:89]
	v_mfma_f32_16x16x32_bf16 v[82:85], v[154:157], v[196:199], v[82:85]
	v_mfma_f32_16x16x32_bf16 v[70:73], v[146:149], v[204:207], v[70:73]
	v_mfma_f32_16x16x32_bf16 v[66:69], v[154:157], v[204:207], v[66:69]
	v_mfma_f32_16x16x32_bf16 v[118:121], v[150:153], v[180:183], v[118:121]
	v_mfma_f32_16x16x32_bf16 v[114:117], v[158:161], v[180:183], v[114:117]
	v_mfma_f32_16x16x32_bf16 v[102:105], v[150:153], v[192:195], v[102:105]
	v_mfma_f32_16x16x32_bf16 v[98:101], v[158:161], v[192:195], v[98:101]
	v_mfma_f32_16x16x32_bf16 v[86:89], v[150:153], v[200:203], v[86:89]
	v_mfma_f32_16x16x32_bf16 v[82:85], v[158:161], v[200:203], v[82:85]
	v_mfma_f32_16x16x32_bf16 v[70:73], v[150:153], v[210:213], v[70:73]
	v_mfma_f32_16x16x32_bf16 v[66:69], v[158:161], v[210:213], v[66:69]
	s_setprio 0
	s_barrier
	s_add_i32 s48, s48, s42
	s_mov_b32 m0, s48
	ds_read_b128 v[174:177], v190 offset:16384
	ds_read_b128 v[180:183], v190 offset:17408
	ds_read_b128 v[184:187], v190 offset:18432
	ds_read_b128 v[192:195], v190 offset:19456
	ds_read_b128 v[196:199], v190 offset:20480
	ds_read_b128 v[200:203], v190 offset:21504
	ds_read_b128 v[204:207], v190 offset:22528
	ds_read_b128 v[210:213], v190 offset:23552
	v_lshl_add_u64 v[188:189], s[28:29], 0, v[166:167]
	global_load_lds_dwordx4 v[188:189], off
	s_add_i32 m0, s48, 0x2000
	s_add_u32 s48, s28, 0x18000
	v_lshl_add_u64 v[214:215], s[28:29], 0, v[162:163]
	s_addc_u32 s49, s29, 0
	s_add_i32 s61, s61, s42
	global_load_lds_dwordx4 v[214:215], off
	v_lshl_add_u64 v[216:217], s[48:49], 0, v[166:167]
	s_mov_b32 m0, s61
	v_lshl_add_u64 v[218:219], s[34:35], 0, v[164:165]
	global_load_lds_dwordx4 v[216:217], off
	v_lshl_add_u64 v[216:217], s[48:49], 0, v[162:163]
	s_add_i32 m0, s61, 0x2000
	s_nop 0
	global_load_lds_dwordx4 v[216:217], off
	v_lshl_add_u64 v[216:217], s[34:35], 0, v[168:169]
	s_mov_b32 m0, s43
	s_nop 0
	global_load_lds_dwordx4 v[216:217], off
	s_mov_b32 m0, s44
	s_nop 0
	global_load_lds_dwordx4 v[218:219], off
	s_waitcnt vmcnt(8)
	s_waitcnt lgkmcnt(0)
	s_barrier
; #define PG8_STAGE(bufoff, gbase, voff) do { _Pragma("unroll") for (int _i = 0; _i < 2; ++_i) \
;         __builtin_amdgcn_global_load_lds((const unsigned*)((const char*)(gbase) + (voff)[_i]), (PG8_LAS unsigned*)(lds + (bufoff) + ldsw + _i * 8192), 16, 0, 0); } while (0)
; #define PG8_LDA(dst, b, h) do { _Pragma("unroll") for (int m = 0; m < 4; ++m) _Pragma("unroll") for (int k = 0; k < 2; ++k) dst[m][k] = *(const PG8_LAS bf16x8*)(lds + PG8_SA(b, h) + aoff + m * 2048 + k * 1024); } while (0)
; #define PG8_LDB(dst, b, h) do { _Pragma("unroll") for (int n = 0; n < 2; ++n) _Pragma("unroll") for (int k = 0; k < 2; ++k) dst[n][k] = *(const PG8_LAS bf16x8*)(lds + PG8_SB(b, h) + boff + n * 2048 + k * 1024); } while (0)
; #define PG8_MMA(ai, bj, At, Bt) do { __builtin_amdgcn_s_setprio(1); _Pragma("unroll") for (int m = 0; m < 4; ++m) _Pragma("unroll") for (int n = 0; n < 2; ++n) _Pragma("unroll") for (int k = 0; k < 2; ++k) \
;         acc[ai][bj][m][n] = __builtin_amdgcn_mfma_f32_16x16x32_bf16(Bt[n][k], At[m][k], acc[ai][bj][m][n], 0, 0, 0); __builtin_amdgcn_s_setprio(0); } while (0)
; #define PG8_WAIT_V(n) asm volatile("s_waitcnt vmcnt(" #n ")" ::: "memory")
; #define PG8_WAIT_L(n) asm volatile("s_waitcnt lgkmcnt(" #n ")" ::: "memory")
; #define PG8_BAR __builtin_amdgcn_s_barrier()
; #define PG8_SCHED __builtin_amdgcn_sched_barrier(0)
;     ...
;             PG8_LDA(At, 0, 1); PG8_STAGE(PG8_SB(0, 0), b2, voffB); PG8_STAGE(PG8_SB(0, 1), b2 + hstepB, voffB); PG8_STAGE(PG8_SA(0, 0), a2, voffA);
;             PG8_WAIT_V(8); PG8_WAIT_L(0); PG8_BAR; PG8_MMA(1, 0, At, B0); PG8_MMA(1, 1, At, B1); PG8_BAR; PG8_SCHED;
;             PG8_LDB(B0, 1, 0); PG8_LDB(B1, 1, 1); PG8_SCHED; PG8_LDA(At, 1, 0); PG8_STAGE(PG8_SA(0, 1), a2 + hstepA, voffA);
;             PG8_WAIT_V(8); PG8_WAIT_L(0); PG8_BAR; PG8_MMA(0, 0, At, B0); PG8_MMA(0, 1, At, B1); PG8_BAR; PG8_SCHED;
	s_setprio 1
	s_waitcnt lgkmcnt(0)
	v_mfma_f32_16x16x32_bf16 v[62:65], v[130:133], v[174:177], v[62:65]
	v_mfma_f32_16x16x32_bf16 v[58:61], v[138:141], v[174:177], v[58:61]
	v_mfma_f32_16x16x32_bf16 v[46:49], v[130:133], v[184:187], v[46:49]
	v_mfma_f32_16x16x32_bf16 v[42:45], v[138:141], v[184:187], v[42:45]
	v_mfma_f32_16x16x32_bf16 v[30:33], v[130:133], v[196:199], v[30:33]
	v_mfma_f32_16x16x32_bf16 v[26:29], v[138:141], v[196:199], v[26:29]
	v_mfma_f32_16x16x32_bf16 v[14:17], v[130:133], v[204:207], v[14:17]
	v_mfma_f32_16x16x32_bf16 v[10:13], v[138:141], v[204:207], v[10:13]
	v_mfma_f32_16x16x32_bf16 v[62:65], v[134:137], v[180:183], v[62:65]
	v_mfma_f32_16x16x32_bf16 v[58:61], v[142:145], v[180:183], v[58:61]
	v_mfma_f32_16x16x32_bf16 v[46:49], v[134:137], v[192:195], v[46:49]
	v_mfma_f32_16x16x32_bf16 v[42:45], v[142:145], v[192:195], v[42:45]
	v_mfma_f32_16x16x32_bf16 v[30:33], v[134:137], v[200:203], v[30:33]
	v_mfma_f32_16x16x32_bf16 v[26:29], v[142:145], v[200:203], v[26:29]
	v_mfma_f32_16x16x32_bf16 v[14:17], v[134:137], v[210:213], v[14:17]
	v_mfma_f32_16x16x32_bf16 v[10:13], v[142:145], v[210:213], v[10:13]
	s_setprio 0
	s_setprio 1
	v_mfma_f32_16x16x32_bf16 v[54:57], v[146:149], v[174:177], v[54:57]
	v_mfma_f32_16x16x32_bf16 v[50:53], v[154:157], v[174:177], v[50:53]
	v_mfma_f32_16x16x32_bf16 v[38:41], v[146:149], v[184:187], v[38:41]
	v_mfma_f32_16x16x32_bf16 v[34:37], v[154:157], v[184:187], v[34:37]
	v_mfma_f32_16x16x32_bf16 v[22:25], v[146:149], v[196:199], v[22:25]
	v_mfma_f32_16x16x32_bf16 v[18:21], v[154:157], v[196:199], v[18:21]
	v_mfma_f32_16x16x32_bf16 v[6:9], v[146:149], v[204:207], v[6:9]
	v_mfma_f32_16x16x32_bf16 v[2:5], v[154:157], v[204:207], v[2:5]
	v_mfma_f32_16x16x32_bf16 v[54:57], v[150:153], v[180:183], v[54:57]
	v_mfma_f32_16x16x32_bf16 v[50:53], v[158:161], v[180:183], v[50:53]
	v_mfma_f32_16x16x32_bf16 v[38:41], v[150:153], v[192:195], v[38:41]
	v_mfma_f32_16x16x32_bf16 v[34:37], v[158:161], v[192:195], v[34:37]
	v_mfma_f32_16x16x32_bf16 v[22:25], v[150:153], v[200:203], v[22:25]
	v_mfma_f32_16x16x32_bf16 v[18:21], v[158:161], v[200:203], v[18:21]
	v_mfma_f32_16x16x32_bf16 v[6:9], v[150:153], v[210:213], v[6:9]
	v_mfma_f32_16x16x32_bf16 v[2:5], v[158:161], v[210:213], v[2:5]
	s_setprio 0
	s_barrier
	s_add_i32 s48, 0, 0x18000
	s_add_i32 s49, 0, 0x1c000
	v_add_u32_e32 v142, s48, v1
	v_add_u32_e32 v158, s49, v1
	ds_read_b128 v[130:133], v142
	ds_read_b128 v[134:137], v142 offset:1024
	ds_read_b128 v[138:141], v142 offset:2048
	ds_read_b128 v[142:145], v142 offset:3072
	ds_read_b128 v[146:149], v158
	ds_read_b128 v[150:153], v158 offset:1024
	ds_read_b128 v[154:157], v158 offset:2048
	ds_read_b128 v[158:161], v158 offset:3072
	s_add_u32 s34, s34, 0x20000
	s_addc_u32 s35, s35, 0
	s_mov_b32 m0, s45
	v_lshl_add_u64 v[222:223], s[34:35], 0, v[168:169]
	ds_read_b128 v[174:177], v190 offset:32768
	ds_read_b128 v[180:183], v190 offset:33792
	ds_read_b128 v[184:187], v190 offset:34816
	ds_read_b128 v[192:195], v190 offset:35840
	ds_read_b128 v[196:199], v190 offset:36864
	ds_read_b128 v[200:203], v190 offset:37888
	ds_read_b128 v[204:207], v190 offset:38912
	ds_read_b128 v[210:213], v190 offset:39936
	global_load_lds_dwordx4 v[222:223], off
	v_lshl_add_u64 v[222:223], s[34:35], 0, v[164:165]
	s_mov_b32 m0, s46
	s_nop 0
	global_load_lds_dwordx4 v[222:223], off
	s_waitcnt vmcnt(8)
	s_waitcnt lgkmcnt(0)
	s_barrier
	s_setprio 1
	s_waitcnt lgkmcnt(0)
	v_mfma_f32_16x16x32_bf16 v[126:129], v[130:133], v[174:177], v[126:129]
	v_mfma_f32_16x16x32_bf16 v[122:125], v[138:141], v[174:177], v[122:125]
	v_mfma_f32_16x16x32_bf16 v[110:113], v[130:133], v[184:187], v[110:113]
	v_mfma_f32_16x16x32_bf16 v[106:109], v[138:141], v[184:187], v[106:109]
	v_mfma_f32_16x16x32_bf16 v[94:97], v[130:133], v[196:199], v[94:97]
	v_mfma_f32_16x16x32_bf16 v[90:93], v[138:141], v[196:199], v[90:93]
	v_mfma_f32_16x16x32_bf16 v[78:81], v[130:133], v[204:207], v[78:81]
	v_mfma_f32_16x16x32_bf16 v[74:77], v[138:141], v[204:207], v[74:77]
	v_mfma_f32_16x16x32_bf16 v[126:129], v[134:137], v[180:183], v[126:129]
	v_mfma_f32_16x16x32_bf16 v[122:125], v[142:145], v[180:183], v[122:125]
	v_mfma_f32_16x16x32_bf16 v[110:113], v[134:137], v[192:195], v[110:113]
	v_mfma_f32_16x16x32_bf16 v[106:109], v[142:145], v[192:195], v[106:109]
	v_mfma_f32_16x16x32_bf16 v[94:97], v[134:137], v[200:203], v[94:97]
	v_mfma_f32_16x16x32_bf16 v[90:93], v[142:145], v[200:203], v[90:93]
	v_mfma_f32_16x16x32_bf16 v[78:81], v[134:137], v[210:213], v[78:81]
	v_mfma_f32_16x16x32_bf16 v[74:77], v[142:145], v[210:213], v[74:77]
	s_setprio 0
	s_setprio 1
	v_mfma_f32_16x16x32_bf16 v[118:121], v[146:149], v[174:177], v[118:121]
	v_mfma_f32_16x16x32_bf16 v[114:117], v[154:157], v[174:177], v[114:117]
	v_mfma_f32_16x16x32_bf16 v[102:105], v[146:149], v[184:187], v[102:105]
	v_mfma_f32_16x16x32_bf16 v[98:101], v[154:157], v[184:187], v[98:101]
	v_mfma_f32_16x16x32_bf16 v[86:89], v[146:149], v[196:199], v[86:89]
	v_mfma_f32_16x16x32_bf16 v[82:85], v[154:157], v[196:199], v[82:85]
	v_mfma_f32_16x16x32_bf16 v[70:73], v[146:149], v[204:207], v[70:73]
	v_mfma_f32_16x16x32_bf16 v[66:69], v[154:157], v[204:207], v[66:69]
	v_mfma_f32_16x16x32_bf16 v[118:121], v[150:153], v[180:183], v[118:121]
	v_mfma_f32_16x16x32_bf16 v[114:117], v[158:161], v[180:183], v[114:117]
	v_mfma_f32_16x16x32_bf16 v[102:105], v[150:153], v[192:195], v[102:105]
	v_mfma_f32_16x16x32_bf16 v[98:101], v[158:161], v[192:195], v[98:101]
	v_mfma_f32_16x16x32_bf16 v[86:89], v[150:153], v[200:203], v[86:89]
	v_mfma_f32_16x16x32_bf16 v[82:85], v[158:161], v[200:203], v[82:85]
	v_mfma_f32_16x16x32_bf16 v[70:73], v[150:153], v[210:213], v[70:73]
	v_mfma_f32_16x16x32_bf16 v[66:69], v[158:161], v[210:213], v[66:69]
	s_setprio 0
	s_barrier
; #define PG8_STAGE(bufoff, gbase, voff) do { _Pragma("unroll") for (int _i = 0; _i < 2; ++_i) \
;         __builtin_amdgcn_global_load_lds((const unsigned*)((const char*)(gbase) + (voff)[_i]), (PG8_LAS unsigned*)(lds + (bufoff) + ldsw + _i * 8192), 16, 0, 0); } while (0)
; #define PG8_LDA(dst, b, h) do { _Pragma("unroll") for (int m = 0; m < 4; ++m) _Pragma("unroll") for (int k = 0; k < 2; ++k) dst[m][k] = *(const PG8_LAS bf16x8*)(lds + PG8_SA(b, h) + aoff + m * 2048 + k * 1024); } while (0)
; #define PG8_MMA(ai, bj, At, Bt) do { __builtin_amdgcn_s_setprio(1); _Pragma("unroll") for (int m = 0; m < 4; ++m) _Pragma("unroll") for (int n = 0; n < 2; ++n) _Pragma("unroll") for (int k = 0; k < 2; ++k) \
;         acc[ai][bj][m][n] = __builtin_amdgcn_mfma_f32_16x16x32_bf16(Bt[n][k], At[m][k], acc[ai][bj][m][n], 0, 0, 0); __builtin_amdgcn_s_setprio(0); } while (0)
; #define PG8_WAIT_V(n) asm volatile("s_waitcnt vmcnt(" #n ")" ::: "memory")
; #define PG8_WAIT_L(n) asm volatile("s_waitcnt lgkmcnt(" #n ")" ::: "memory")
; #define PG8_BAR __builtin_amdgcn_s_barrier()
; #define PG8_SCHED __builtin_amdgcn_sched_barrier(0)
;     ...
;             PG8_LDA(At, 1, 1); PG8_STAGE(PG8_SB(1, 0), b3, voffB); PG8_STAGE(PG8_SB(1, 1), b3 + hstepB, voffB); PG8_STAGE(PG8_SA(1, 0), a3, voffA);
;             PG8_WAIT_V(8); PG8_WAIT_L(0); PG8_BAR; PG8_MMA(1, 0, At, B0); PG8_MMA(1, 1, At, B1); PG8_BAR; PG8_SCHED;
;     ...
;         if constexpr (ALIGN_EPI) { if (wr == 0) PG8_BAR; }
	s_add_i32 s34, s48, s42
	s_mov_b32 m0, s34
	ds_read_b128 v[174:177], v190 offset:49152
	ds_read_b128 v[180:183], v190 offset:50176
	ds_read_b128 v[184:187], v190 offset:51200
	ds_read_b128 v[192:195], v190 offset:52224
	ds_read_b128 v[196:199], v190 offset:53248
	ds_read_b128 v[200:203], v190 offset:54272
	ds_read_b128 v[204:207], v190 offset:55296
	ds_read_b128 v[210:213], v190 offset:56320
	v_lshl_add_u64 v[188:189], v[188:189], 0, s[66:67]
	global_load_lds_dwordx4 v[188:189], off
	s_add_i32 m0, s34, 0x2000
	s_add_u32 s28, s28, 0x18080
	v_lshl_add_u64 v[188:189], v[214:215], 0, s[66:67]
	s_addc_u32 s29, s29, 0
	s_add_i32 s34, s49, s42
	global_load_lds_dwordx4 v[188:189], off
	v_lshl_add_u64 v[188:189], s[28:29], 0, v[166:167]
	s_mov_b32 m0, s34
	s_nop 0
	global_load_lds_dwordx4 v[188:189], off
	v_lshl_add_u64 v[188:189], s[28:29], 0, v[162:163]
	s_add_i32 m0, s34, 0x2000
	s_nop 0
	global_load_lds_dwordx4 v[188:189], off
	v_lshl_add_u64 v[188:189], v[216:217], 0, s[66:67]
	s_mov_b32 m0, s55
	s_nop 0
	global_load_lds_dwordx4 v[188:189], off
	v_lshl_add_u64 v[188:189], v[218:219], 0, s[66:67]
	s_mov_b32 m0, s56
	s_nop 0
	global_load_lds_dwordx4 v[188:189], off
	s_waitcnt vmcnt(8)
	s_waitcnt lgkmcnt(0)
	s_barrier
	s_setprio 1
	s_waitcnt lgkmcnt(0)
	v_mfma_f32_16x16x32_bf16 v[62:65], v[130:133], v[174:177], v[62:65]
	v_mfma_f32_16x16x32_bf16 v[58:61], v[138:141], v[174:177], v[58:61]
	v_mfma_f32_16x16x32_bf16 v[46:49], v[130:133], v[184:187], v[46:49]
	v_mfma_f32_16x16x32_bf16 v[42:45], v[138:141], v[184:187], v[42:45]
	v_mfma_f32_16x16x32_bf16 v[30:33], v[130:133], v[196:199], v[30:33]
	v_mfma_f32_16x16x32_bf16 v[26:29], v[138:141], v[196:199], v[26:29]
	v_mfma_f32_16x16x32_bf16 v[14:17], v[130:133], v[204:207], v[14:17]
	v_mfma_f32_16x16x32_bf16 v[10:13], v[138:141], v[204:207], v[10:13]
	v_mfma_f32_16x16x32_bf16 v[62:65], v[134:137], v[180:183], v[62:65]
	v_mfma_f32_16x16x32_bf16 v[58:61], v[142:145], v[180:183], v[58:61]
	v_mfma_f32_16x16x32_bf16 v[46:49], v[134:137], v[192:195], v[46:49]
	v_mfma_f32_16x16x32_bf16 v[42:45], v[142:145], v[192:195], v[42:45]
	v_mfma_f32_16x16x32_bf16 v[30:33], v[134:137], v[200:203], v[30:33]
	v_mfma_f32_16x16x32_bf16 v[26:29], v[142:145], v[200:203], v[26:29]
	v_mfma_f32_16x16x32_bf16 v[14:17], v[134:137], v[210:213], v[14:17]
	v_mfma_f32_16x16x32_bf16 v[10:13], v[142:145], v[210:213], v[10:13]
	s_setprio 0
	s_setprio 1
	v_mfma_f32_16x16x32_bf16 v[54:57], v[146:149], v[174:177], v[54:57]
	v_mfma_f32_16x16x32_bf16 v[50:53], v[154:157], v[174:177], v[50:53]
	v_mfma_f32_16x16x32_bf16 v[38:41], v[146:149], v[184:187], v[38:41]
	v_mfma_f32_16x16x32_bf16 v[34:37], v[154:157], v[184:187], v[34:37]
	v_mfma_f32_16x16x32_bf16 v[22:25], v[146:149], v[196:199], v[22:25]
	v_mfma_f32_16x16x32_bf16 v[18:21], v[154:157], v[196:199], v[18:21]
	v_mfma_f32_16x16x32_bf16 v[6:9], v[146:149], v[204:207], v[6:9]
	v_mfma_f32_16x16x32_bf16 v[2:5], v[154:157], v[204:207], v[2:5]
	v_mfma_f32_16x16x32_bf16 v[54:57], v[150:153], v[180:183], v[54:57]
	v_mfma_f32_16x16x32_bf16 v[50:53], v[158:161], v[180:183], v[50:53]
	v_mfma_f32_16x16x32_bf16 v[38:41], v[150:153], v[192:195], v[38:41]
	v_mfma_f32_16x16x32_bf16 v[34:37], v[158:161], v[192:195], v[34:37]
	v_mfma_f32_16x16x32_bf16 v[22:25], v[150:153], v[200:203], v[22:25]
	v_mfma_f32_16x16x32_bf16 v[18:21], v[158:161], v[200:203], v[18:21]
	v_mfma_f32_16x16x32_bf16 v[6:9], v[150:153], v[210:213], v[6:9]
	v_mfma_f32_16x16x32_bf16 v[2:5], v[158:161], v[210:213], v[2:5]
	s_setprio 0
	s_barrier
	s_add_i32 s86, s86, 2
	s_add_u32 s8, s8, 0x100
	s_addc_u32 s9, s9, 0
	s_add_u32 s69, s69, 0x100
	s_addc_u32 s85, s85, 0
	s_cmp_gt_u32 s86, 3
	s_cbranch_scc0 .LBB0_632
	s_and_b64 vcc, exec, s[20:21]
	s_cbranch_vccz .LBB0_635
	s_barrier

; #define PG8_STAGE(bufoff, gbase, voff) do { _Pragma("unroll") for (int _i = 0; _i < 2; ++_i) \
;         __builtin_amdgcn_global_load_lds((const unsigned*)((const char*)(gbase) + (voff)[_i]), (PG8_LAS unsigned*)(lds + (bufoff) + ldsw + _i * 8192), 16, 0, 0); } while (0)
; #define PG8_LDA(dst, b, h) do { _Pragma("unroll") for (int m = 0; m < 4; ++m) _Pragma("unroll") for (int k = 0; k < 2; ++k) dst[m][k] = *(const PG8_LAS bf16x8*)(lds + PG8_SA(b, h) + aoff + m * 2048 + k * 1024); } while (0)
; #define PG8_LDB(dst, b, h) do { _Pragma("unroll") for (int n = 0; n < 2; ++n) _Pragma("unroll") for (int k = 0; k < 2; ++k) dst[n][k] = *(const PG8_LAS bf16x8*)(lds + PG8_SB(b, h) + boff + n * 2048 + k * 1024); } while (0)
; #define PG8_MMA(ai, bj, At, Bt) do { __builtin_amdgcn_s_setprio(1); _Pragma("unroll") for (int m = 0; m < 4; ++m) _Pragma("unroll") for (int n = 0; n < 2; ++n) _Pragma("unroll") for (int k = 0; k < 2; ++k) \
;         acc[ai][bj][m][n] = __builtin_amdgcn_mfma_f32_16x16x32_bf16(Bt[n][k], At[m][k], acc[ai][bj][m][n], 0, 0, 0); __builtin_amdgcn_s_setprio(0); } while (0)
; #define PG8_WAIT_V(n) asm volatile("s_waitcnt vmcnt(" #n ")" ::: "memory")
; #define PG8_WAIT_L(n) asm volatile("s_waitcnt lgkmcnt(" #n ")" ::: "memory")
; #define PG8_BAR __builtin_amdgcn_s_barrier()
; #define PG8_SCHED __builtin_amdgcn_sched_barrier(0)
;     ...
;             const char* a1 = cA + (size_t)(t + 1) * kstep;
;             const char* a2 = last ? nA : cA + (size_t)(t + 2) * kstep; const char* b2 = last ? nB : cB + (size_t)(t + 2) * kstep;
;             const char* a3 = a2 + kstep; const char* b3 = b2 + kstep;
;             if (last && has_next) S.a_ready(nxt);
;             if constexpr (SP2) {
;             PG8_LDB(B0, 0, 0); PG8_LDB(B1, 0, 1); PG8_SCHED; PG8_LDA(At, 0, 0); PG8_STAGE(PG8_SA(1, 1), a1 + hstepA, voffA);
;             PG8_WAIT_V(8); PG8_WAIT_L(0); PG8_BAR; PG8_MMA(0, 0, At, B0); PG8_MMA(0, 1, At, B1); PG8_BAR; PG8_SCHED;
;             PG8_LDA(At, 0, 1); PG8_STAGE(PG8_SB(0, 0), b2, voffB); PG8_STAGE(PG8_SB(0, 1), b2 + hstepB, voffB); PG8_STAGE(PG8_SA(0, 0), a2, voffA);
.LBB0_720:
	s_add_u32 s42, s26, s36
	s_addc_u32 s43, s27, s37
	s_add_u32 s40, s42, 0x100
	s_addc_u32 s41, s43, 0
	s_and_b64 s[38:39], s[34:35], exec
	s_cselect_b32 s39, s19, s41
	s_cselect_b32 s38, s85, s40
	s_add_u32 s36, s24, s36
	s_addc_u32 s37, s25, s37
	s_add_u32 s36, s36, 0x100
	s_addc_u32 s37, s37, 0
	s_add_i32 s48, 0, 0x10000
	s_and_b64 s[34:35], s[34:35], exec
	s_cselect_b32 s41, s17, s37
	s_cselect_b32 s40, s91, s36
	s_add_i32 s35, 0, 0x14000
	s_add_u32 s44, s42, 0x10080
	s_addc_u32 s45, s43, 0
	s_add_i32 vcc_hi, s48, s54
	s_add_i32 m0, s55, 0xc000
	s_add_i32 s49, s55, 0xe000
	s_add_i32 s96, vcc_hi, 0x2000
	s_add_u32 s42, s40, 0x10000
	v_add_u32_e32 v150, s48, v1
	v_add_u32_e32 v158, s35, v1
	s_addc_u32 s43, s41, 0
	s_add_i32 vcc_lo, s35, s54
	ds_read_b128 v[130:133], v150
	ds_read_b128 v[134:137], v150 offset:1024
	ds_read_b128 v[146:149], v150 offset:2048
	ds_read_b128 v[150:153], v150 offset:3072
	ds_read_b128 v[154:157], v158
	ds_read_b128 v[160:163], v158 offset:1024
	ds_read_b128 v[164:167], v158 offset:2048
	ds_read_b128 v[168:171], v158 offset:3072
	s_add_i32 s97, vcc_lo, 0x2000
	s_add_i32 s95, 0, 0x18000
	s_add_i32 s94, 0, 0x1c000
	s_add_u32 s36, s38, 0x10000
	s_addc_u32 s37, s39, 0
	s_add_i32 s93, s95, s54
	s_add_i32 s92, s93, 0x2000
	s_add_u32 s34, s40, 0x10080
	s_addc_u32 s35, s41, 0
	s_add_i32 s61, s94, s54
	s_add_i32 s48, s61, 0x2000
	v_lshl_add_u64 v[176:177], s[44:45], 0, v[144:145]
	ds_read_b128 v[172:175], v159
	ds_read_b128 v[180:183], v159 offset:1024
	ds_read_b128 v[184:187], v159 offset:2048
	ds_read_b128 v[188:191], v159 offset:3072
	ds_read_b128 v[192:195], v159 offset:4096
	ds_read_b128 v[196:199], v159 offset:5120
	ds_read_b128 v[200:203], v159 offset:6144
	ds_read_b128 v[204:207], v159 offset:7168
	global_load_lds_dwordx4 v[176:177], off
	v_lshl_add_u64 v[176:177], s[44:45], 0, v[140:141]
	s_mov_b32 m0, s49
	s_nop 0
	global_load_lds_dwordx4 v[176:177], off
	s_waitcnt vmcnt(8)
	s_waitcnt lgkmcnt(0)
	s_barrier
	s_setprio 1
	s_waitcnt lgkmcnt(0)
	v_mfma_f32_16x16x32_bf16 v[126:129], v[130:133], v[172:175], v[126:129]
	v_mfma_f32_16x16x32_bf16 v[122:125], v[146:149], v[172:175], v[122:125]
	v_mfma_f32_16x16x32_bf16 v[110:113], v[130:133], v[184:187], v[110:113]
	v_mfma_f32_16x16x32_bf16 v[106:109], v[146:149], v[184:187], v[106:109]
	v_mfma_f32_16x16x32_bf16 v[94:97], v[130:133], v[192:195], v[94:97]
	v_mfma_f32_16x16x32_bf16 v[90:93], v[146:149], v[192:195], v[90:93]
	v_mfma_f32_16x16x32_bf16 v[78:81], v[130:133], v[200:203], v[78:81]
	v_mfma_f32_16x16x32_bf16 v[74:77], v[146:149], v[200:203], v[74:77]
	v_mfma_f32_16x16x32_bf16 v[126:129], v[134:137], v[180:183], v[126:129]
	v_mfma_f32_16x16x32_bf16 v[122:125], v[150:153], v[180:183], v[122:125]
	v_mfma_f32_16x16x32_bf16 v[110:113], v[134:137], v[188:191], v[110:113]
	v_mfma_f32_16x16x32_bf16 v[106:109], v[150:153], v[188:191], v[106:109]
	v_mfma_f32_16x16x32_bf16 v[94:97], v[134:137], v[196:199], v[94:97]
	v_mfma_f32_16x16x32_bf16 v[90:93], v[150:153], v[196:199], v[90:93]
	v_mfma_f32_16x16x32_bf16 v[78:81], v[134:137], v[204:207], v[78:81]
	v_mfma_f32_16x16x32_bf16 v[74:77], v[150:153], v[204:207], v[74:77]
	s_setprio 0
	s_setprio 1
	v_mfma_f32_16x16x32_bf16 v[118:121], v[154:157], v[172:175], v[118:121]
	v_mfma_f32_16x16x32_bf16 v[114:117], v[164:167], v[172:175], v[114:117]
	v_mfma_f32_16x16x32_bf16 v[102:105], v[154:157], v[184:187], v[102:105]
	v_mfma_f32_16x16x32_bf16 v[98:101], v[164:167], v[184:187], v[98:101]
	v_mfma_f32_16x16x32_bf16 v[86:89], v[154:157], v[192:195], v[86:89]
	v_mfma_f32_16x16x32_bf16 v[82:85], v[164:167], v[192:195], v[82:85]
	v_mfma_f32_16x16x32_bf16 v[70:73], v[154:157], v[200:203], v[70:73]
	v_mfma_f32_16x16x32_bf16 v[66:69], v[164:167], v[200:203], v[66:69]
	v_mfma_f32_16x16x32_bf16 v[118:121], v[160:163], v[180:183], v[118:121]
	v_mfma_f32_16x16x32_bf16 v[114:117], v[168:171], v[180:183], v[114:117]
	v_mfma_f32_16x16x32_bf16 v[102:105], v[160:163], v[188:191], v[102:105]
	v_mfma_f32_16x16x32_bf16 v[98:101], v[168:171], v[188:191], v[98:101]
	v_mfma_f32_16x16x32_bf16 v[86:89], v[160:163], v[196:199], v[86:89]
	v_mfma_f32_16x16x32_bf16 v[82:85], v[168:171], v[196:199], v[82:85]
	v_mfma_f32_16x16x32_bf16 v[70:73], v[160:163], v[204:207], v[70:73]
	v_mfma_f32_16x16x32_bf16 v[66:69], v[168:171], v[204:207], v[66:69]
	s_setprio 0
	s_barrier
	s_mov_b32 m0, vcc_hi
	ds_read_b128 v[172:175], v159 offset:16384
	ds_read_b128 v[180:183], v159 offset:17408
	ds_read_b128 v[184:187], v159 offset:18432
	ds_read_b128 v[188:191], v159 offset:19456
	ds_read_b128 v[192:195], v159 offset:20480
	ds_read_b128 v[196:199], v159 offset:21504
	ds_read_b128 v[200:203], v159 offset:22528
	ds_read_b128 v[204:207], v159 offset:23552
	v_lshl_add_u64 v[176:177], s[40:41], 0, v[142:143]
	global_load_lds_dwordx4 v[176:177], off
	v_lshl_add_u64 v[210:211], s[40:41], 0, v[138:139]
	s_mov_b32 m0, s96
	v_lshl_add_u64 v[212:213], s[42:43], 0, v[142:143]
	global_load_lds_dwordx4 v[210:211], off
	s_mov_b32 m0, vcc_lo
	v_lshl_add_u64 v[214:215], s[38:39], 0, v[140:141]
	global_load_lds_dwordx4 v[212:213], off
	v_lshl_add_u64 v[212:213], s[42:43], 0, v[138:139]
	s_mov_b32 m0, s97
	s_nop 0
	global_load_lds_dwordx4 v[212:213], off
	v_lshl_add_u64 v[212:213], s[38:39], 0, v[144:145]
	s_mov_b32 m0, s55
	s_nop 0
	global_load_lds_dwordx4 v[212:213], off
	s_mov_b32 m0, s56
	s_nop 0
	global_load_lds_dwordx4 v[214:215], off
	s_waitcnt vmcnt(8)
	s_waitcnt lgkmcnt(0)
	s_barrier
; #define PG8_STAGE(bufoff, gbase, voff) do { _Pragma("unroll") for (int _i = 0; _i < 2; ++_i) \
;         __builtin_amdgcn_global_load_lds((const unsigned*)((const char*)(gbase) + (voff)[_i]), (PG8_LAS unsigned*)(lds + (bufoff) + ldsw + _i * 8192), 16, 0, 0); } while (0)
; #define PG8_LDA(dst, b, h) do { _Pragma("unroll") for (int m = 0; m < 4; ++m) _Pragma("unroll") for (int k = 0; k < 2; ++k) dst[m][k] = *(const PG8_LAS bf16x8*)(lds + PG8_SA(b, h) + aoff + m * 2048 + k * 1024); } while (0)
; #define PG8_LDB(dst, b, h) do { _Pragma("unroll") for (int n = 0; n < 2; ++n) _Pragma("unroll") for (int k = 0; k < 2; ++k) dst[n][k] = *(const PG8_LAS bf16x8*)(lds + PG8_SB(b, h) + boff + n * 2048 + k * 1024); } while (0)
; #define PG8_MMA(ai, bj, At, Bt) do { __builtin_amdgcn_s_setprio(1); _Pragma("unroll") for (int m = 0; m < 4; ++m) _Pragma("unroll") for (int n = 0; n < 2; ++n) _Pragma("unroll") for (int k = 0; k < 2; ++k) \
;         acc[ai][bj][m][n] = __builtin_amdgcn_mfma_f32_16x16x32_bf16(Bt[n][k], At[m][k], acc[ai][bj][m][n], 0, 0, 0); __builtin_amdgcn_s_setprio(0); } while (0)
; #define PG8_WAIT_V(n) asm volatile("s_waitcnt vmcnt(" #n ")" ::: "memory")
; #define PG8_WAIT_L(n) asm volatile("s_waitcnt lgkmcnt(" #n ")" ::: "memory")
; #define PG8_BAR __builtin_amdgcn_s_barrier()
; #define PG8_SCHED __builtin_amdgcn_sched_barrier(0)
;     ...
;             PG8_LDA(At, 0, 1); PG8_STAGE(PG8_SB(0, 0), b2, voffB); PG8_STAGE(PG8_SB(0, 1), b2 + hstepB, voffB); PG8_STAGE(PG8_SA(0, 0), a2, voffA);
;             PG8_WAIT_V(8); PG8_WAIT_L(0); PG8_BAR; PG8_MMA(1, 0, At, B0); PG8_MMA(1, 1, At, B1); PG8_BAR; PG8_SCHED;
;             PG8_LDB(B0, 1, 0); PG8_LDB(B1, 1, 1); PG8_SCHED; PG8_LDA(At, 1, 0); PG8_STAGE(PG8_SA(0, 1), a2 + hstepA, voffA);
;             PG8_WAIT_V(8); PG8_WAIT_L(0); PG8_BAR; PG8_MMA(0, 0, At, B0); PG8_MMA(0, 1, At, B1); PG8_BAR; PG8_SCHED;
	s_setprio 1
	s_waitcnt lgkmcnt(0)
	v_mfma_f32_16x16x32_bf16 v[62:65], v[130:133], v[172:175], v[62:65]
	v_mfma_f32_16x16x32_bf16 v[58:61], v[146:149], v[172:175], v[58:61]
	v_mfma_f32_16x16x32_bf16 v[46:49], v[130:133], v[184:187], v[46:49]
	v_mfma_f32_16x16x32_bf16 v[42:45], v[146:149], v[184:187], v[42:45]
	v_mfma_f32_16x16x32_bf16 v[30:33], v[130:133], v[192:195], v[30:33]
	v_mfma_f32_16x16x32_bf16 v[26:29], v[146:149], v[192:195], v[26:29]
	v_mfma_f32_16x16x32_bf16 v[14:17], v[130:133], v[200:203], v[14:17]
	v_mfma_f32_16x16x32_bf16 v[10:13], v[146:149], v[200:203], v[10:13]
	v_mfma_f32_16x16x32_bf16 v[62:65], v[134:137], v[180:183], v[62:65]
	v_mfma_f32_16x16x32_bf16 v[58:61], v[150:153], v[180:183], v[58:61]
	v_mfma_f32_16x16x32_bf16 v[46:49], v[134:137], v[188:191], v[46:49]
	v_mfma_f32_16x16x32_bf16 v[42:45], v[150:153], v[188:191], v[42:45]
	v_mfma_f32_16x16x32_bf16 v[30:33], v[134:137], v[196:199], v[30:33]
	v_mfma_f32_16x16x32_bf16 v[26:29], v[150:153], v[196:199], v[26:29]
	v_mfma_f32_16x16x32_bf16 v[14:17], v[134:137], v[204:207], v[14:17]
	v_mfma_f32_16x16x32_bf16 v[10:13], v[150:153], v[204:207], v[10:13]
	s_setprio 0
	s_setprio 1
	v_mfma_f32_16x16x32_bf16 v[54:57], v[154:157], v[172:175], v[54:57]
	v_mfma_f32_16x16x32_bf16 v[50:53], v[164:167], v[172:175], v[50:53]
	v_mfma_f32_16x16x32_bf16 v[38:41], v[154:157], v[184:187], v[38:41]
	v_mfma_f32_16x16x32_bf16 v[34:37], v[164:167], v[184:187], v[34:37]
	v_mfma_f32_16x16x32_bf16 v[22:25], v[154:157], v[192:195], v[22:25]
	v_mfma_f32_16x16x32_bf16 v[18:21], v[164:167], v[192:195], v[18:21]
	v_mfma_f32_16x16x32_bf16 v[6:9], v[154:157], v[200:203], v[6:9]
	v_mfma_f32_16x16x32_bf16 v[2:5], v[164:167], v[200:203], v[2:5]
	v_mfma_f32_16x16x32_bf16 v[54:57], v[160:163], v[180:183], v[54:57]
	v_mfma_f32_16x16x32_bf16 v[50:53], v[168:171], v[180:183], v[50:53]
	v_mfma_f32_16x16x32_bf16 v[38:41], v[160:163], v[188:191], v[38:41]
	v_mfma_f32_16x16x32_bf16 v[34:37], v[168:171], v[188:191], v[34:37]
	v_mfma_f32_16x16x32_bf16 v[22:25], v[160:163], v[196:199], v[22:25]
	v_mfma_f32_16x16x32_bf16 v[18:21], v[168:171], v[196:199], v[18:21]
	v_mfma_f32_16x16x32_bf16 v[6:9], v[160:163], v[204:207], v[6:9]
	v_mfma_f32_16x16x32_bf16 v[2:5], v[168:171], v[204:207], v[2:5]
	s_setprio 0
	s_barrier
	v_add_u32_e32 v150, s95, v1
	v_add_u32_e32 v158, s94, v1
	ds_read_b128 v[130:133], v150
	ds_read_b128 v[134:137], v150 offset:1024
	ds_read_b128 v[146:149], v150 offset:2048
	ds_read_b128 v[150:153], v150 offset:3072
	ds_read_b128 v[154:157], v158
	ds_read_b128 v[160:163], v158 offset:1024
	ds_read_b128 v[164:167], v158 offset:2048
	ds_read_b128 v[168:171], v158 offset:3072
	s_mov_b32 m0, s57
	v_lshl_add_u64 v[216:217], s[36:37], 0, v[144:145]
	ds_read_b128 v[172:175], v159 offset:32768
	ds_read_b128 v[180:183], v159 offset:33792
	ds_read_b128 v[184:187], v159 offset:34816
	ds_read_b128 v[188:191], v159 offset:35840
	ds_read_b128 v[192:195], v159 offset:36864
	ds_read_b128 v[196:199], v159 offset:37888
	ds_read_b128 v[200:203], v159 offset:38912
	ds_read_b128 v[204:207], v159 offset:39936
	global_load_lds_dwordx4 v[216:217], off
	v_lshl_add_u64 v[216:217], s[36:37], 0, v[140:141]
	s_mov_b32 m0, s58
	s_nop 0
	global_load_lds_dwordx4 v[216:217], off
	s_waitcnt vmcnt(8)
	s_waitcnt lgkmcnt(0)
	s_barrier
	s_setprio 1
	s_waitcnt lgkmcnt(0)
	v_mfma_f32_16x16x32_bf16 v[126:129], v[130:133], v[172:175], v[126:129]
	v_mfma_f32_16x16x32_bf16 v[122:125], v[146:149], v[172:175], v[122:125]
	v_mfma_f32_16x16x32_bf16 v[110:113], v[130:133], v[184:187], v[110:113]
	v_mfma_f32_16x16x32_bf16 v[106:109], v[146:149], v[184:187], v[106:109]
	v_mfma_f32_16x16x32_bf16 v[94:97], v[130:133], v[192:195], v[94:97]
	v_mfma_f32_16x16x32_bf16 v[90:93], v[146:149], v[192:195], v[90:93]
	v_mfma_f32_16x16x32_bf16 v[78:81], v[130:133], v[200:203], v[78:81]
	v_mfma_f32_16x16x32_bf16 v[74:77], v[146:149], v[200:203], v[74:77]
	v_mfma_f32_16x16x32_bf16 v[126:129], v[134:137], v[180:183], v[126:129]
	v_mfma_f32_16x16x32_bf16 v[122:125], v[150:153], v[180:183], v[122:125]
	v_mfma_f32_16x16x32_bf16 v[110:113], v[134:137], v[188:191], v[110:113]
	v_mfma_f32_16x16x32_bf16 v[106:109], v[150:153], v[188:191], v[106:109]
	v_mfma_f32_16x16x32_bf16 v[94:97], v[134:137], v[196:199], v[94:97]
	v_mfma_f32_16x16x32_bf16 v[90:93], v[150:153], v[196:199], v[90:93]
	v_mfma_f32_16x16x32_bf16 v[78:81], v[134:137], v[204:207], v[78:81]
	v_mfma_f32_16x16x32_bf16 v[74:77], v[150:153], v[204:207], v[74:77]
	s_setprio 0
	s_setprio 1
	v_mfma_f32_16x16x32_bf16 v[118:121], v[154:157], v[172:175], v[118:121]
	v_mfma_f32_16x16x32_bf16 v[114:117], v[164:167], v[172:175], v[114:117]
	v_mfma_f32_16x16x32_bf16 v[102:105], v[154:157], v[184:187], v[102:105]
	v_mfma_f32_16x16x32_bf16 v[98:101], v[164:167], v[184:187], v[98:101]
	v_mfma_f32_16x16x32_bf16 v[86:89], v[154:157], v[192:195], v[86:89]
	v_mfma_f32_16x16x32_bf16 v[82:85], v[164:167], v[192:195], v[82:85]
	v_mfma_f32_16x16x32_bf16 v[70:73], v[154:157], v[200:203], v[70:73]
	v_mfma_f32_16x16x32_bf16 v[66:69], v[164:167], v[200:203], v[66:69]
	v_mfma_f32_16x16x32_bf16 v[118:121], v[160:163], v[180:183], v[118:121]
	v_mfma_f32_16x16x32_bf16 v[114:117], v[168:171], v[180:183], v[114:117]
	v_mfma_f32_16x16x32_bf16 v[102:105], v[160:163], v[188:191], v[102:105]
	v_mfma_f32_16x16x32_bf16 v[98:101], v[168:171], v[188:191], v[98:101]
	v_mfma_f32_16x16x32_bf16 v[86:89], v[160:163], v[196:199], v[86:89]
	v_mfma_f32_16x16x32_bf16 v[82:85], v[168:171], v[196:199], v[82:85]
	v_mfma_f32_16x16x32_bf16 v[70:73], v[160:163], v[204:207], v[70:73]
	v_mfma_f32_16x16x32_bf16 v[66:69], v[168:171], v[204:207], v[66:69]
	s_setprio 0
	s_barrier
; #define PG8_STAGE(bufoff, gbase, voff) do { _Pragma("unroll") for (int _i = 0; _i < 2; ++_i) \
;         __builtin_amdgcn_global_load_lds((const unsigned*)((const char*)(gbase) + (voff)[_i]), (PG8_LAS unsigned*)(lds + (bufoff) + ldsw + _i * 8192), 16, 0, 0); } while (0)
; #define PG8_LDA(dst, b, h) do { _Pragma("unroll") for (int m = 0; m < 4; ++m) _Pragma("unroll") for (int k = 0; k < 2; ++k) dst[m][k] = *(const PG8_LAS bf16x8*)(lds + PG8_SA(b, h) + aoff + m * 2048 + k * 1024); } while (0)
; #define PG8_MMA(ai, bj, At, Bt) do { __builtin_amdgcn_s_setprio(1); _Pragma("unroll") for (int m = 0; m < 4; ++m) _Pragma("unroll") for (int n = 0; n < 2; ++n) _Pragma("unroll") for (int k = 0; k < 2; ++k) \
;         acc[ai][bj][m][n] = __builtin_amdgcn_mfma_f32_16x16x32_bf16(Bt[n][k], At[m][k], acc[ai][bj][m][n], 0, 0, 0); __builtin_amdgcn_s_setprio(0); } while (0)
; #define PG8_WAIT_V(n) asm volatile("s_waitcnt vmcnt(" #n ")" ::: "memory")
; #define PG8_WAIT_L(n) asm volatile("s_waitcnt lgkmcnt(" #n ")" ::: "memory")
; #define PG8_BAR __builtin_amdgcn_s_barrier()
; #define PG8_SCHED __builtin_amdgcn_sched_barrier(0)
;     ...
;             PG8_LDA(At, 1, 1); PG8_STAGE(PG8_SB(1, 0), b3, voffB); PG8_STAGE(PG8_SB(1, 1), b3 + hstepB, voffB); PG8_STAGE(PG8_SA(1, 0), a3, voffA);
;             PG8_WAIT_V(8); PG8_WAIT_L(0); PG8_BAR; PG8_MMA(1, 0, At, B0); PG8_MMA(1, 1, At, B1); PG8_BAR; PG8_SCHED;
	s_mov_b32 m0, s93
	ds_read_b128 v[172:175], v159 offset:49152
	ds_read_b128 v[180:183], v159 offset:50176
	ds_read_b128 v[184:187], v159 offset:51200
	ds_read_b128 v[188:191], v159 offset:52224
	ds_read_b128 v[192:195], v159 offset:53248
	ds_read_b128 v[196:199], v159 offset:54272
	ds_read_b128 v[200:203], v159 offset:55296
	ds_read_b128 v[204:207], v159 offset:56320
	v_lshl_add_u64 v[176:177], v[176:177], 0, s[66:67]
	global_load_lds_dwordx4 v[176:177], off
	v_lshl_add_u64 v[176:177], v[210:211], 0, s[66:67]
	s_mov_b32 m0, s92
	s_nop 0
	global_load_lds_dwordx4 v[176:177], off
	v_lshl_add_u64 v[176:177], s[34:35], 0, v[142:143]
	s_mov_b32 m0, s61
	s_nop 0
	global_load_lds_dwordx4 v[176:177], off
	v_lshl_add_u64 v[176:177], s[34:35], 0, v[138:139]
	s_mov_b32 m0, s48
	s_nop 0
	global_load_lds_dwordx4 v[176:177], off
	v_lshl_add_u64 v[176:177], v[212:213], 0, s[66:67]
	s_mov_b32 m0, s87
	s_nop 0
	global_load_lds_dwordx4 v[176:177], off
	v_lshl_add_u64 v[176:177], v[214:215], 0, s[66:67]
	s_mov_b32 m0, s88
	s_nop 0
	global_load_lds_dwordx4 v[176:177], off
	s_waitcnt vmcnt(8)
	s_waitcnt lgkmcnt(0)
	s_barrier
	s_setprio 1
	s_waitcnt lgkmcnt(0)
	v_mfma_f32_16x16x32_bf16 v[62:65], v[130:133], v[172:175], v[62:65]
	v_mfma_f32_16x16x32_bf16 v[58:61], v[146:149], v[172:175], v[58:61]
	v_mfma_f32_16x16x32_bf16 v[46:49], v[130:133], v[184:187], v[46:49]
	v_mfma_f32_16x16x32_bf16 v[42:45], v[146:149], v[184:187], v[42:45]
	v_mfma_f32_16x16x32_bf16 v[30:33], v[130:133], v[192:195], v[30:33]
	v_mfma_f32_16x16x32_bf16 v[26:29], v[146:149], v[192:195], v[26:29]
	v_mfma_f32_16x16x32_bf16 v[14:17], v[130:133], v[200:203], v[14:17]
	v_mfma_f32_16x16x32_bf16 v[10:13], v[146:149], v[200:203], v[10:13]
	v_mfma_f32_16x16x32_bf16 v[62:65], v[134:137], v[180:183], v[62:65]
	v_mfma_f32_16x16x32_bf16 v[58:61], v[150:153], v[180:183], v[58:61]
	v_mfma_f32_16x16x32_bf16 v[46:49], v[134:137], v[188:191], v[46:49]
	v_mfma_f32_16x16x32_bf16 v[42:45], v[150:153], v[188:191], v[42:45]
	v_mfma_f32_16x16x32_bf16 v[30:33], v[134:137], v[196:199], v[30:33]
	v_mfma_f32_16x16x32_bf16 v[26:29], v[150:153], v[196:199], v[26:29]
	v_mfma_f32_16x16x32_bf16 v[14:17], v[134:137], v[204:207], v[14:17]
	v_mfma_f32_16x16x32_bf16 v[10:13], v[150:153], v[204:207], v[10:13]
	s_setprio 0
	s_setprio 1
	v_mfma_f32_16x16x32_bf16 v[54:57], v[154:157], v[172:175], v[54:57]
	v_mfma_f32_16x16x32_bf16 v[50:53], v[164:167], v[172:175], v[50:53]
	v_mfma_f32_16x16x32_bf16 v[38:41], v[154:157], v[184:187], v[38:41]
	v_mfma_f32_16x16x32_bf16 v[34:37], v[164:167], v[184:187], v[34:37]
	v_mfma_f32_16x16x32_bf16 v[22:25], v[154:157], v[192:195], v[22:25]
	v_mfma_f32_16x16x32_bf16 v[18:21], v[164:167], v[192:195], v[18:21]
	v_mfma_f32_16x16x32_bf16 v[6:9], v[154:157], v[200:203], v[6:9]
	v_mfma_f32_16x16x32_bf16 v[2:5], v[164:167], v[200:203], v[2:5]
	v_mfma_f32_16x16x32_bf16 v[54:57], v[160:163], v[180:183], v[54:57]
	v_mfma_f32_16x16x32_bf16 v[50:53], v[168:171], v[180:183], v[50:53]
	v_mfma_f32_16x16x32_bf16 v[38:41], v[160:163], v[188:191], v[38:41]
	v_mfma_f32_16x16x32_bf16 v[34:37], v[168:171], v[188:191], v[34:37]
	v_mfma_f32_16x16x32_bf16 v[22:25], v[160:163], v[196:199], v[22:25]
	v_mfma_f32_16x16x32_bf16 v[18:21], v[168:171], v[196:199], v[18:21]
	v_mfma_f32_16x16x32_bf16 v[6:9], v[160:163], v[204:207], v[6:9]
	v_mfma_f32_16x16x32_bf16 v[2:5], v[168:171], v[204:207], v[2:5]
	s_setprio 0
	s_barrier
	s_andn2_b64 vcc, exec, s[28:29]
	s_mov_b64 s[34:35], -1
	s_mov_b64 s[28:29], 0
	s_mov_b64 s[36:37], 0x100
	s_cbranch_vccz .LBB0_720
	s_and_b64 vcc, exec, s[14:15]
	s_cbranch_vccz .LBB0_723
	s_barrier

; #define PG8_STAGE(bufoff, gbase, voff) do { _Pragma("unroll") for (int _i = 0; _i < 2; ++_i) \
;         __builtin_amdgcn_global_load_lds((const unsigned*)((const char*)(gbase) + (voff)[_i]), (PG8_LAS unsigned*)(lds + (bufoff) + ldsw + _i * 8192), 16, 0, 0); } while (0)
; #define PG8_LDA(dst, b, h) do { _Pragma("unroll") for (int m = 0; m < 4; ++m) _Pragma("unroll") for (int k = 0; k < 2; ++k) dst[m][k] = *(const PG8_LAS bf16x8*)(lds + PG8_SA(b, h) + aoff + m * 2048 + k * 1024); } while (0)
; #define PG8_LDB(dst, b, h) do { _Pragma("unroll") for (int n = 0; n < 2; ++n) _Pragma("unroll") for (int k = 0; k < 2; ++k) dst[n][k] = *(const PG8_LAS bf16x8*)(lds + PG8_SB(b, h) + boff + n * 2048 + k * 1024); } while (0)
; #define PG8_MMA(ai, bj, At, Bt) do { __builtin_amdgcn_s_setprio(1); _Pragma("unroll") for (int m = 0; m < 4; ++m) _Pragma("unroll") for (int n = 0; n < 2; ++n) _Pragma("unroll") for (int k = 0; k < 2; ++k) \
;         acc[ai][bj][m][n] = __builtin_amdgcn_mfma_f32_16x16x32_bf16(Bt[n][k], At[m][k], acc[ai][bj][m][n], 0, 0, 0); __builtin_amdgcn_s_setprio(0); } while (0)
; #define PG8_WAIT_V(n) asm volatile("s_waitcnt vmcnt(" #n ")" ::: "memory")
; #define PG8_WAIT_L(n) asm volatile("s_waitcnt lgkmcnt(" #n ")" ::: "memory")
; #define PG8_BAR __builtin_amdgcn_s_barrier()
; #define PG8_SCHED __builtin_amdgcn_sched_barrier(0)
;     ...
;             const char* a1 = cA + (size_t)(t + 1) * kstep;
;             const char* a2 = last ? nA : cA + (size_t)(t + 2) * kstep; const char* b2 = last ? nB : cB + (size_t)(t + 2) * kstep;
;             const char* a3 = a2 + kstep; const char* b3 = b2 + kstep;
;             if (last && has_next) S.a_ready(nxt);
;             if constexpr (SP2) {
;             PG8_LDB(B0, 0, 0); PG8_LDB(B1, 0, 1); PG8_SCHED; PG8_LDA(At, 0, 0); PG8_STAGE(PG8_SA(1, 1), a1 + hstepA, voffA);
;             PG8_WAIT_V(8); PG8_WAIT_L(0); PG8_BAR; PG8_MMA(0, 0, At, B0); PG8_MMA(0, 1, At, B1); PG8_BAR; PG8_SCHED;
;             PG8_LDA(At, 0, 1); PG8_STAGE(PG8_SB(0, 0), b2, voffB); PG8_STAGE(PG8_SB(0, 1), b2 + hstepB, voffB); PG8_STAGE(PG8_SA(0, 0), a2, voffA);
.LBB0_963:
	s_add_u32 s28, s6, 0xfffe0080
	s_addc_u32 s29, s7, -1
	s_add_i32 s48, 0, 0x10000
	s_cmp_eq_u32 s81, 4
	s_cselect_b32 s35, s57, s29
	s_cselect_b32 s34, s77, s28
	s_cselect_b32 s29, s55, s80
	s_cselect_b32 s28, s78, s79
	s_add_i32 s82, 0, 0x14000
	v_add_u32_e32 v92, s48, v234
	v_add_u32_e32 v132, s82, v234
	ds_read_b128 v[64:67], v92
	ds_read_b128 v[68:71], v92 offset:1024
	ds_read_b128 v[80:83], v92 offset:2048
	ds_read_b128 v[92:95], v92 offset:3072
	ds_read_b128 v[104:107], v132
	ds_read_b128 v[108:111], v132 offset:1024
	ds_read_b128 v[120:123], v132 offset:2048
	ds_read_b128 v[132:135], v132 offset:3072
	v_lshl_add_u64 v[208:209], s[6:7], 0, v[204:205]
	s_add_i32 m0, s66, 0xc000
	ds_read_b128 v[152:155], v235
	ds_read_b128 v[164:167], v235 offset:1024
	ds_read_b128 v[168:171], v235 offset:2048
	ds_read_b128 v[172:175], v235 offset:3072
	ds_read_b128 v[176:179], v235 offset:4096
	ds_read_b128 v[180:183], v235 offset:5120
	ds_read_b128 v[184:187], v235 offset:6144
	ds_read_b128 v[188:191], v235 offset:7168
	global_load_lds_dwordx4 v[208:209], off
	v_lshl_add_u64 v[208:209], s[6:7], 0, v[206:207]
	s_add_i32 m0, s66, 0xe000
	s_nop 0
	global_load_lds_dwordx4 v[208:209], off
	s_waitcnt vmcnt(8)
	s_waitcnt lgkmcnt(0)
	s_barrier
	s_setprio 1
	s_waitcnt lgkmcnt(0)
	v_mfma_f32_16x16x32_bf16 v[160:163], v[64:67], v[152:155], v[160:163]
	v_mfma_f32_16x16x32_bf16 v[156:159], v[80:83], v[152:155], v[156:159]
	v_mfma_f32_16x16x32_bf16 v[140:143], v[64:67], v[168:171], v[140:143]
	v_mfma_f32_16x16x32_bf16 v[136:139], v[80:83], v[168:171], v[136:139]
	v_mfma_f32_16x16x32_bf16 v[116:119], v[64:67], v[176:179], v[116:119]
	v_mfma_f32_16x16x32_bf16 v[112:115], v[80:83], v[176:179], v[112:115]
	v_mfma_f32_16x16x32_bf16 v[88:91], v[64:67], v[184:187], v[88:91]
	v_mfma_f32_16x16x32_bf16 v[84:87], v[80:83], v[184:187], v[84:87]
	v_mfma_f32_16x16x32_bf16 v[160:163], v[68:71], v[164:167], v[160:163]
	v_mfma_f32_16x16x32_bf16 v[156:159], v[92:95], v[164:167], v[156:159]
	v_mfma_f32_16x16x32_bf16 v[140:143], v[68:71], v[172:175], v[140:143]
	v_mfma_f32_16x16x32_bf16 v[136:139], v[92:95], v[172:175], v[136:139]
	v_mfma_f32_16x16x32_bf16 v[116:119], v[68:71], v[180:183], v[116:119]
	v_mfma_f32_16x16x32_bf16 v[112:115], v[92:95], v[180:183], v[112:115]
	v_mfma_f32_16x16x32_bf16 v[88:91], v[68:71], v[188:191], v[88:91]
	v_mfma_f32_16x16x32_bf16 v[84:87], v[92:95], v[188:191], v[84:87]
	s_setprio 0
	s_setprio 1
	v_mfma_f32_16x16x32_bf16 v[148:151], v[104:107], v[152:155], v[148:151]
	v_mfma_f32_16x16x32_bf16 v[144:147], v[120:123], v[152:155], v[144:147]
	v_mfma_f32_16x16x32_bf16 v[128:131], v[104:107], v[168:171], v[128:131]
	v_mfma_f32_16x16x32_bf16 v[124:127], v[120:123], v[168:171], v[124:127]
	v_mfma_f32_16x16x32_bf16 v[100:103], v[104:107], v[176:179], v[100:103]
	v_mfma_f32_16x16x32_bf16 v[96:99], v[120:123], v[176:179], v[96:99]
	v_mfma_f32_16x16x32_bf16 v[76:79], v[104:107], v[184:187], v[76:79]
	v_mfma_f32_16x16x32_bf16 v[72:75], v[120:123], v[184:187], v[72:75]
	v_mfma_f32_16x16x32_bf16 v[148:151], v[108:111], v[164:167], v[148:151]
	v_mfma_f32_16x16x32_bf16 v[144:147], v[132:135], v[164:167], v[144:147]
	v_mfma_f32_16x16x32_bf16 v[128:131], v[108:111], v[172:175], v[128:131]
	v_mfma_f32_16x16x32_bf16 v[124:127], v[132:135], v[172:175], v[124:127]
	v_mfma_f32_16x16x32_bf16 v[100:103], v[108:111], v[180:183], v[100:103]
	v_mfma_f32_16x16x32_bf16 v[96:99], v[132:135], v[180:183], v[96:99]
	v_mfma_f32_16x16x32_bf16 v[76:79], v[108:111], v[188:191], v[76:79]
	v_mfma_f32_16x16x32_bf16 v[72:75], v[132:135], v[188:191], v[72:75]
	s_setprio 0
	s_barrier
	s_add_i32 s48, s48, s65
	s_mov_b32 m0, s48
	ds_read_b128 v[152:155], v235 offset:16384
	ds_read_b128 v[164:167], v235 offset:17408
	ds_read_b128 v[168:171], v235 offset:18432
	ds_read_b128 v[172:175], v235 offset:19456
	ds_read_b128 v[176:179], v235 offset:20480
	ds_read_b128 v[180:183], v235 offset:21504
	ds_read_b128 v[184:187], v235 offset:22528
	ds_read_b128 v[188:191], v235 offset:23552
	v_lshl_add_u64 v[208:209], s[28:29], 0, v[192:193]
	global_load_lds_dwordx4 v[208:209], off
	s_add_i32 m0, s48, 0x2000
	s_add_u32 s48, s28, 0x20000
	v_lshl_add_u64 v[210:211], s[28:29], 0, v[198:199]
	s_addc_u32 s49, s29, 0
	s_add_i32 s82, s82, s65
	global_load_lds_dwordx4 v[210:211], off
	v_lshl_add_u64 v[212:213], s[48:49], 0, v[192:193]
	s_mov_b32 m0, s82
	v_lshl_add_u64 v[214:215], s[34:35], 0, v[200:201]
	global_load_lds_dwordx4 v[212:213], off
	v_lshl_add_u64 v[212:213], s[48:49], 0, v[198:199]
	s_add_i32 m0, s82, 0x2000
	s_nop 0
	global_load_lds_dwordx4 v[212:213], off
	v_lshl_add_u64 v[212:213], s[34:35], 0, v[202:203]
	s_mov_b32 m0, s66
	s_nop 0
	global_load_lds_dwordx4 v[212:213], off
	s_mov_b32 m0, s67
	s_nop 0
	global_load_lds_dwordx4 v[214:215], off
	s_waitcnt vmcnt(8)
	s_waitcnt lgkmcnt(0)
	s_barrier
; #define PG8_STAGE(bufoff, gbase, voff) do { _Pragma("unroll") for (int _i = 0; _i < 2; ++_i) \
;         __builtin_amdgcn_global_load_lds((const unsigned*)((const char*)(gbase) + (voff)[_i]), (PG8_LAS unsigned*)(lds + (bufoff) + ldsw + _i * 8192), 16, 0, 0); } while (0)
; #define PG8_LDA(dst, b, h) do { _Pragma("unroll") for (int m = 0; m < 4; ++m) _Pragma("unroll") for (int k = 0; k < 2; ++k) dst[m][k] = *(const PG8_LAS bf16x8*)(lds + PG8_SA(b, h) + aoff + m * 2048 + k * 1024); } while (0)
; #define PG8_LDB(dst, b, h) do { _Pragma("unroll") for (int n = 0; n < 2; ++n) _Pragma("unroll") for (int k = 0; k < 2; ++k) dst[n][k] = *(const PG8_LAS bf16x8*)(lds + PG8_SB(b, h) + boff + n * 2048 + k * 1024); } while (0)
; #define PG8_MMA(ai, bj, At, Bt) do { __builtin_amdgcn_s_setprio(1); _Pragma("unroll") for (int m = 0; m < 4; ++m) _Pragma("unroll") for (int n = 0; n < 2; ++n) _Pragma("unroll") for (int k = 0; k < 2; ++k) \
;         acc[ai][bj][m][n] = __builtin_amdgcn_mfma_f32_16x16x32_bf16(Bt[n][k], At[m][k], acc[ai][bj][m][n], 0, 0, 0); __builtin_amdgcn_s_setprio(0); } while (0)
; #define PG8_WAIT_V(n) asm volatile("s_waitcnt vmcnt(" #n ")" ::: "memory")
; #define PG8_WAIT_L(n) asm volatile("s_waitcnt lgkmcnt(" #n ")" ::: "memory")
; #define PG8_BAR __builtin_amdgcn_s_barrier()
; #define PG8_SCHED __builtin_amdgcn_sched_barrier(0)
;     ...
;             PG8_LDA(At, 0, 1); PG8_STAGE(PG8_SB(0, 0), b2, voffB); PG8_STAGE(PG8_SB(0, 1), b2 + hstepB, voffB); PG8_STAGE(PG8_SA(0, 0), a2, voffA);
;             PG8_WAIT_V(8); PG8_WAIT_L(0); PG8_BAR; PG8_MMA(1, 0, At, B0); PG8_MMA(1, 1, At, B1); PG8_BAR; PG8_SCHED;
;             PG8_LDB(B0, 1, 0); PG8_LDB(B1, 1, 1); PG8_SCHED; PG8_LDA(At, 1, 0); PG8_STAGE(PG8_SA(0, 1), a2 + hstepA, voffA);
;             PG8_WAIT_V(8); PG8_WAIT_L(0); PG8_BAR; PG8_MMA(0, 0, At, B0); PG8_MMA(0, 1, At, B1); PG8_BAR; PG8_SCHED;
	s_setprio 1
	s_waitcnt lgkmcnt(0)
	v_mfma_f32_16x16x32_bf16 v[60:63], v[64:67], v[152:155], v[60:63]
	v_mfma_f32_16x16x32_bf16 v[56:59], v[80:83], v[152:155], v[56:59]
	v_mfma_f32_16x16x32_bf16 v[44:47], v[64:67], v[168:171], v[44:47]
	v_mfma_f32_16x16x32_bf16 v[40:43], v[80:83], v[168:171], v[40:43]
	v_mfma_f32_16x16x32_bf16 v[28:31], v[64:67], v[176:179], v[28:31]
	v_mfma_f32_16x16x32_bf16 v[24:27], v[80:83], v[176:179], v[24:27]
	v_mfma_f32_16x16x32_bf16 v[12:15], v[64:67], v[184:187], v[12:15]
	v_mfma_f32_16x16x32_bf16 v[8:11], v[80:83], v[184:187], v[8:11]
	v_mfma_f32_16x16x32_bf16 v[60:63], v[68:71], v[164:167], v[60:63]
	v_mfma_f32_16x16x32_bf16 v[56:59], v[92:95], v[164:167], v[56:59]
	v_mfma_f32_16x16x32_bf16 v[44:47], v[68:71], v[172:175], v[44:47]
	v_mfma_f32_16x16x32_bf16 v[40:43], v[92:95], v[172:175], v[40:43]
	v_mfma_f32_16x16x32_bf16 v[28:31], v[68:71], v[180:183], v[28:31]
	v_mfma_f32_16x16x32_bf16 v[24:27], v[92:95], v[180:183], v[24:27]
	v_mfma_f32_16x16x32_bf16 v[12:15], v[68:71], v[188:191], v[12:15]
	v_mfma_f32_16x16x32_bf16 v[8:11], v[92:95], v[188:191], v[8:11]
	s_setprio 0
	s_setprio 1
	v_mfma_f32_16x16x32_bf16 v[52:55], v[104:107], v[152:155], v[52:55]
	v_mfma_f32_16x16x32_bf16 v[48:51], v[120:123], v[152:155], v[48:51]
	v_mfma_f32_16x16x32_bf16 v[36:39], v[104:107], v[168:171], v[36:39]
	v_mfma_f32_16x16x32_bf16 v[32:35], v[120:123], v[168:171], v[32:35]
	v_mfma_f32_16x16x32_bf16 v[20:23], v[104:107], v[176:179], v[20:23]
	v_mfma_f32_16x16x32_bf16 v[16:19], v[120:123], v[176:179], v[16:19]
	v_mfma_f32_16x16x32_bf16 v[4:7], v[104:107], v[184:187], v[4:7]
	v_mfma_f32_16x16x32_bf16 v[0:3], v[120:123], v[184:187], v[0:3]
	v_mfma_f32_16x16x32_bf16 v[52:55], v[108:111], v[164:167], v[52:55]
	v_mfma_f32_16x16x32_bf16 v[48:51], v[132:135], v[164:167], v[48:51]
	v_mfma_f32_16x16x32_bf16 v[36:39], v[108:111], v[172:175], v[36:39]
	v_mfma_f32_16x16x32_bf16 v[32:35], v[132:135], v[172:175], v[32:35]
	v_mfma_f32_16x16x32_bf16 v[20:23], v[108:111], v[180:183], v[20:23]
	v_mfma_f32_16x16x32_bf16 v[16:19], v[132:135], v[180:183], v[16:19]
	v_mfma_f32_16x16x32_bf16 v[4:7], v[108:111], v[188:191], v[4:7]
	v_mfma_f32_16x16x32_bf16 v[0:3], v[132:135], v[188:191], v[0:3]
	s_setprio 0
	s_barrier
	s_add_i32 s48, 0, 0x18000
	s_add_i32 s49, 0, 0x1c000
	v_add_u32_e32 v92, s48, v234
	v_add_u32_e32 v132, s49, v234
	ds_read_b128 v[64:67], v92
	ds_read_b128 v[68:71], v92 offset:1024
	ds_read_b128 v[80:83], v92 offset:2048
	ds_read_b128 v[92:95], v92 offset:3072
	ds_read_b128 v[104:107], v132
	ds_read_b128 v[108:111], v132 offset:1024
	ds_read_b128 v[120:123], v132 offset:2048
	ds_read_b128 v[132:135], v132 offset:3072
	s_add_u32 s34, s34, 0x20000
	s_addc_u32 s35, s35, 0
	s_mov_b32 m0, s68
	v_lshl_add_u64 v[216:217], s[34:35], 0, v[202:203]
	ds_read_b128 v[152:155], v235 offset:32768
	ds_read_b128 v[164:167], v235 offset:33792
	ds_read_b128 v[168:171], v235 offset:34816
	ds_read_b128 v[172:175], v235 offset:35840
	ds_read_b128 v[176:179], v235 offset:36864
	ds_read_b128 v[180:183], v235 offset:37888
	ds_read_b128 v[184:187], v235 offset:38912
	ds_read_b128 v[188:191], v235 offset:39936
	global_load_lds_dwordx4 v[216:217], off
	v_lshl_add_u64 v[216:217], s[34:35], 0, v[200:201]
	s_mov_b32 m0, s69
	s_nop 0
	global_load_lds_dwordx4 v[216:217], off
	s_waitcnt vmcnt(8)
	s_waitcnt lgkmcnt(0)
	s_barrier
	s_setprio 1
	s_waitcnt lgkmcnt(0)
	v_mfma_f32_16x16x32_bf16 v[160:163], v[64:67], v[152:155], v[160:163]
	v_mfma_f32_16x16x32_bf16 v[156:159], v[80:83], v[152:155], v[156:159]
	v_mfma_f32_16x16x32_bf16 v[140:143], v[64:67], v[168:171], v[140:143]
	v_mfma_f32_16x16x32_bf16 v[136:139], v[80:83], v[168:171], v[136:139]
	v_mfma_f32_16x16x32_bf16 v[116:119], v[64:67], v[176:179], v[116:119]
	v_mfma_f32_16x16x32_bf16 v[112:115], v[80:83], v[176:179], v[112:115]
	v_mfma_f32_16x16x32_bf16 v[88:91], v[64:67], v[184:187], v[88:91]
	v_mfma_f32_16x16x32_bf16 v[84:87], v[80:83], v[184:187], v[84:87]
	v_mfma_f32_16x16x32_bf16 v[160:163], v[68:71], v[164:167], v[160:163]
	v_mfma_f32_16x16x32_bf16 v[156:159], v[92:95], v[164:167], v[156:159]
	v_mfma_f32_16x16x32_bf16 v[140:143], v[68:71], v[172:175], v[140:143]
	v_mfma_f32_16x16x32_bf16 v[136:139], v[92:95], v[172:175], v[136:139]
	v_mfma_f32_16x16x32_bf16 v[116:119], v[68:71], v[180:183], v[116:119]
	v_mfma_f32_16x16x32_bf16 v[112:115], v[92:95], v[180:183], v[112:115]
	v_mfma_f32_16x16x32_bf16 v[88:91], v[68:71], v[188:191], v[88:91]
	v_mfma_f32_16x16x32_bf16 v[84:87], v[92:95], v[188:191], v[84:87]
	s_setprio 0
	s_setprio 1
	v_mfma_f32_16x16x32_bf16 v[148:151], v[104:107], v[152:155], v[148:151]
	v_mfma_f32_16x16x32_bf16 v[144:147], v[120:123], v[152:155], v[144:147]
	v_mfma_f32_16x16x32_bf16 v[128:131], v[104:107], v[168:171], v[128:131]
	v_mfma_f32_16x16x32_bf16 v[124:127], v[120:123], v[168:171], v[124:127]
	v_mfma_f32_16x16x32_bf16 v[100:103], v[104:107], v[176:179], v[100:103]
	v_mfma_f32_16x16x32_bf16 v[96:99], v[120:123], v[176:179], v[96:99]
	v_mfma_f32_16x16x32_bf16 v[76:79], v[104:107], v[184:187], v[76:79]
	v_mfma_f32_16x16x32_bf16 v[72:75], v[120:123], v[184:187], v[72:75]
	v_mfma_f32_16x16x32_bf16 v[148:151], v[108:111], v[164:167], v[148:151]
	v_mfma_f32_16x16x32_bf16 v[144:147], v[132:135], v[164:167], v[144:147]
	v_mfma_f32_16x16x32_bf16 v[128:131], v[108:111], v[172:175], v[128:131]
	v_mfma_f32_16x16x32_bf16 v[124:127], v[132:135], v[172:175], v[124:127]
	v_mfma_f32_16x16x32_bf16 v[100:103], v[108:111], v[180:183], v[100:103]
	v_mfma_f32_16x16x32_bf16 v[96:99], v[132:135], v[180:183], v[96:99]
	v_mfma_f32_16x16x32_bf16 v[76:79], v[108:111], v[188:191], v[76:79]
	v_mfma_f32_16x16x32_bf16 v[72:75], v[132:135], v[188:191], v[72:75]
	s_setprio 0
	s_barrier
; #define PG8_STAGE(bufoff, gbase, voff) do { _Pragma("unroll") for (int _i = 0; _i < 2; ++_i) \
;         __builtin_amdgcn_global_load_lds((const unsigned*)((const char*)(gbase) + (voff)[_i]), (PG8_LAS unsigned*)(lds + (bufoff) + ldsw + _i * 8192), 16, 0, 0); } while (0)
; #define PG8_LDA(dst, b, h) do { _Pragma("unroll") for (int m = 0; m < 4; ++m) _Pragma("unroll") for (int k = 0; k < 2; ++k) dst[m][k] = *(const PG8_LAS bf16x8*)(lds + PG8_SA(b, h) + aoff + m * 2048 + k * 1024); } while (0)
; #define PG8_MMA(ai, bj, At, Bt) do { __builtin_amdgcn_s_setprio(1); _Pragma("unroll") for (int m = 0; m < 4; ++m) _Pragma("unroll") for (int n = 0; n < 2; ++n) _Pragma("unroll") for (int k = 0; k < 2; ++k) \
;         acc[ai][bj][m][n] = __builtin_amdgcn_mfma_f32_16x16x32_bf16(Bt[n][k], At[m][k], acc[ai][bj][m][n], 0, 0, 0); __builtin_amdgcn_s_setprio(0); } while (0)
; #define PG8_WAIT_V(n) asm volatile("s_waitcnt vmcnt(" #n ")" ::: "memory")
; #define PG8_WAIT_L(n) asm volatile("s_waitcnt lgkmcnt(" #n ")" ::: "memory")
; #define PG8_BAR __builtin_amdgcn_s_barrier()
; #define PG8_SCHED __builtin_amdgcn_sched_barrier(0)
;     ...
;             PG8_LDA(At, 1, 1); PG8_STAGE(PG8_SB(1, 0), b3, voffB); PG8_STAGE(PG8_SB(1, 1), b3 + hstepB, voffB); PG8_STAGE(PG8_SA(1, 0), a3, voffA);
;             PG8_WAIT_V(8); PG8_WAIT_L(0); PG8_BAR; PG8_MMA(1, 0, At, B0); PG8_MMA(1, 1, At, B1); PG8_BAR; PG8_SCHED;
;     ...
;         if constexpr (ALIGN_EPI) { if (wr == 0) PG8_BAR; }
	s_add_i32 s34, s48, s65
	s_mov_b32 m0, s34
	ds_read_b128 v[152:155], v235 offset:49152
	ds_read_b128 v[164:167], v235 offset:50176
	ds_read_b128 v[168:171], v235 offset:51200
	ds_read_b128 v[172:175], v235 offset:52224
	ds_read_b128 v[176:179], v235 offset:53248
	ds_read_b128 v[180:183], v235 offset:54272
	ds_read_b128 v[184:187], v235 offset:55296
	ds_read_b128 v[188:191], v235 offset:56320
	v_lshl_add_u64 v[208:209], v[208:209], 0, s[22:23]
	global_load_lds_dwordx4 v[208:209], off
	s_add_i32 m0, s34, 0x2000
	s_add_u32 s28, s28, 0x20080
	v_lshl_add_u64 v[208:209], v[210:211], 0, s[22:23]
	s_addc_u32 s29, s29, 0
	s_add_i32 s34, s49, s65
	global_load_lds_dwordx4 v[208:209], off
	v_lshl_add_u64 v[208:209], s[28:29], 0, v[192:193]
	s_mov_b32 m0, s34
	s_nop 0
	global_load_lds_dwordx4 v[208:209], off
	v_lshl_add_u64 v[208:209], s[28:29], 0, v[198:199]
	s_add_i32 m0, s34, 0x2000
	s_nop 0
	global_load_lds_dwordx4 v[208:209], off
	v_lshl_add_u64 v[208:209], v[212:213], 0, s[22:23]
	s_mov_b32 m0, s72
	s_nop 0
	global_load_lds_dwordx4 v[208:209], off
	v_lshl_add_u64 v[208:209], v[214:215], 0, s[22:23]
	s_mov_b32 m0, s73
	s_nop 0
	global_load_lds_dwordx4 v[208:209], off
	s_waitcnt vmcnt(8)
	s_waitcnt lgkmcnt(0)
	s_barrier
	s_setprio 1
	s_waitcnt lgkmcnt(0)
	v_mfma_f32_16x16x32_bf16 v[60:63], v[64:67], v[152:155], v[60:63]
	v_mfma_f32_16x16x32_bf16 v[56:59], v[80:83], v[152:155], v[56:59]
	v_mfma_f32_16x16x32_bf16 v[44:47], v[64:67], v[168:171], v[44:47]
	v_mfma_f32_16x16x32_bf16 v[40:43], v[80:83], v[168:171], v[40:43]
	v_mfma_f32_16x16x32_bf16 v[28:31], v[64:67], v[176:179], v[28:31]
	v_mfma_f32_16x16x32_bf16 v[24:27], v[80:83], v[176:179], v[24:27]
	v_mfma_f32_16x16x32_bf16 v[12:15], v[64:67], v[184:187], v[12:15]
	v_mfma_f32_16x16x32_bf16 v[8:11], v[80:83], v[184:187], v[8:11]
	v_mfma_f32_16x16x32_bf16 v[60:63], v[68:71], v[164:167], v[60:63]
	v_mfma_f32_16x16x32_bf16 v[56:59], v[92:95], v[164:167], v[56:59]
	v_mfma_f32_16x16x32_bf16 v[44:47], v[68:71], v[172:175], v[44:47]
	v_mfma_f32_16x16x32_bf16 v[40:43], v[92:95], v[172:175], v[40:43]
	v_mfma_f32_16x16x32_bf16 v[28:31], v[68:71], v[180:183], v[28:31]
	v_mfma_f32_16x16x32_bf16 v[24:27], v[92:95], v[180:183], v[24:27]
	v_mfma_f32_16x16x32_bf16 v[12:15], v[68:71], v[188:191], v[12:15]
	v_mfma_f32_16x16x32_bf16 v[8:11], v[92:95], v[188:191], v[8:11]
	s_setprio 0
	s_setprio 1
	v_mfma_f32_16x16x32_bf16 v[52:55], v[104:107], v[152:155], v[52:55]
	v_mfma_f32_16x16x32_bf16 v[48:51], v[120:123], v[152:155], v[48:51]
	v_mfma_f32_16x16x32_bf16 v[36:39], v[104:107], v[168:171], v[36:39]
	v_mfma_f32_16x16x32_bf16 v[32:35], v[120:123], v[168:171], v[32:35]
	v_mfma_f32_16x16x32_bf16 v[20:23], v[104:107], v[176:179], v[20:23]
	v_mfma_f32_16x16x32_bf16 v[16:19], v[120:123], v[176:179], v[16:19]
	v_mfma_f32_16x16x32_bf16 v[4:7], v[104:107], v[184:187], v[4:7]
	v_mfma_f32_16x16x32_bf16 v[0:3], v[120:123], v[184:187], v[0:3]
	v_mfma_f32_16x16x32_bf16 v[52:55], v[108:111], v[164:167], v[52:55]
	v_mfma_f32_16x16x32_bf16 v[48:51], v[132:135], v[164:167], v[48:51]
	v_mfma_f32_16x16x32_bf16 v[36:39], v[108:111], v[172:175], v[36:39]
	v_mfma_f32_16x16x32_bf16 v[32:35], v[132:135], v[172:175], v[32:35]
	v_mfma_f32_16x16x32_bf16 v[20:23], v[108:111], v[180:183], v[20:23]
	v_mfma_f32_16x16x32_bf16 v[16:19], v[132:135], v[180:183], v[16:19]
	v_mfma_f32_16x16x32_bf16 v[4:7], v[108:111], v[188:191], v[4:7]
	v_mfma_f32_16x16x32_bf16 v[0:3], v[132:135], v[188:191], v[0:3]
	s_setprio 0
	s_barrier
	s_add_i32 s81, s81, 2
	s_add_u32 s6, s6, 0x100
	s_addc_u32 s7, s7, 0
	s_add_u32 s79, s79, 0x100
	s_addc_u32 s80, s80, 0
	s_cmp_gt_u32 s81, 5
	s_cbranch_scc0 .LBB0_963
	s_and_b64 vcc, exec, s[38:39]
	s_cbranch_vccz .LBB0_966
	s_barrier

; #define PG8_STAGE(bufoff, gbase, voff) do { _Pragma("unroll") for (int _i = 0; _i < 2; ++_i) \
;         __builtin_amdgcn_global_load_lds((const unsigned*)((const char*)(gbase) + (voff)[_i]), (PG8_LAS unsigned*)(lds + (bufoff) + ldsw + _i * 8192), 16, 0, 0); } while (0)
; #define PG8_LDA(dst, b, h) do { _Pragma("unroll") for (int m = 0; m < 4; ++m) _Pragma("unroll") for (int k = 0; k < 2; ++k) dst[m][k] = *(const PG8_LAS bf16x8*)(lds + PG8_SA(b, h) + aoff + m * 2048 + k * 1024); } while (0)
; #define PG8_LDB(dst, b, h) do { _Pragma("unroll") for (int n = 0; n < 2; ++n) _Pragma("unroll") for (int k = 0; k < 2; ++k) dst[n][k] = *(const PG8_LAS bf16x8*)(lds + PG8_SB(b, h) + boff + n * 2048 + k * 1024); } while (0)
; #define PG8_MMA(ai, bj, At, Bt) do { __builtin_amdgcn_s_setprio(1); _Pragma("unroll") for (int m = 0; m < 4; ++m) _Pragma("unroll") for (int n = 0; n < 2; ++n) _Pragma("unroll") for (int k = 0; k < 2; ++k) \
;         acc[ai][bj][m][n] = __builtin_amdgcn_mfma_f32_16x16x32_bf16(Bt[n][k], At[m][k], acc[ai][bj][m][n], 0, 0, 0); __builtin_amdgcn_s_setprio(0); } while (0)
; #define PG8_WAIT_V(n) asm volatile("s_waitcnt vmcnt(" #n ")" ::: "memory")
; #define PG8_WAIT_L(n) asm volatile("s_waitcnt lgkmcnt(" #n ")" ::: "memory")
; #define PG8_BAR __builtin_amdgcn_s_barrier()
; #define PG8_SCHED __builtin_amdgcn_sched_barrier(0)
;     ...
;             const char* a1 = cA + (size_t)(t + 1) * kstep;
;             const char* a2 = last ? nA : cA + (size_t)(t + 2) * kstep; const char* b2 = last ? nB : cB + (size_t)(t + 2) * kstep;
;             const char* a3 = a2 + kstep; const char* b3 = b2 + kstep;
;             if (last && has_next) S.a_ready(nxt);
;             if constexpr (SP2) {
;             PG8_LDB(B0, 0, 0); PG8_LDB(B1, 0, 1); PG8_SCHED; PG8_LDA(At, 0, 0); PG8_STAGE(PG8_SA(1, 1), a1 + hstepA, voffA);
;             PG8_WAIT_V(8); PG8_WAIT_L(0); PG8_BAR; PG8_MMA(0, 0, At, B0); PG8_MMA(0, 1, At, B1); PG8_BAR; PG8_SCHED;
;             PG8_LDA(At, 0, 1); PG8_STAGE(PG8_SB(0, 0), b2, voffB); PG8_STAGE(PG8_SB(0, 1), b2 + hstepB, voffB); PG8_STAGE(PG8_SA(0, 0), a2, voffA);
.LBB0_1083:
	s_add_u32 s6, s28, 0x100
	s_addc_u32 s7, s29, 0
	s_add_i32 s48, 0, 0x10000
	s_cmp_eq_u32 s76, 12
	s_cselect_b32 s41, s53, s7
	s_cselect_b32 s40, s52, s6
	s_cselect_b32 s35, s51, s75
	s_cselect_b32 s34, s73, s74
	s_add_i32 s49, 0, 0x14000
	v_add_u32_e32 v92, s48, v234
	v_add_u32_e32 v132, s49, v234
	ds_read_b128 v[64:67], v92
	ds_read_b128 v[68:71], v92 offset:1024
	ds_read_b128 v[80:83], v92 offset:2048
	ds_read_b128 v[92:95], v92 offset:3072
	ds_read_b128 v[104:107], v132
	ds_read_b128 v[108:111], v132 offset:1024
	ds_read_b128 v[120:123], v132 offset:2048
	ds_read_b128 v[132:135], v132 offset:3072
	v_lshl_add_u64 v[208:209], s[28:29], 0, v[204:205]
	s_add_i32 m0, s61, 0xc000
	ds_read_b128 v[152:155], v235
	ds_read_b128 v[164:167], v235 offset:1024
	ds_read_b128 v[168:171], v235 offset:2048
	ds_read_b128 v[172:175], v235 offset:3072
	ds_read_b128 v[176:179], v235 offset:4096
	ds_read_b128 v[180:183], v235 offset:5120
	ds_read_b128 v[184:187], v235 offset:6144
	ds_read_b128 v[188:191], v235 offset:7168
	global_load_lds_dwordx4 v[208:209], off
	v_lshl_add_u64 v[208:209], s[28:29], 0, v[206:207]
	s_add_i32 m0, s61, 0xe000
	s_nop 0
	global_load_lds_dwordx4 v[208:209], off
	s_waitcnt vmcnt(8)
	s_waitcnt lgkmcnt(0)
	s_barrier
	s_setprio 1
	s_waitcnt lgkmcnt(0)
	v_mfma_f32_16x16x32_bf16 v[160:163], v[64:67], v[152:155], v[160:163]
	v_mfma_f32_16x16x32_bf16 v[156:159], v[80:83], v[152:155], v[156:159]
	v_mfma_f32_16x16x32_bf16 v[140:143], v[64:67], v[168:171], v[140:143]
	v_mfma_f32_16x16x32_bf16 v[136:139], v[80:83], v[168:171], v[136:139]
	v_mfma_f32_16x16x32_bf16 v[116:119], v[64:67], v[176:179], v[116:119]
	v_mfma_f32_16x16x32_bf16 v[112:115], v[80:83], v[176:179], v[112:115]
	v_mfma_f32_16x16x32_bf16 v[88:91], v[64:67], v[184:187], v[88:91]
	v_mfma_f32_16x16x32_bf16 v[84:87], v[80:83], v[184:187], v[84:87]
	v_mfma_f32_16x16x32_bf16 v[160:163], v[68:71], v[164:167], v[160:163]
	v_mfma_f32_16x16x32_bf16 v[156:159], v[92:95], v[164:167], v[156:159]
	v_mfma_f32_16x16x32_bf16 v[140:143], v[68:71], v[172:175], v[140:143]
	v_mfma_f32_16x16x32_bf16 v[136:139], v[92:95], v[172:175], v[136:139]
	v_mfma_f32_16x16x32_bf16 v[116:119], v[68:71], v[180:183], v[116:119]
	v_mfma_f32_16x16x32_bf16 v[112:115], v[92:95], v[180:183], v[112:115]
	v_mfma_f32_16x16x32_bf16 v[88:91], v[68:71], v[188:191], v[88:91]
	v_mfma_f32_16x16x32_bf16 v[84:87], v[92:95], v[188:191], v[84:87]
	s_setprio 0
	s_setprio 1
	v_mfma_f32_16x16x32_bf16 v[148:151], v[104:107], v[152:155], v[148:151]
	v_mfma_f32_16x16x32_bf16 v[144:147], v[120:123], v[152:155], v[144:147]
	v_mfma_f32_16x16x32_bf16 v[128:131], v[104:107], v[168:171], v[128:131]
	v_mfma_f32_16x16x32_bf16 v[124:127], v[120:123], v[168:171], v[124:127]
	v_mfma_f32_16x16x32_bf16 v[100:103], v[104:107], v[176:179], v[100:103]
	v_mfma_f32_16x16x32_bf16 v[96:99], v[120:123], v[176:179], v[96:99]
	v_mfma_f32_16x16x32_bf16 v[76:79], v[104:107], v[184:187], v[76:79]
	v_mfma_f32_16x16x32_bf16 v[72:75], v[120:123], v[184:187], v[72:75]
	v_mfma_f32_16x16x32_bf16 v[148:151], v[108:111], v[164:167], v[148:151]
	v_mfma_f32_16x16x32_bf16 v[144:147], v[132:135], v[164:167], v[144:147]
	v_mfma_f32_16x16x32_bf16 v[128:131], v[108:111], v[172:175], v[128:131]
	v_mfma_f32_16x16x32_bf16 v[124:127], v[132:135], v[172:175], v[124:127]
	v_mfma_f32_16x16x32_bf16 v[100:103], v[108:111], v[180:183], v[100:103]
	v_mfma_f32_16x16x32_bf16 v[96:99], v[132:135], v[180:183], v[96:99]
	v_mfma_f32_16x16x32_bf16 v[76:79], v[108:111], v[188:191], v[76:79]
	v_mfma_f32_16x16x32_bf16 v[72:75], v[132:135], v[188:191], v[72:75]
	s_setprio 0
	s_barrier
	s_add_i32 s28, s48, s58
	s_mov_b32 m0, s28
	ds_read_b128 v[152:155], v235 offset:16384
	ds_read_b128 v[164:167], v235 offset:17408
	ds_read_b128 v[168:171], v235 offset:18432
	ds_read_b128 v[172:175], v235 offset:19456
	ds_read_b128 v[176:179], v235 offset:20480
	ds_read_b128 v[180:183], v235 offset:21504
	ds_read_b128 v[184:187], v235 offset:22528
	ds_read_b128 v[188:191], v235 offset:23552
	v_lshl_add_u64 v[208:209], s[34:35], 0, v[192:193]
	global_load_lds_dwordx4 v[208:209], off
	s_add_i32 m0, s28, 0x2000
	s_add_u32 s28, s34, 0x40000
	v_lshl_add_u64 v[210:211], s[34:35], 0, v[198:199]
	s_addc_u32 s29, s35, 0
	s_add_i32 s48, s49, s58
	global_load_lds_dwordx4 v[210:211], off
	v_lshl_add_u64 v[212:213], s[28:29], 0, v[192:193]
	s_mov_b32 m0, s48
	v_lshl_add_u64 v[214:215], s[40:41], 0, v[200:201]
	global_load_lds_dwordx4 v[212:213], off
	v_lshl_add_u64 v[212:213], s[28:29], 0, v[198:199]
	s_add_i32 m0, s48, 0x2000
	s_nop 0
	global_load_lds_dwordx4 v[212:213], off
	v_lshl_add_u64 v[212:213], s[40:41], 0, v[202:203]
	s_mov_b32 m0, s61
	s_nop 0
	global_load_lds_dwordx4 v[212:213], off
	s_mov_b32 m0, s62
	s_nop 0
	global_load_lds_dwordx4 v[214:215], off
	s_waitcnt vmcnt(8)
	s_waitcnt lgkmcnt(0)
	s_barrier
; #define PG8_STAGE(bufoff, gbase, voff) do { _Pragma("unroll") for (int _i = 0; _i < 2; ++_i) \
;         __builtin_amdgcn_global_load_lds((const unsigned*)((const char*)(gbase) + (voff)[_i]), (PG8_LAS unsigned*)(lds + (bufoff) + ldsw + _i * 8192), 16, 0, 0); } while (0)
; #define PG8_LDA(dst, b, h) do { _Pragma("unroll") for (int m = 0; m < 4; ++m) _Pragma("unroll") for (int k = 0; k < 2; ++k) dst[m][k] = *(const PG8_LAS bf16x8*)(lds + PG8_SA(b, h) + aoff + m * 2048 + k * 1024); } while (0)
; #define PG8_LDB(dst, b, h) do { _Pragma("unroll") for (int n = 0; n < 2; ++n) _Pragma("unroll") for (int k = 0; k < 2; ++k) dst[n][k] = *(const PG8_LAS bf16x8*)(lds + PG8_SB(b, h) + boff + n * 2048 + k * 1024); } while (0)
; #define PG8_MMA(ai, bj, At, Bt) do { __builtin_amdgcn_s_setprio(1); _Pragma("unroll") for (int m = 0; m < 4; ++m) _Pragma("unroll") for (int n = 0; n < 2; ++n) _Pragma("unroll") for (int k = 0; k < 2; ++k) \
;         acc[ai][bj][m][n] = __builtin_amdgcn_mfma_f32_16x16x32_bf16(Bt[n][k], At[m][k], acc[ai][bj][m][n], 0, 0, 0); __builtin_amdgcn_s_setprio(0); } while (0)
; #define PG8_WAIT_V(n) asm volatile("s_waitcnt vmcnt(" #n ")" ::: "memory")
; #define PG8_WAIT_L(n) asm volatile("s_waitcnt lgkmcnt(" #n ")" ::: "memory")
; #define PG8_BAR __builtin_amdgcn_s_barrier()
; #define PG8_SCHED __builtin_amdgcn_sched_barrier(0)
;     ...
;             PG8_LDA(At, 0, 1); PG8_STAGE(PG8_SB(0, 0), b2, voffB); PG8_STAGE(PG8_SB(0, 1), b2 + hstepB, voffB); PG8_STAGE(PG8_SA(0, 0), a2, voffA);
;             PG8_WAIT_V(8); PG8_WAIT_L(0); PG8_BAR; PG8_MMA(1, 0, At, B0); PG8_MMA(1, 1, At, B1); PG8_BAR; PG8_SCHED;
;             PG8_LDB(B0, 1, 0); PG8_LDB(B1, 1, 1); PG8_SCHED; PG8_LDA(At, 1, 0); PG8_STAGE(PG8_SA(0, 1), a2 + hstepA, voffA);
;             PG8_WAIT_V(8); PG8_WAIT_L(0); PG8_BAR; PG8_MMA(0, 0, At, B0); PG8_MMA(0, 1, At, B1); PG8_BAR; PG8_SCHED;
	s_setprio 1
	s_waitcnt lgkmcnt(0)
	v_mfma_f32_16x16x32_bf16 v[60:63], v[64:67], v[152:155], v[60:63]
	v_mfma_f32_16x16x32_bf16 v[56:59], v[80:83], v[152:155], v[56:59]
	v_mfma_f32_16x16x32_bf16 v[44:47], v[64:67], v[168:171], v[44:47]
	v_mfma_f32_16x16x32_bf16 v[40:43], v[80:83], v[168:171], v[40:43]
	v_mfma_f32_16x16x32_bf16 v[28:31], v[64:67], v[176:179], v[28:31]
	v_mfma_f32_16x16x32_bf16 v[24:27], v[80:83], v[176:179], v[24:27]
	v_mfma_f32_16x16x32_bf16 v[12:15], v[64:67], v[184:187], v[12:15]
	v_mfma_f32_16x16x32_bf16 v[8:11], v[80:83], v[184:187], v[8:11]
	v_mfma_f32_16x16x32_bf16 v[60:63], v[68:71], v[164:167], v[60:63]
	v_mfma_f32_16x16x32_bf16 v[56:59], v[92:95], v[164:167], v[56:59]
	v_mfma_f32_16x16x32_bf16 v[44:47], v[68:71], v[172:175], v[44:47]
	v_mfma_f32_16x16x32_bf16 v[40:43], v[92:95], v[172:175], v[40:43]
	v_mfma_f32_16x16x32_bf16 v[28:31], v[68:71], v[180:183], v[28:31]
	v_mfma_f32_16x16x32_bf16 v[24:27], v[92:95], v[180:183], v[24:27]
	v_mfma_f32_16x16x32_bf16 v[12:15], v[68:71], v[188:191], v[12:15]
	v_mfma_f32_16x16x32_bf16 v[8:11], v[92:95], v[188:191], v[8:11]
	s_setprio 0
	s_setprio 1
	v_mfma_f32_16x16x32_bf16 v[52:55], v[104:107], v[152:155], v[52:55]
	v_mfma_f32_16x16x32_bf16 v[48:51], v[120:123], v[152:155], v[48:51]
	v_mfma_f32_16x16x32_bf16 v[36:39], v[104:107], v[168:171], v[36:39]
	v_mfma_f32_16x16x32_bf16 v[32:35], v[120:123], v[168:171], v[32:35]
	v_mfma_f32_16x16x32_bf16 v[20:23], v[104:107], v[176:179], v[20:23]
	v_mfma_f32_16x16x32_bf16 v[16:19], v[120:123], v[176:179], v[16:19]
	v_mfma_f32_16x16x32_bf16 v[4:7], v[104:107], v[184:187], v[4:7]
	v_mfma_f32_16x16x32_bf16 v[0:3], v[120:123], v[184:187], v[0:3]
	v_mfma_f32_16x16x32_bf16 v[52:55], v[108:111], v[164:167], v[52:55]
	v_mfma_f32_16x16x32_bf16 v[48:51], v[132:135], v[164:167], v[48:51]
	v_mfma_f32_16x16x32_bf16 v[36:39], v[108:111], v[172:175], v[36:39]
	v_mfma_f32_16x16x32_bf16 v[32:35], v[132:135], v[172:175], v[32:35]
	v_mfma_f32_16x16x32_bf16 v[20:23], v[108:111], v[180:183], v[20:23]
	v_mfma_f32_16x16x32_bf16 v[16:19], v[132:135], v[180:183], v[16:19]
	v_mfma_f32_16x16x32_bf16 v[4:7], v[108:111], v[188:191], v[4:7]
	v_mfma_f32_16x16x32_bf16 v[0:3], v[132:135], v[188:191], v[0:3]
	s_setprio 0
	s_barrier
	s_add_i32 s48, 0, 0x18000
	s_add_i32 s49, 0, 0x1c000
	v_add_u32_e32 v92, s48, v234
	v_add_u32_e32 v132, s49, v234
	ds_read_b128 v[64:67], v92
	ds_read_b128 v[68:71], v92 offset:1024
	ds_read_b128 v[80:83], v92 offset:2048
	ds_read_b128 v[92:95], v92 offset:3072
	ds_read_b128 v[104:107], v132
	ds_read_b128 v[108:111], v132 offset:1024
	ds_read_b128 v[120:123], v132 offset:2048
	ds_read_b128 v[132:135], v132 offset:3072
	s_add_u32 s28, s40, 0x60000
	s_addc_u32 s29, s41, 0
	s_mov_b32 m0, s63
	v_lshl_add_u64 v[216:217], s[28:29], 0, v[202:203]
	ds_read_b128 v[152:155], v235 offset:32768
	ds_read_b128 v[164:167], v235 offset:33792
	ds_read_b128 v[168:171], v235 offset:34816
	ds_read_b128 v[172:175], v235 offset:35840
	ds_read_b128 v[176:179], v235 offset:36864
	ds_read_b128 v[180:183], v235 offset:37888
	ds_read_b128 v[184:187], v235 offset:38912
	ds_read_b128 v[188:191], v235 offset:39936
	global_load_lds_dwordx4 v[216:217], off
	v_lshl_add_u64 v[216:217], s[28:29], 0, v[200:201]
	s_mov_b32 m0, s64
	s_nop 0
	global_load_lds_dwordx4 v[216:217], off
	s_waitcnt vmcnt(8)
	s_waitcnt lgkmcnt(0)
	s_barrier
	s_setprio 1
	s_waitcnt lgkmcnt(0)
	v_mfma_f32_16x16x32_bf16 v[160:163], v[64:67], v[152:155], v[160:163]
	v_mfma_f32_16x16x32_bf16 v[156:159], v[80:83], v[152:155], v[156:159]
	v_mfma_f32_16x16x32_bf16 v[140:143], v[64:67], v[168:171], v[140:143]
	v_mfma_f32_16x16x32_bf16 v[136:139], v[80:83], v[168:171], v[136:139]
	v_mfma_f32_16x16x32_bf16 v[116:119], v[64:67], v[176:179], v[116:119]
	v_mfma_f32_16x16x32_bf16 v[112:115], v[80:83], v[176:179], v[112:115]
	v_mfma_f32_16x16x32_bf16 v[88:91], v[64:67], v[184:187], v[88:91]
	v_mfma_f32_16x16x32_bf16 v[84:87], v[80:83], v[184:187], v[84:87]
	v_mfma_f32_16x16x32_bf16 v[160:163], v[68:71], v[164:167], v[160:163]
	v_mfma_f32_16x16x32_bf16 v[156:159], v[92:95], v[164:167], v[156:159]
	v_mfma_f32_16x16x32_bf16 v[140:143], v[68:71], v[172:175], v[140:143]
	v_mfma_f32_16x16x32_bf16 v[136:139], v[92:95], v[172:175], v[136:139]
	v_mfma_f32_16x16x32_bf16 v[116:119], v[68:71], v[180:183], v[116:119]
	v_mfma_f32_16x16x32_bf16 v[112:115], v[92:95], v[180:183], v[112:115]
	v_mfma_f32_16x16x32_bf16 v[88:91], v[68:71], v[188:191], v[88:91]
	v_mfma_f32_16x16x32_bf16 v[84:87], v[92:95], v[188:191], v[84:87]
	s_setprio 0
	s_setprio 1
	v_mfma_f32_16x16x32_bf16 v[148:151], v[104:107], v[152:155], v[148:151]
	v_mfma_f32_16x16x32_bf16 v[144:147], v[120:123], v[152:155], v[144:147]
	v_mfma_f32_16x16x32_bf16 v[128:131], v[104:107], v[168:171], v[128:131]
	v_mfma_f32_16x16x32_bf16 v[124:127], v[120:123], v[168:171], v[124:127]
	v_mfma_f32_16x16x32_bf16 v[100:103], v[104:107], v[176:179], v[100:103]
	v_mfma_f32_16x16x32_bf16 v[96:99], v[120:123], v[176:179], v[96:99]
	v_mfma_f32_16x16x32_bf16 v[76:79], v[104:107], v[184:187], v[76:79]
	v_mfma_f32_16x16x32_bf16 v[72:75], v[120:123], v[184:187], v[72:75]
	v_mfma_f32_16x16x32_bf16 v[148:151], v[108:111], v[164:167], v[148:151]
	v_mfma_f32_16x16x32_bf16 v[144:147], v[132:135], v[164:167], v[144:147]
	v_mfma_f32_16x16x32_bf16 v[128:131], v[108:111], v[172:175], v[128:131]
	v_mfma_f32_16x16x32_bf16 v[124:127], v[132:135], v[172:175], v[124:127]
	v_mfma_f32_16x16x32_bf16 v[100:103], v[108:111], v[180:183], v[100:103]
	v_mfma_f32_16x16x32_bf16 v[96:99], v[132:135], v[180:183], v[96:99]
	v_mfma_f32_16x16x32_bf16 v[76:79], v[108:111], v[188:191], v[76:79]
	v_mfma_f32_16x16x32_bf16 v[72:75], v[132:135], v[188:191], v[72:75]
	s_setprio 0
	s_barrier
; #define PG8_STAGE(bufoff, gbase, voff) do { _Pragma("unroll") for (int _i = 0; _i < 2; ++_i) \
;         __builtin_amdgcn_global_load_lds((const unsigned*)((const char*)(gbase) + (voff)[_i]), (PG8_LAS unsigned*)(lds + (bufoff) + ldsw + _i * 8192), 16, 0, 0); } while (0)
; #define PG8_LDA(dst, b, h) do { _Pragma("unroll") for (int m = 0; m < 4; ++m) _Pragma("unroll") for (int k = 0; k < 2; ++k) dst[m][k] = *(const PG8_LAS bf16x8*)(lds + PG8_SA(b, h) + aoff + m * 2048 + k * 1024); } while (0)
; #define PG8_MMA(ai, bj, At, Bt) do { __builtin_amdgcn_s_setprio(1); _Pragma("unroll") for (int m = 0; m < 4; ++m) _Pragma("unroll") for (int n = 0; n < 2; ++n) _Pragma("unroll") for (int k = 0; k < 2; ++k) \
;         acc[ai][bj][m][n] = __builtin_amdgcn_mfma_f32_16x16x32_bf16(Bt[n][k], At[m][k], acc[ai][bj][m][n], 0, 0, 0); __builtin_amdgcn_s_setprio(0); } while (0)
; #define PG8_WAIT_V(n) asm volatile("s_waitcnt vmcnt(" #n ")" ::: "memory")
; #define PG8_WAIT_L(n) asm volatile("s_waitcnt lgkmcnt(" #n ")" ::: "memory")
; #define PG8_BAR __builtin_amdgcn_s_barrier()
; #define PG8_SCHED __builtin_amdgcn_sched_barrier(0)
;     ...
;             PG8_LDA(At, 1, 1); PG8_STAGE(PG8_SB(1, 0), b3, voffB); PG8_STAGE(PG8_SB(1, 1), b3 + hstepB, voffB); PG8_STAGE(PG8_SA(1, 0), a3, voffA);
;             PG8_WAIT_V(8); PG8_WAIT_L(0); PG8_BAR; PG8_MMA(1, 0, At, B0); PG8_MMA(1, 1, At, B1); PG8_BAR; PG8_SCHED;
;     ...
;         if constexpr (ALIGN_EPI) { if (wr == 0) PG8_BAR; }
	s_add_i32 s28, s48, s58
	s_mov_b32 m0, s28
	ds_read_b128 v[152:155], v235 offset:49152
	ds_read_b128 v[164:167], v235 offset:50176
	ds_read_b128 v[168:171], v235 offset:51200
	ds_read_b128 v[172:175], v235 offset:52224
	ds_read_b128 v[176:179], v235 offset:53248
	ds_read_b128 v[180:183], v235 offset:54272
	ds_read_b128 v[184:187], v235 offset:55296
	ds_read_b128 v[188:191], v235 offset:56320
	v_lshl_add_u64 v[208:209], v[208:209], 0, s[22:23]
	global_load_lds_dwordx4 v[208:209], off
	s_add_i32 m0, s28, 0x2000
	s_add_u32 s28, s34, 0x40080
	v_lshl_add_u64 v[208:209], v[210:211], 0, s[22:23]
	s_addc_u32 s29, s35, 0
	s_add_i32 s34, s49, s58
	global_load_lds_dwordx4 v[208:209], off
	v_lshl_add_u64 v[208:209], s[28:29], 0, v[192:193]
	s_mov_b32 m0, s34
	s_nop 0
	global_load_lds_dwordx4 v[208:209], off
	v_lshl_add_u64 v[208:209], s[28:29], 0, v[198:199]
	s_add_i32 m0, s34, 0x2000
	s_nop 0
	global_load_lds_dwordx4 v[208:209], off
	v_lshl_add_u64 v[208:209], v[212:213], 0, s[22:23]
	s_mov_b32 m0, s67
	s_nop 0
	global_load_lds_dwordx4 v[208:209], off
	v_lshl_add_u64 v[208:209], v[214:215], 0, s[22:23]
	s_mov_b32 m0, s68
	s_nop 0
	global_load_lds_dwordx4 v[208:209], off
	s_waitcnt vmcnt(8)
	s_waitcnt lgkmcnt(0)
	s_barrier
	s_setprio 1
	s_waitcnt lgkmcnt(0)
	v_mfma_f32_16x16x32_bf16 v[60:63], v[64:67], v[152:155], v[60:63]
	v_mfma_f32_16x16x32_bf16 v[56:59], v[80:83], v[152:155], v[56:59]
	v_mfma_f32_16x16x32_bf16 v[44:47], v[64:67], v[168:171], v[44:47]
	v_mfma_f32_16x16x32_bf16 v[40:43], v[80:83], v[168:171], v[40:43]
	v_mfma_f32_16x16x32_bf16 v[28:31], v[64:67], v[176:179], v[28:31]
	v_mfma_f32_16x16x32_bf16 v[24:27], v[80:83], v[176:179], v[24:27]
	v_mfma_f32_16x16x32_bf16 v[12:15], v[64:67], v[184:187], v[12:15]
	v_mfma_f32_16x16x32_bf16 v[8:11], v[80:83], v[184:187], v[8:11]
	v_mfma_f32_16x16x32_bf16 v[60:63], v[68:71], v[164:167], v[60:63]
	v_mfma_f32_16x16x32_bf16 v[56:59], v[92:95], v[164:167], v[56:59]
	v_mfma_f32_16x16x32_bf16 v[44:47], v[68:71], v[172:175], v[44:47]
	v_mfma_f32_16x16x32_bf16 v[40:43], v[92:95], v[172:175], v[40:43]
	v_mfma_f32_16x16x32_bf16 v[28:31], v[68:71], v[180:183], v[28:31]
	v_mfma_f32_16x16x32_bf16 v[24:27], v[92:95], v[180:183], v[24:27]
	v_mfma_f32_16x16x32_bf16 v[12:15], v[68:71], v[188:191], v[12:15]
	v_mfma_f32_16x16x32_bf16 v[8:11], v[92:95], v[188:191], v[8:11]
	s_setprio 0
	s_setprio 1
	v_mfma_f32_16x16x32_bf16 v[52:55], v[104:107], v[152:155], v[52:55]
	v_mfma_f32_16x16x32_bf16 v[48:51], v[120:123], v[152:155], v[48:51]
	v_mfma_f32_16x16x32_bf16 v[36:39], v[104:107], v[168:171], v[36:39]
	v_mfma_f32_16x16x32_bf16 v[32:35], v[120:123], v[168:171], v[32:35]
	v_mfma_f32_16x16x32_bf16 v[20:23], v[104:107], v[176:179], v[20:23]
	v_mfma_f32_16x16x32_bf16 v[16:19], v[120:123], v[176:179], v[16:19]
	v_mfma_f32_16x16x32_bf16 v[4:7], v[104:107], v[184:187], v[4:7]
	v_mfma_f32_16x16x32_bf16 v[0:3], v[120:123], v[184:187], v[0:3]
	v_mfma_f32_16x16x32_bf16 v[52:55], v[108:111], v[164:167], v[52:55]
	v_mfma_f32_16x16x32_bf16 v[48:51], v[132:135], v[164:167], v[48:51]
	v_mfma_f32_16x16x32_bf16 v[36:39], v[108:111], v[172:175], v[36:39]
	v_mfma_f32_16x16x32_bf16 v[32:35], v[132:135], v[172:175], v[32:35]
	v_mfma_f32_16x16x32_bf16 v[20:23], v[108:111], v[180:183], v[20:23]
	v_mfma_f32_16x16x32_bf16 v[16:19], v[132:135], v[180:183], v[16:19]
	v_mfma_f32_16x16x32_bf16 v[4:7], v[108:111], v[188:191], v[4:7]
	v_mfma_f32_16x16x32_bf16 v[0:3], v[132:135], v[188:191], v[0:3]
	s_setprio 0
	s_barrier
	s_add_i32 s76, s76, 2
	s_add_u32 s74, s74, 0x100
	s_addc_u32 s75, s75, 0
	s_cmp_gt_u32 s76, 13
	s_mov_b64 s[28:29], s[6:7]
	s_cbranch_scc0 .LBB0_1083
	s_and_b64 vcc, exec, s[36:37]
	s_cbranch_vccz .LBB0_1086
	s_barrier

; #define PG8_STAGE(bufoff, gbase, voff) do { _Pragma("unroll") for (int _i = 0; _i < 2; ++_i) \
;         __builtin_amdgcn_global_load_lds((const unsigned*)((const char*)(gbase) + (voff)[_i]), (PG8_LAS unsigned*)(lds + (bufoff) + ldsw + _i * 8192), 16, 0, 0); } while (0)
; #define PG8_LDA(dst, b, h) do { _Pragma("unroll") for (int m = 0; m < 4; ++m) _Pragma("unroll") for (int k = 0; k < 2; ++k) dst[m][k] = *(const PG8_LAS bf16x8*)(lds + PG8_SA(b, h) + aoff + m * 2048 + k * 1024); } while (0)
; #define PG8_LDB(dst, b, h) do { _Pragma("unroll") for (int n = 0; n < 2; ++n) _Pragma("unroll") for (int k = 0; k < 2; ++k) dst[n][k] = *(const PG8_LAS bf16x8*)(lds + PG8_SB(b, h) + boff + n * 2048 + k * 1024); } while (0)
; #define PG8_MMA(ai, bj, At, Bt) do { __builtin_amdgcn_s_setprio(1); _Pragma("unroll") for (int m = 0; m < 4; ++m) _Pragma("unroll") for (int n = 0; n < 2; ++n) _Pragma("unroll") for (int k = 0; k < 2; ++k) \
;         acc[ai][bj][m][n] = __builtin_amdgcn_mfma_f32_16x16x32_bf16(Bt[n][k], At[m][k], acc[ai][bj][m][n], 0, 0, 0); __builtin_amdgcn_s_setprio(0); } while (0)
; #define PG8_WAIT_V(n) asm volatile("s_waitcnt vmcnt(" #n ")" ::: "memory")
; #define PG8_WAIT_L(n) asm volatile("s_waitcnt lgkmcnt(" #n ")" ::: "memory")
; #define PG8_BAR __builtin_amdgcn_s_barrier()
; #define PG8_SCHED __builtin_amdgcn_sched_barrier(0)
;     ...
;             const char* a1 = cA + (size_t)(t + 1) * kstep;
;             const char* a2 = last ? nA : cA + (size_t)(t + 2) * kstep; const char* b2 = last ? nB : cB + (size_t)(t + 2) * kstep;
;             const char* a3 = a2 + kstep; const char* b3 = b2 + kstep;
;             if (last && has_next) S.a_ready(nxt);
;             if constexpr (SP2) {
;             PG8_LDB(B0, 0, 0); PG8_LDB(B1, 0, 1); PG8_SCHED; PG8_LDA(At, 0, 0); PG8_STAGE(PG8_SA(1, 1), a1 + hstepA, voffA);
;             PG8_WAIT_V(8); PG8_WAIT_L(0); PG8_BAR; PG8_MMA(0, 0, At, B0); PG8_MMA(0, 1, At, B1); PG8_BAR; PG8_SCHED;
;             PG8_LDA(At, 0, 1); PG8_STAGE(PG8_SB(0, 0), b2, voffB); PG8_STAGE(PG8_SB(0, 1), b2 + hstepB, voffB); PG8_STAGE(PG8_SA(0, 0), a2, voffA);
.LBB0_1252:
	ds_read_b128 v[128:131], v203
	ds_read_b128 v[132:135], v203 offset:1024
	ds_read_b128 v[136:139], v203 offset:2048
	ds_read_b128 v[140:143], v203 offset:3072
	ds_read_b128 v[144:147], v204
	ds_read_b128 v[148:151], v204 offset:1024
	ds_read_b128 v[152:155], v204 offset:2048
	ds_read_b128 v[156:159], v204 offset:3072
	s_add_u32 s34, s28, 0xfffc0080
	s_addc_u32 s35, s29, -1
	s_cmp_eq_u32 s61, 12
	s_cselect_b32 s41, s25, s35
	s_cselect_b32 s40, s57, s34
	s_cselect_b32 s35, s23, s60
	s_cselect_b32 s34, s58, s59
	v_lshl_add_u64 v[200:201], s[28:29], 0, v[184:185]
	s_add_i32 m0, s39, 0xc000
	ds_read_b128 v[160:163], v205
	ds_read_b128 v[164:167], v205 offset:1024
	ds_read_b128 v[168:171], v205 offset:2048
	ds_read_b128 v[172:175], v205 offset:3072
	ds_read_b128 v[192:195], v205 offset:4096
	ds_read_b128 v[196:199], v205 offset:5120
	ds_read_b128 v[206:209], v205 offset:6144
	ds_read_b128 v[210:213], v205 offset:7168
	global_load_lds_dwordx4 v[200:201], off
	v_lshl_add_u64 v[200:201], s[28:29], 0, v[186:187]
	s_add_i32 m0, s39, 0xe000
	s_nop 0
	global_load_lds_dwordx4 v[200:201], off
	s_waitcnt vmcnt(8)
	s_waitcnt lgkmcnt(0)
	s_barrier
	s_setprio 1
	s_waitcnt lgkmcnt(0)
	v_mfma_f32_16x16x32_bf16 v[124:127], v[128:131], v[160:163], v[124:127]
	v_mfma_f32_16x16x32_bf16 v[120:123], v[136:139], v[160:163], v[120:123]
	v_mfma_f32_16x16x32_bf16 v[108:111], v[128:131], v[168:171], v[108:111]
	v_mfma_f32_16x16x32_bf16 v[104:107], v[136:139], v[168:171], v[104:107]
	v_mfma_f32_16x16x32_bf16 v[92:95], v[128:131], v[192:195], v[92:95]
	v_mfma_f32_16x16x32_bf16 v[88:91], v[136:139], v[192:195], v[88:91]
	v_mfma_f32_16x16x32_bf16 v[76:79], v[128:131], v[206:209], v[76:79]
	v_mfma_f32_16x16x32_bf16 v[72:75], v[136:139], v[206:209], v[72:75]
	v_mfma_f32_16x16x32_bf16 v[124:127], v[132:135], v[164:167], v[124:127]
	v_mfma_f32_16x16x32_bf16 v[120:123], v[140:143], v[164:167], v[120:123]
	v_mfma_f32_16x16x32_bf16 v[108:111], v[132:135], v[172:175], v[108:111]
	v_mfma_f32_16x16x32_bf16 v[104:107], v[140:143], v[172:175], v[104:107]
	v_mfma_f32_16x16x32_bf16 v[92:95], v[132:135], v[196:199], v[92:95]
	v_mfma_f32_16x16x32_bf16 v[88:91], v[140:143], v[196:199], v[88:91]
	v_mfma_f32_16x16x32_bf16 v[76:79], v[132:135], v[210:213], v[76:79]
	v_mfma_f32_16x16x32_bf16 v[72:75], v[140:143], v[210:213], v[72:75]
	s_setprio 0
	s_setprio 1
	v_mfma_f32_16x16x32_bf16 v[116:119], v[144:147], v[160:163], v[116:119]
	v_mfma_f32_16x16x32_bf16 v[112:115], v[152:155], v[160:163], v[112:115]
	v_mfma_f32_16x16x32_bf16 v[100:103], v[144:147], v[168:171], v[100:103]
	v_mfma_f32_16x16x32_bf16 v[96:99], v[152:155], v[168:171], v[96:99]
	v_mfma_f32_16x16x32_bf16 v[84:87], v[144:147], v[192:195], v[84:87]
	v_mfma_f32_16x16x32_bf16 v[80:83], v[152:155], v[192:195], v[80:83]
	v_mfma_f32_16x16x32_bf16 v[68:71], v[144:147], v[206:209], v[68:71]
	v_mfma_f32_16x16x32_bf16 v[64:67], v[152:155], v[206:209], v[64:67]
	v_mfma_f32_16x16x32_bf16 v[116:119], v[148:151], v[164:167], v[116:119]
	v_mfma_f32_16x16x32_bf16 v[112:115], v[156:159], v[164:167], v[112:115]
	v_mfma_f32_16x16x32_bf16 v[100:103], v[148:151], v[172:175], v[100:103]
	v_mfma_f32_16x16x32_bf16 v[96:99], v[156:159], v[172:175], v[96:99]
	v_mfma_f32_16x16x32_bf16 v[84:87], v[148:151], v[196:199], v[84:87]
	v_mfma_f32_16x16x32_bf16 v[80:83], v[156:159], v[196:199], v[80:83]
	v_mfma_f32_16x16x32_bf16 v[68:71], v[148:151], v[210:213], v[68:71]
	v_mfma_f32_16x16x32_bf16 v[64:67], v[156:159], v[210:213], v[64:67]
	s_setprio 0
	s_barrier
	s_add_i32 s48, s55, s43
	s_mov_b32 m0, s48
	ds_read_b128 v[160:163], v205 offset:16384
	ds_read_b128 v[164:167], v205 offset:17408
	ds_read_b128 v[168:171], v205 offset:18432
	ds_read_b128 v[172:175], v205 offset:19456
	ds_read_b128 v[192:195], v205 offset:20480
	ds_read_b128 v[196:199], v205 offset:21504
	ds_read_b128 v[206:209], v205 offset:22528
	ds_read_b128 v[210:213], v205 offset:23552
	v_lshl_add_u64 v[200:201], s[34:35], 0, v[178:179]
	global_load_lds_dwordx4 v[200:201], off
	s_add_i32 m0, s48, 0x2000
	s_add_u32 s48, s34, 0x40000
	v_lshl_add_u64 v[214:215], s[34:35], 0, v[182:183]
	s_addc_u32 s49, s35, 0
	s_add_i32 s62, s56, s43
	global_load_lds_dwordx4 v[214:215], off
	v_lshl_add_u64 v[216:217], s[48:49], 0, v[178:179]
	s_mov_b32 m0, s62
	v_lshl_add_u64 v[218:219], s[40:41], 0, v[180:181]
	global_load_lds_dwordx4 v[216:217], off
	v_lshl_add_u64 v[216:217], s[48:49], 0, v[182:183]
	s_add_i32 m0, s62, 0x2000
	s_nop 0
	global_load_lds_dwordx4 v[216:217], off
	v_lshl_add_u64 v[216:217], s[40:41], 0, v[176:177]
	s_mov_b32 m0, s39
	s_nop 0
	global_load_lds_dwordx4 v[216:217], off
	s_mov_b32 m0, s45
	s_nop 0
	global_load_lds_dwordx4 v[218:219], off
	s_waitcnt vmcnt(8)
	s_waitcnt lgkmcnt(0)
	s_barrier
; #define PG8_STAGE(bufoff, gbase, voff) do { _Pragma("unroll") for (int _i = 0; _i < 2; ++_i) \
;         __builtin_amdgcn_global_load_lds((const unsigned*)((const char*)(gbase) + (voff)[_i]), (PG8_LAS unsigned*)(lds + (bufoff) + ldsw + _i * 8192), 16, 0, 0); } while (0)
; #define PG8_LDA(dst, b, h) do { _Pragma("unroll") for (int m = 0; m < 4; ++m) _Pragma("unroll") for (int k = 0; k < 2; ++k) dst[m][k] = *(const PG8_LAS bf16x8*)(lds + PG8_SA(b, h) + aoff + m * 2048 + k * 1024); } while (0)
; #define PG8_LDB(dst, b, h) do { _Pragma("unroll") for (int n = 0; n < 2; ++n) _Pragma("unroll") for (int k = 0; k < 2; ++k) dst[n][k] = *(const PG8_LAS bf16x8*)(lds + PG8_SB(b, h) + boff + n * 2048 + k * 1024); } while (0)
; #define PG8_MMA(ai, bj, At, Bt) do { __builtin_amdgcn_s_setprio(1); _Pragma("unroll") for (int m = 0; m < 4; ++m) _Pragma("unroll") for (int n = 0; n < 2; ++n) _Pragma("unroll") for (int k = 0; k < 2; ++k) \
;         acc[ai][bj][m][n] = __builtin_amdgcn_mfma_f32_16x16x32_bf16(Bt[n][k], At[m][k], acc[ai][bj][m][n], 0, 0, 0); __builtin_amdgcn_s_setprio(0); } while (0)
; #define PG8_WAIT_V(n) asm volatile("s_waitcnt vmcnt(" #n ")" ::: "memory")
; #define PG8_WAIT_L(n) asm volatile("s_waitcnt lgkmcnt(" #n ")" ::: "memory")
; #define PG8_BAR __builtin_amdgcn_s_barrier()
; #define PG8_SCHED __builtin_amdgcn_sched_barrier(0)
;     ...
;             PG8_WAIT_V(8); PG8_WAIT_L(0); PG8_BAR; PG8_MMA(1, 0, At, B0); PG8_MMA(1, 1, At, B1); PG8_BAR; PG8_SCHED;
;             PG8_LDB(B0, 1, 0); PG8_LDB(B1, 1, 1); PG8_SCHED; PG8_LDA(At, 1, 0); PG8_STAGE(PG8_SA(0, 1), a2 + hstepA, voffA);
;             PG8_WAIT_V(8); PG8_WAIT_L(0); PG8_BAR; PG8_MMA(0, 0, At, B0); PG8_MMA(0, 1, At, B1); PG8_BAR; PG8_SCHED;
	s_setprio 1
	s_waitcnt lgkmcnt(0)
	v_mfma_f32_16x16x32_bf16 v[60:63], v[128:131], v[160:163], v[60:63]
	v_mfma_f32_16x16x32_bf16 v[56:59], v[136:139], v[160:163], v[56:59]
	v_mfma_f32_16x16x32_bf16 v[44:47], v[128:131], v[168:171], v[44:47]
	v_mfma_f32_16x16x32_bf16 v[40:43], v[136:139], v[168:171], v[40:43]
	v_mfma_f32_16x16x32_bf16 v[28:31], v[128:131], v[192:195], v[28:31]
	v_mfma_f32_16x16x32_bf16 v[24:27], v[136:139], v[192:195], v[24:27]
	v_mfma_f32_16x16x32_bf16 v[12:15], v[128:131], v[206:209], v[12:15]
	v_mfma_f32_16x16x32_bf16 v[8:11], v[136:139], v[206:209], v[8:11]
	v_mfma_f32_16x16x32_bf16 v[60:63], v[132:135], v[164:167], v[60:63]
	v_mfma_f32_16x16x32_bf16 v[56:59], v[140:143], v[164:167], v[56:59]
	v_mfma_f32_16x16x32_bf16 v[44:47], v[132:135], v[172:175], v[44:47]
	v_mfma_f32_16x16x32_bf16 v[40:43], v[140:143], v[172:175], v[40:43]
	v_mfma_f32_16x16x32_bf16 v[28:31], v[132:135], v[196:199], v[28:31]
	v_mfma_f32_16x16x32_bf16 v[24:27], v[140:143], v[196:199], v[24:27]
	v_mfma_f32_16x16x32_bf16 v[12:15], v[132:135], v[210:213], v[12:15]
	v_mfma_f32_16x16x32_bf16 v[8:11], v[140:143], v[210:213], v[8:11]
	s_setprio 0
	s_setprio 1
	v_mfma_f32_16x16x32_bf16 v[52:55], v[144:147], v[160:163], v[52:55]
	v_mfma_f32_16x16x32_bf16 v[48:51], v[152:155], v[160:163], v[48:51]
	v_mfma_f32_16x16x32_bf16 v[36:39], v[144:147], v[168:171], v[36:39]
	v_mfma_f32_16x16x32_bf16 v[32:35], v[152:155], v[168:171], v[32:35]
	v_mfma_f32_16x16x32_bf16 v[20:23], v[144:147], v[192:195], v[20:23]
	v_mfma_f32_16x16x32_bf16 v[16:19], v[152:155], v[192:195], v[16:19]
	v_mfma_f32_16x16x32_bf16 v[4:7], v[144:147], v[206:209], v[4:7]
	v_mfma_f32_16x16x32_bf16 v[0:3], v[152:155], v[206:209], v[0:3]
	v_mfma_f32_16x16x32_bf16 v[52:55], v[148:151], v[164:167], v[52:55]
	v_mfma_f32_16x16x32_bf16 v[48:51], v[156:159], v[164:167], v[48:51]
	v_mfma_f32_16x16x32_bf16 v[36:39], v[148:151], v[172:175], v[36:39]
	v_mfma_f32_16x16x32_bf16 v[32:35], v[156:159], v[172:175], v[32:35]
	v_mfma_f32_16x16x32_bf16 v[20:23], v[148:151], v[196:199], v[20:23]
	v_mfma_f32_16x16x32_bf16 v[16:19], v[156:159], v[196:199], v[16:19]
	v_mfma_f32_16x16x32_bf16 v[4:7], v[148:151], v[210:213], v[4:7]
	v_mfma_f32_16x16x32_bf16 v[0:3], v[156:159], v[210:213], v[0:3]
	s_setprio 0
	s_barrier
	s_add_i32 s48, 0, 0x18000
	s_add_i32 s49, 0, 0x1c000
	v_add_u32_e32 v140, s48, v202
	v_add_u32_e32 v156, s49, v202
	ds_read_b128 v[128:131], v140
	ds_read_b128 v[132:135], v140 offset:1024
	ds_read_b128 v[136:139], v140 offset:2048
	ds_read_b128 v[140:143], v140 offset:3072
	ds_read_b128 v[144:147], v156
	ds_read_b128 v[148:151], v156 offset:1024
	ds_read_b128 v[152:155], v156 offset:2048
	ds_read_b128 v[156:159], v156 offset:3072
	s_add_u32 s40, s40, 0x40000
	s_addc_u32 s41, s41, 0
	s_mov_b32 m0, s46
	v_lshl_add_u64 v[220:221], s[40:41], 0, v[176:177]
	ds_read_b128 v[160:163], v205 offset:32768
	ds_read_b128 v[164:167], v205 offset:33792
	ds_read_b128 v[168:171], v205 offset:34816
	ds_read_b128 v[172:175], v205 offset:35840
	ds_read_b128 v[192:195], v205 offset:36864
	ds_read_b128 v[196:199], v205 offset:37888
	ds_read_b128 v[206:209], v205 offset:38912
	ds_read_b128 v[210:213], v205 offset:39936
	global_load_lds_dwordx4 v[220:221], off
	v_lshl_add_u64 v[220:221], s[40:41], 0, v[180:181]
	s_mov_b32 m0, s47
	s_nop 0
	global_load_lds_dwordx4 v[220:221], off
	s_waitcnt vmcnt(8)
	s_waitcnt lgkmcnt(0)
	s_barrier
	s_setprio 1
	s_waitcnt lgkmcnt(0)
	v_mfma_f32_16x16x32_bf16 v[124:127], v[128:131], v[160:163], v[124:127]
	v_mfma_f32_16x16x32_bf16 v[120:123], v[136:139], v[160:163], v[120:123]
	v_mfma_f32_16x16x32_bf16 v[108:111], v[128:131], v[168:171], v[108:111]
	v_mfma_f32_16x16x32_bf16 v[104:107], v[136:139], v[168:171], v[104:107]
	v_mfma_f32_16x16x32_bf16 v[92:95], v[128:131], v[192:195], v[92:95]
	v_mfma_f32_16x16x32_bf16 v[88:91], v[136:139], v[192:195], v[88:91]
	v_mfma_f32_16x16x32_bf16 v[76:79], v[128:131], v[206:209], v[76:79]
	v_mfma_f32_16x16x32_bf16 v[72:75], v[136:139], v[206:209], v[72:75]
	v_mfma_f32_16x16x32_bf16 v[124:127], v[132:135], v[164:167], v[124:127]
	v_mfma_f32_16x16x32_bf16 v[120:123], v[140:143], v[164:167], v[120:123]
	v_mfma_f32_16x16x32_bf16 v[108:111], v[132:135], v[172:175], v[108:111]
	v_mfma_f32_16x16x32_bf16 v[104:107], v[140:143], v[172:175], v[104:107]
	v_mfma_f32_16x16x32_bf16 v[92:95], v[132:135], v[196:199], v[92:95]
	v_mfma_f32_16x16x32_bf16 v[88:91], v[140:143], v[196:199], v[88:91]
	v_mfma_f32_16x16x32_bf16 v[76:79], v[132:135], v[210:213], v[76:79]
	v_mfma_f32_16x16x32_bf16 v[72:75], v[140:143], v[210:213], v[72:75]
	s_setprio 0
	s_setprio 1
	v_mfma_f32_16x16x32_bf16 v[116:119], v[144:147], v[160:163], v[116:119]
	v_mfma_f32_16x16x32_bf16 v[112:115], v[152:155], v[160:163], v[112:115]
	v_mfma_f32_16x16x32_bf16 v[100:103], v[144:147], v[168:171], v[100:103]
	v_mfma_f32_16x16x32_bf16 v[96:99], v[152:155], v[168:171], v[96:99]
	v_mfma_f32_16x16x32_bf16 v[84:87], v[144:147], v[192:195], v[84:87]
	v_mfma_f32_16x16x32_bf16 v[80:83], v[152:155], v[192:195], v[80:83]
	v_mfma_f32_16x16x32_bf16 v[68:71], v[144:147], v[206:209], v[68:71]
	v_mfma_f32_16x16x32_bf16 v[64:67], v[152:155], v[206:209], v[64:67]
	v_mfma_f32_16x16x32_bf16 v[116:119], v[148:151], v[164:167], v[116:119]
	v_mfma_f32_16x16x32_bf16 v[112:115], v[156:159], v[164:167], v[112:115]
	v_mfma_f32_16x16x32_bf16 v[100:103], v[148:151], v[172:175], v[100:103]
	v_mfma_f32_16x16x32_bf16 v[96:99], v[156:159], v[172:175], v[96:99]
	v_mfma_f32_16x16x32_bf16 v[84:87], v[148:151], v[196:199], v[84:87]
	v_mfma_f32_16x16x32_bf16 v[80:83], v[156:159], v[196:199], v[80:83]
	v_mfma_f32_16x16x32_bf16 v[68:71], v[148:151], v[210:213], v[68:71]
	v_mfma_f32_16x16x32_bf16 v[64:67], v[156:159], v[210:213], v[64:67]
	s_setprio 0
	s_barrier
; #define PG8_STAGE(bufoff, gbase, voff) do { _Pragma("unroll") for (int _i = 0; _i < 2; ++_i) \
;         __builtin_amdgcn_global_load_lds((const unsigned*)((const char*)(gbase) + (voff)[_i]), (PG8_LAS unsigned*)(lds + (bufoff) + ldsw + _i * 8192), 16, 0, 0); } while (0)
; #define PG8_LDA(dst, b, h) do { _Pragma("unroll") for (int m = 0; m < 4; ++m) _Pragma("unroll") for (int k = 0; k < 2; ++k) dst[m][k] = *(const PG8_LAS bf16x8*)(lds + PG8_SA(b, h) + aoff + m * 2048 + k * 1024); } while (0)
; #define PG8_MMA(ai, bj, At, Bt) do { __builtin_amdgcn_s_setprio(1); _Pragma("unroll") for (int m = 0; m < 4; ++m) _Pragma("unroll") for (int n = 0; n < 2; ++n) _Pragma("unroll") for (int k = 0; k < 2; ++k) \
;         acc[ai][bj][m][n] = __builtin_amdgcn_mfma_f32_16x16x32_bf16(Bt[n][k], At[m][k], acc[ai][bj][m][n], 0, 0, 0); __builtin_amdgcn_s_setprio(0); } while (0)
; #define PG8_WAIT_V(n) asm volatile("s_waitcnt vmcnt(" #n ")" ::: "memory")
; #define PG8_WAIT_L(n) asm volatile("s_waitcnt lgkmcnt(" #n ")" ::: "memory")
; #define PG8_BAR __builtin_amdgcn_s_barrier()
; #define PG8_SCHED __builtin_amdgcn_sched_barrier(0)
;     ...
;         for (int t = 0; t < nt; t += 2) {
;     ...
;             PG8_LDA(At, 1, 1); PG8_STAGE(PG8_SB(1, 0), b3, voffB); PG8_STAGE(PG8_SB(1, 1), b3 + hstepB, voffB); PG8_STAGE(PG8_SA(1, 0), a3, voffA);
;             PG8_WAIT_V(8); PG8_WAIT_L(0); PG8_BAR; PG8_MMA(1, 0, At, B0); PG8_MMA(1, 1, At, B1); PG8_BAR; PG8_SCHED;
	s_add_i32 s40, s48, s43
	s_mov_b32 m0, s40
	ds_read_b128 v[160:163], v205 offset:49152
	ds_read_b128 v[164:167], v205 offset:50176
	ds_read_b128 v[168:171], v205 offset:51200
	ds_read_b128 v[172:175], v205 offset:52224
	ds_read_b128 v[192:195], v205 offset:53248
	ds_read_b128 v[196:199], v205 offset:54272
	ds_read_b128 v[206:209], v205 offset:55296
	ds_read_b128 v[210:213], v205 offset:56320
	v_lshl_add_u64 v[200:201], v[200:201], 0, s[18:19]
	global_load_lds_dwordx4 v[200:201], off
	s_add_i32 m0, s40, 0x2000
	s_add_u32 s34, s34, 0x40080
	v_lshl_add_u64 v[200:201], v[214:215], 0, s[18:19]
	s_addc_u32 s35, s35, 0
	s_add_i32 s40, s49, s43
	global_load_lds_dwordx4 v[200:201], off
	v_lshl_add_u64 v[200:201], s[34:35], 0, v[178:179]
	s_mov_b32 m0, s40
	s_nop 0
	global_load_lds_dwordx4 v[200:201], off
	v_lshl_add_u64 v[200:201], s[34:35], 0, v[182:183]
	s_add_i32 m0, s40, 0x2000
	s_nop 0
	global_load_lds_dwordx4 v[200:201], off
	v_lshl_add_u64 v[200:201], v[216:217], 0, s[18:19]
	s_mov_b32 m0, s53
	s_nop 0
	global_load_lds_dwordx4 v[200:201], off
	v_lshl_add_u64 v[200:201], v[218:219], 0, s[18:19]
	s_mov_b32 m0, s54
	s_nop 0
	global_load_lds_dwordx4 v[200:201], off
	s_waitcnt vmcnt(8)
	s_waitcnt lgkmcnt(0)
	s_barrier
	s_setprio 1
	s_waitcnt lgkmcnt(0)
	v_mfma_f32_16x16x32_bf16 v[60:63], v[128:131], v[160:163], v[60:63]
	v_mfma_f32_16x16x32_bf16 v[56:59], v[136:139], v[160:163], v[56:59]
	v_mfma_f32_16x16x32_bf16 v[44:47], v[128:131], v[168:171], v[44:47]
	v_mfma_f32_16x16x32_bf16 v[40:43], v[136:139], v[168:171], v[40:43]
	v_mfma_f32_16x16x32_bf16 v[28:31], v[128:131], v[192:195], v[28:31]
	v_mfma_f32_16x16x32_bf16 v[24:27], v[136:139], v[192:195], v[24:27]
	v_mfma_f32_16x16x32_bf16 v[12:15], v[128:131], v[206:209], v[12:15]
	v_mfma_f32_16x16x32_bf16 v[8:11], v[136:139], v[206:209], v[8:11]
	v_mfma_f32_16x16x32_bf16 v[60:63], v[132:135], v[164:167], v[60:63]
	v_mfma_f32_16x16x32_bf16 v[56:59], v[140:143], v[164:167], v[56:59]
	v_mfma_f32_16x16x32_bf16 v[44:47], v[132:135], v[172:175], v[44:47]
	v_mfma_f32_16x16x32_bf16 v[40:43], v[140:143], v[172:175], v[40:43]
	v_mfma_f32_16x16x32_bf16 v[28:31], v[132:135], v[196:199], v[28:31]
	v_mfma_f32_16x16x32_bf16 v[24:27], v[140:143], v[196:199], v[24:27]
	v_mfma_f32_16x16x32_bf16 v[12:15], v[132:135], v[210:213], v[12:15]
	v_mfma_f32_16x16x32_bf16 v[8:11], v[140:143], v[210:213], v[8:11]
	s_setprio 0
	s_setprio 1
	v_mfma_f32_16x16x32_bf16 v[52:55], v[144:147], v[160:163], v[52:55]
	v_mfma_f32_16x16x32_bf16 v[48:51], v[152:155], v[160:163], v[48:51]
	v_mfma_f32_16x16x32_bf16 v[36:39], v[144:147], v[168:171], v[36:39]
	v_mfma_f32_16x16x32_bf16 v[32:35], v[152:155], v[168:171], v[32:35]
	v_mfma_f32_16x16x32_bf16 v[20:23], v[144:147], v[192:195], v[20:23]
	v_mfma_f32_16x16x32_bf16 v[16:19], v[152:155], v[192:195], v[16:19]
	v_mfma_f32_16x16x32_bf16 v[4:7], v[144:147], v[206:209], v[4:7]
	v_mfma_f32_16x16x32_bf16 v[0:3], v[152:155], v[206:209], v[0:3]
	v_mfma_f32_16x16x32_bf16 v[52:55], v[148:151], v[164:167], v[52:55]
	v_mfma_f32_16x16x32_bf16 v[48:51], v[156:159], v[164:167], v[48:51]
	v_mfma_f32_16x16x32_bf16 v[36:39], v[148:151], v[172:175], v[36:39]
	v_mfma_f32_16x16x32_bf16 v[32:35], v[156:159], v[172:175], v[32:35]
	v_mfma_f32_16x16x32_bf16 v[20:23], v[148:151], v[196:199], v[20:23]
	v_mfma_f32_16x16x32_bf16 v[16:19], v[156:159], v[196:199], v[16:19]
	v_mfma_f32_16x16x32_bf16 v[4:7], v[148:151], v[210:213], v[4:7]
	v_mfma_f32_16x16x32_bf16 v[0:3], v[156:159], v[210:213], v[0:3]
	s_setprio 0
	s_barrier
	s_add_i32 s61, s61, 2
	s_add_u32 s28, s28, 0x100
	s_addc_u32 s29, s29, 0
	s_add_u32 s59, s59, 0x100
	s_addc_u32 s60, s60, 0
	s_cmp_gt_u32 s61, 13
	s_cbranch_scc0 .LBB0_1252
	s_and_b64 vcc, exec, s[20:21]
	s_cbranch_vccz .LBB0_1255
	s_barrier

; #define PG8_STAGE(bufoff, gbase, voff) do { _Pragma("unroll") for (int _i = 0; _i < 2; ++_i) \
;         __builtin_amdgcn_global_load_lds((const unsigned*)((const char*)(gbase) + (voff)[_i]), (PG8_LAS unsigned*)(lds + (bufoff) + ldsw + _i * 8192), 16, 0, 0); } while (0)
; #define PG8_LDA(dst, b, h) do { _Pragma("unroll") for (int m = 0; m < 4; ++m) _Pragma("unroll") for (int k = 0; k < 2; ++k) dst[m][k] = *(const PG8_LAS bf16x8*)(lds + PG8_SA(b, h) + aoff + m * 2048 + k * 1024); } while (0)
; #define PG8_LDB(dst, b, h) do { _Pragma("unroll") for (int n = 0; n < 2; ++n) _Pragma("unroll") for (int k = 0; k < 2; ++k) dst[n][k] = *(const PG8_LAS bf16x8*)(lds + PG8_SB(b, h) + boff + n * 2048 + k * 1024); } while (0)
; #define PG8_MMA(ai, bj, At, Bt) do { __builtin_amdgcn_s_setprio(1); _Pragma("unroll") for (int m = 0; m < 4; ++m) _Pragma("unroll") for (int n = 0; n < 2; ++n) _Pragma("unroll") for (int k = 0; k < 2; ++k) \
;         acc[ai][bj][m][n] = __builtin_amdgcn_mfma_f32_16x16x32_bf16(Bt[n][k], At[m][k], acc[ai][bj][m][n], 0, 0, 0); __builtin_amdgcn_s_setprio(0); } while (0)
; #define PG8_WAIT_V(n) asm volatile("s_waitcnt vmcnt(" #n ")" ::: "memory")
; #define PG8_WAIT_L(n) asm volatile("s_waitcnt lgkmcnt(" #n ")" ::: "memory")
; #define PG8_BAR __builtin_amdgcn_s_barrier()
; #define PG8_SCHED __builtin_amdgcn_sched_barrier(0)
;     ...
;             const bool last = (t == nt - 2);
;             const char* a1 = cA + (size_t)(t + 1) * kstep;
;             const char* a2 = last ? nA : cA + (size_t)(t + 2) * kstep; const char* b2 = last ? nB : cB + (size_t)(t + 2) * kstep;
;             const char* a3 = a2 + kstep; const char* b3 = b2 + kstep;
;             if (last && has_next) S.a_ready(nxt);
;             if constexpr (SP2) {
;             PG8_LDB(B0, 0, 0); PG8_LDB(B1, 0, 1); PG8_SCHED; PG8_LDA(At, 0, 0); PG8_STAGE(PG8_SA(1, 1), a1 + hstepA, voffA);
;             PG8_WAIT_V(8); PG8_WAIT_L(0); PG8_BAR; PG8_MMA(0, 0, At, B0); PG8_MMA(0, 1, At, B1); PG8_BAR; PG8_SCHED;
;             PG8_LDA(At, 0, 1); PG8_STAGE(PG8_SB(0, 0), b2, voffB); PG8_STAGE(PG8_SB(0, 1), b2 + hstepB, voffB); PG8_STAGE(PG8_SA(0, 0), a2, voffA);
.LBB0_1341:
	ds_read_b128 v[144:147], v151
	ds_read_b128 v[160:163], v151 offset:1024
	ds_read_b128 v[164:167], v151 offset:2048
	ds_read_b128 v[168:171], v151 offset:3072
	ds_read_b128 v[172:175], v153
	ds_read_b128 v[176:179], v153 offset:1024
	ds_read_b128 v[180:183], v153 offset:2048
	ds_read_b128 v[184:187], v153 offset:3072
	s_add_u32 s36, s34, 0xfffc0080
	s_addc_u32 s37, s35, -1
	s_cmp_eq_u32 s62, 12
	s_cselect_b32 s39, s23, s37
	s_cselect_b32 s38, s58, s36
	s_cselect_b32 s37, s21, s61
	s_cselect_b32 s36, s59, s60
	v_lshl_add_u64 v[154:155], s[34:35], 0, v[136:137]
	s_add_i32 m0, s29, 0xc000
	ds_read_b128 v[188:191], v157
	ds_read_b128 v[192:195], v157 offset:1024
	ds_read_b128 v[196:199], v157 offset:2048
	ds_read_b128 v[200:203], v157 offset:3072
	ds_read_b128 v[204:207], v157 offset:4096
	ds_read_b128 v[208:211], v157 offset:5120
	ds_read_b128 v[212:215], v157 offset:6144
	ds_read_b128 v[216:219], v157 offset:7168
	global_load_lds_dwordx4 v[154:155], off
	v_lshl_add_u64 v[154:155], s[34:35], 0, v[138:139]
	s_add_i32 m0, s29, 0xe000
	s_nop 0
	global_load_lds_dwordx4 v[154:155], off
	s_waitcnt vmcnt(8)
	s_waitcnt lgkmcnt(0)
	s_barrier
	s_setprio 1
	s_waitcnt lgkmcnt(0)
	v_mfma_f32_16x16x32_bf16 v[124:127], v[144:147], v[188:191], v[124:127]
	v_mfma_f32_16x16x32_bf16 v[120:123], v[164:167], v[188:191], v[120:123]
	v_mfma_f32_16x16x32_bf16 v[108:111], v[144:147], v[196:199], v[108:111]
	v_mfma_f32_16x16x32_bf16 v[104:107], v[164:167], v[196:199], v[104:107]
	v_mfma_f32_16x16x32_bf16 v[92:95], v[144:147], v[204:207], v[92:95]
	v_mfma_f32_16x16x32_bf16 v[88:91], v[164:167], v[204:207], v[88:91]
	v_mfma_f32_16x16x32_bf16 v[76:79], v[144:147], v[212:215], v[76:79]
	v_mfma_f32_16x16x32_bf16 v[72:75], v[164:167], v[212:215], v[72:75]
	v_mfma_f32_16x16x32_bf16 v[124:127], v[160:163], v[192:195], v[124:127]
	v_mfma_f32_16x16x32_bf16 v[120:123], v[168:171], v[192:195], v[120:123]
	v_mfma_f32_16x16x32_bf16 v[108:111], v[160:163], v[200:203], v[108:111]
	v_mfma_f32_16x16x32_bf16 v[104:107], v[168:171], v[200:203], v[104:107]
	v_mfma_f32_16x16x32_bf16 v[92:95], v[160:163], v[208:211], v[92:95]
	v_mfma_f32_16x16x32_bf16 v[88:91], v[168:171], v[208:211], v[88:91]
	v_mfma_f32_16x16x32_bf16 v[76:79], v[160:163], v[216:219], v[76:79]
	v_mfma_f32_16x16x32_bf16 v[72:75], v[168:171], v[216:219], v[72:75]
	s_setprio 0
	s_setprio 1
	v_mfma_f32_16x16x32_bf16 v[116:119], v[172:175], v[188:191], v[116:119]
	v_mfma_f32_16x16x32_bf16 v[112:115], v[180:183], v[188:191], v[112:115]
	v_mfma_f32_16x16x32_bf16 v[100:103], v[172:175], v[196:199], v[100:103]
	v_mfma_f32_16x16x32_bf16 v[96:99], v[180:183], v[196:199], v[96:99]
	v_mfma_f32_16x16x32_bf16 v[84:87], v[172:175], v[204:207], v[84:87]
	v_mfma_f32_16x16x32_bf16 v[80:83], v[180:183], v[204:207], v[80:83]
	v_mfma_f32_16x16x32_bf16 v[68:71], v[172:175], v[212:215], v[68:71]
	v_mfma_f32_16x16x32_bf16 v[64:67], v[180:183], v[212:215], v[64:67]
	v_mfma_f32_16x16x32_bf16 v[116:119], v[176:179], v[192:195], v[116:119]
	v_mfma_f32_16x16x32_bf16 v[112:115], v[184:187], v[192:195], v[112:115]
	v_mfma_f32_16x16x32_bf16 v[100:103], v[176:179], v[200:203], v[100:103]
	v_mfma_f32_16x16x32_bf16 v[96:99], v[184:187], v[200:203], v[96:99]
	v_mfma_f32_16x16x32_bf16 v[84:87], v[176:179], v[208:211], v[84:87]
	v_mfma_f32_16x16x32_bf16 v[80:83], v[184:187], v[208:211], v[80:83]
	v_mfma_f32_16x16x32_bf16 v[68:71], v[176:179], v[216:219], v[68:71]
	v_mfma_f32_16x16x32_bf16 v[64:67], v[184:187], v[216:219], v[64:67]
	s_setprio 0
	s_barrier
	s_add_i32 s48, s54, s43
	s_mov_b32 m0, s48
	ds_read_b128 v[188:191], v157 offset:16384
	ds_read_b128 v[192:195], v157 offset:17408
	ds_read_b128 v[196:199], v157 offset:18432
	ds_read_b128 v[200:203], v157 offset:19456
	ds_read_b128 v[204:207], v157 offset:20480
	ds_read_b128 v[208:211], v157 offset:21504
	ds_read_b128 v[212:215], v157 offset:22528
	ds_read_b128 v[216:219], v157 offset:23552
	v_lshl_add_u64 v[154:155], s[36:37], 0, v[132:133]
	global_load_lds_dwordx4 v[154:155], off
	s_add_i32 m0, s48, 0x2000
	s_add_u32 s48, s36, 0x40000
	v_lshl_add_u64 v[220:221], s[36:37], 0, v[128:129]
	s_addc_u32 s49, s37, 0
	s_add_i32 s63, s55, s43
	global_load_lds_dwordx4 v[220:221], off
	v_lshl_add_u64 v[222:223], s[48:49], 0, v[132:133]
	s_mov_b32 m0, s63
	v_lshl_add_u64 v[224:225], s[38:39], 0, v[130:131]
	global_load_lds_dwordx4 v[222:223], off
	v_lshl_add_u64 v[222:223], s[48:49], 0, v[128:129]
	s_add_i32 m0, s63, 0x2000
	s_nop 0
	global_load_lds_dwordx4 v[222:223], off
	v_lshl_add_u64 v[222:223], s[38:39], 0, v[134:135]
	s_mov_b32 m0, s29
	s_nop 0
	global_load_lds_dwordx4 v[222:223], off
	s_mov_b32 m0, s44
	s_nop 0
	global_load_lds_dwordx4 v[224:225], off
	s_waitcnt vmcnt(8)
	s_waitcnt lgkmcnt(0)
	s_barrier
; #define PG8_STAGE(bufoff, gbase, voff) do { _Pragma("unroll") for (int _i = 0; _i < 2; ++_i) \
;         __builtin_amdgcn_global_load_lds((const unsigned*)((const char*)(gbase) + (voff)[_i]), (PG8_LAS unsigned*)(lds + (bufoff) + ldsw + _i * 8192), 16, 0, 0); } while (0)
; #define PG8_LDA(dst, b, h) do { _Pragma("unroll") for (int m = 0; m < 4; ++m) _Pragma("unroll") for (int k = 0; k < 2; ++k) dst[m][k] = *(const PG8_LAS bf16x8*)(lds + PG8_SA(b, h) + aoff + m * 2048 + k * 1024); } while (0)
; #define PG8_LDB(dst, b, h) do { _Pragma("unroll") for (int n = 0; n < 2; ++n) _Pragma("unroll") for (int k = 0; k < 2; ++k) dst[n][k] = *(const PG8_LAS bf16x8*)(lds + PG8_SB(b, h) + boff + n * 2048 + k * 1024); } while (0)
; #define PG8_MMA(ai, bj, At, Bt) do { __builtin_amdgcn_s_setprio(1); _Pragma("unroll") for (int m = 0; m < 4; ++m) _Pragma("unroll") for (int n = 0; n < 2; ++n) _Pragma("unroll") for (int k = 0; k < 2; ++k) \
;         acc[ai][bj][m][n] = __builtin_amdgcn_mfma_f32_16x16x32_bf16(Bt[n][k], At[m][k], acc[ai][bj][m][n], 0, 0, 0); __builtin_amdgcn_s_setprio(0); } while (0)
; #define PG8_WAIT_V(n) asm volatile("s_waitcnt vmcnt(" #n ")" ::: "memory")
; #define PG8_WAIT_L(n) asm volatile("s_waitcnt lgkmcnt(" #n ")" ::: "memory")
; #define PG8_BAR __builtin_amdgcn_s_barrier()
; #define PG8_SCHED __builtin_amdgcn_sched_barrier(0)
;     ...
;             PG8_WAIT_V(8); PG8_WAIT_L(0); PG8_BAR; PG8_MMA(1, 0, At, B0); PG8_MMA(1, 1, At, B1); PG8_BAR; PG8_SCHED;
;             PG8_LDB(B0, 1, 0); PG8_LDB(B1, 1, 1); PG8_SCHED; PG8_LDA(At, 1, 0); PG8_STAGE(PG8_SA(0, 1), a2 + hstepA, voffA);
;             PG8_WAIT_V(8); PG8_WAIT_L(0); PG8_BAR; PG8_MMA(0, 0, At, B0); PG8_MMA(0, 1, At, B1); PG8_BAR; PG8_SCHED;
	s_setprio 1
	s_waitcnt lgkmcnt(0)
	v_mfma_f32_16x16x32_bf16 v[60:63], v[144:147], v[188:191], v[60:63]
	v_mfma_f32_16x16x32_bf16 v[56:59], v[164:167], v[188:191], v[56:59]
	v_mfma_f32_16x16x32_bf16 v[44:47], v[144:147], v[196:199], v[44:47]
	v_mfma_f32_16x16x32_bf16 v[40:43], v[164:167], v[196:199], v[40:43]
	v_mfma_f32_16x16x32_bf16 v[28:31], v[144:147], v[204:207], v[28:31]
	v_mfma_f32_16x16x32_bf16 v[24:27], v[164:167], v[204:207], v[24:27]
	v_mfma_f32_16x16x32_bf16 v[12:15], v[144:147], v[212:215], v[12:15]
	v_mfma_f32_16x16x32_bf16 v[8:11], v[164:167], v[212:215], v[8:11]
	v_mfma_f32_16x16x32_bf16 v[60:63], v[160:163], v[192:195], v[60:63]
	v_mfma_f32_16x16x32_bf16 v[56:59], v[168:171], v[192:195], v[56:59]
	v_mfma_f32_16x16x32_bf16 v[44:47], v[160:163], v[200:203], v[44:47]
	v_mfma_f32_16x16x32_bf16 v[40:43], v[168:171], v[200:203], v[40:43]
	v_mfma_f32_16x16x32_bf16 v[28:31], v[160:163], v[208:211], v[28:31]
	v_mfma_f32_16x16x32_bf16 v[24:27], v[168:171], v[208:211], v[24:27]
	v_mfma_f32_16x16x32_bf16 v[12:15], v[160:163], v[216:219], v[12:15]
	v_mfma_f32_16x16x32_bf16 v[8:11], v[168:171], v[216:219], v[8:11]
	s_setprio 0
	s_setprio 1
	v_mfma_f32_16x16x32_bf16 v[52:55], v[172:175], v[188:191], v[52:55]
	v_mfma_f32_16x16x32_bf16 v[48:51], v[180:183], v[188:191], v[48:51]
	v_mfma_f32_16x16x32_bf16 v[36:39], v[172:175], v[196:199], v[36:39]
	v_mfma_f32_16x16x32_bf16 v[32:35], v[180:183], v[196:199], v[32:35]
	v_mfma_f32_16x16x32_bf16 v[20:23], v[172:175], v[204:207], v[20:23]
	v_mfma_f32_16x16x32_bf16 v[16:19], v[180:183], v[204:207], v[16:19]
	v_mfma_f32_16x16x32_bf16 v[4:7], v[172:175], v[212:215], v[4:7]
	v_mfma_f32_16x16x32_bf16 v[0:3], v[180:183], v[212:215], v[0:3]
	v_mfma_f32_16x16x32_bf16 v[52:55], v[176:179], v[192:195], v[52:55]
	v_mfma_f32_16x16x32_bf16 v[48:51], v[184:187], v[192:195], v[48:51]
	v_mfma_f32_16x16x32_bf16 v[36:39], v[176:179], v[200:203], v[36:39]
	v_mfma_f32_16x16x32_bf16 v[32:35], v[184:187], v[200:203], v[32:35]
	v_mfma_f32_16x16x32_bf16 v[20:23], v[176:179], v[208:211], v[20:23]
	v_mfma_f32_16x16x32_bf16 v[16:19], v[184:187], v[208:211], v[16:19]
	v_mfma_f32_16x16x32_bf16 v[4:7], v[176:179], v[216:219], v[4:7]
	v_mfma_f32_16x16x32_bf16 v[0:3], v[184:187], v[216:219], v[0:3]
	s_setprio 0
	s_barrier
	s_add_i32 s48, 0, 0x18000
	v_add_u32_e32 v148, s48, v149
	s_add_i32 s49, 0, 0x1c000
	ds_read_b128 v[144:147], v148
	ds_read_b128 v[160:163], v148 offset:1024
	ds_read_b128 v[164:167], v148 offset:2048
	ds_read_b128 v[168:171], v148 offset:3072
	v_add_u32_e32 v148, s49, v149
	ds_read_b128 v[172:175], v148
	ds_read_b128 v[176:179], v148 offset:1024
	ds_read_b128 v[180:183], v148 offset:2048
	ds_read_b128 v[184:187], v148 offset:3072
	s_add_u32 s38, s38, 0x40000
	s_addc_u32 s39, s39, 0
	s_mov_b32 m0, s45
	v_lshl_add_u64 v[226:227], s[38:39], 0, v[134:135]
	ds_read_b128 v[188:191], v157 offset:32768
	ds_read_b128 v[192:195], v157 offset:33792
	ds_read_b128 v[196:199], v157 offset:34816
	ds_read_b128 v[200:203], v157 offset:35840
	ds_read_b128 v[204:207], v157 offset:36864
	ds_read_b128 v[208:211], v157 offset:37888
	ds_read_b128 v[212:215], v157 offset:38912
	ds_read_b128 v[216:219], v157 offset:39936
	global_load_lds_dwordx4 v[226:227], off
	v_lshl_add_u64 v[226:227], s[38:39], 0, v[130:131]
	s_mov_b32 m0, s46
	s_nop 0
	global_load_lds_dwordx4 v[226:227], off
	s_waitcnt vmcnt(8)
	s_waitcnt lgkmcnt(0)
	s_barrier
	s_setprio 1
	s_waitcnt lgkmcnt(0)
	v_mfma_f32_16x16x32_bf16 v[124:127], v[144:147], v[188:191], v[124:127]
	v_mfma_f32_16x16x32_bf16 v[120:123], v[164:167], v[188:191], v[120:123]
	v_mfma_f32_16x16x32_bf16 v[108:111], v[144:147], v[196:199], v[108:111]
	v_mfma_f32_16x16x32_bf16 v[104:107], v[164:167], v[196:199], v[104:107]
	v_mfma_f32_16x16x32_bf16 v[92:95], v[144:147], v[204:207], v[92:95]
	v_mfma_f32_16x16x32_bf16 v[88:91], v[164:167], v[204:207], v[88:91]
	v_mfma_f32_16x16x32_bf16 v[76:79], v[144:147], v[212:215], v[76:79]
	v_mfma_f32_16x16x32_bf16 v[72:75], v[164:167], v[212:215], v[72:75]
	v_mfma_f32_16x16x32_bf16 v[124:127], v[160:163], v[192:195], v[124:127]
	v_mfma_f32_16x16x32_bf16 v[120:123], v[168:171], v[192:195], v[120:123]
	v_mfma_f32_16x16x32_bf16 v[108:111], v[160:163], v[200:203], v[108:111]
	v_mfma_f32_16x16x32_bf16 v[104:107], v[168:171], v[200:203], v[104:107]
	v_mfma_f32_16x16x32_bf16 v[92:95], v[160:163], v[208:211], v[92:95]
	v_mfma_f32_16x16x32_bf16 v[88:91], v[168:171], v[208:211], v[88:91]
	v_mfma_f32_16x16x32_bf16 v[76:79], v[160:163], v[216:219], v[76:79]
	v_mfma_f32_16x16x32_bf16 v[72:75], v[168:171], v[216:219], v[72:75]
	s_setprio 0
	s_setprio 1
	v_mfma_f32_16x16x32_bf16 v[116:119], v[172:175], v[188:191], v[116:119]
	v_mfma_f32_16x16x32_bf16 v[112:115], v[180:183], v[188:191], v[112:115]
	v_mfma_f32_16x16x32_bf16 v[100:103], v[172:175], v[196:199], v[100:103]
	v_mfma_f32_16x16x32_bf16 v[96:99], v[180:183], v[196:199], v[96:99]
	v_mfma_f32_16x16x32_bf16 v[84:87], v[172:175], v[204:207], v[84:87]
	v_mfma_f32_16x16x32_bf16 v[80:83], v[180:183], v[204:207], v[80:83]
	v_mfma_f32_16x16x32_bf16 v[68:71], v[172:175], v[212:215], v[68:71]
	v_mfma_f32_16x16x32_bf16 v[64:67], v[180:183], v[212:215], v[64:67]
	v_mfma_f32_16x16x32_bf16 v[116:119], v[176:179], v[192:195], v[116:119]
	v_mfma_f32_16x16x32_bf16 v[112:115], v[184:187], v[192:195], v[112:115]
	v_mfma_f32_16x16x32_bf16 v[100:103], v[176:179], v[200:203], v[100:103]
	v_mfma_f32_16x16x32_bf16 v[96:99], v[184:187], v[200:203], v[96:99]
	v_mfma_f32_16x16x32_bf16 v[84:87], v[176:179], v[208:211], v[84:87]
	v_mfma_f32_16x16x32_bf16 v[80:83], v[184:187], v[208:211], v[80:83]
	v_mfma_f32_16x16x32_bf16 v[68:71], v[176:179], v[216:219], v[68:71]
	v_mfma_f32_16x16x32_bf16 v[64:67], v[184:187], v[216:219], v[64:67]
	s_setprio 0
	s_barrier
; #define PG8_STAGE(bufoff, gbase, voff) do { _Pragma("unroll") for (int _i = 0; _i < 2; ++_i) \
;         __builtin_amdgcn_global_load_lds((const unsigned*)((const char*)(gbase) + (voff)[_i]), (PG8_LAS unsigned*)(lds + (bufoff) + ldsw + _i * 8192), 16, 0, 0); } while (0)
; #define PG8_LDA(dst, b, h) do { _Pragma("unroll") for (int m = 0; m < 4; ++m) _Pragma("unroll") for (int k = 0; k < 2; ++k) dst[m][k] = *(const PG8_LAS bf16x8*)(lds + PG8_SA(b, h) + aoff + m * 2048 + k * 1024); } while (0)
; #define PG8_MMA(ai, bj, At, Bt) do { __builtin_amdgcn_s_setprio(1); _Pragma("unroll") for (int m = 0; m < 4; ++m) _Pragma("unroll") for (int n = 0; n < 2; ++n) _Pragma("unroll") for (int k = 0; k < 2; ++k) \
;         acc[ai][bj][m][n] = __builtin_amdgcn_mfma_f32_16x16x32_bf16(Bt[n][k], At[m][k], acc[ai][bj][m][n], 0, 0, 0); __builtin_amdgcn_s_setprio(0); } while (0)
; #define PG8_WAIT_V(n) asm volatile("s_waitcnt vmcnt(" #n ")" ::: "memory")
; #define PG8_WAIT_L(n) asm volatile("s_waitcnt lgkmcnt(" #n ")" ::: "memory")
; #define PG8_BAR __builtin_amdgcn_s_barrier()
; #define PG8_SCHED __builtin_amdgcn_sched_barrier(0)
;     ...
;         for (int t = 0; t < nt; t += 2) {
;     ...
;             PG8_LDA(At, 1, 1); PG8_STAGE(PG8_SB(1, 0), b3, voffB); PG8_STAGE(PG8_SB(1, 1), b3 + hstepB, voffB); PG8_STAGE(PG8_SA(1, 0), a3, voffA);
;             PG8_WAIT_V(8); PG8_WAIT_L(0); PG8_BAR; PG8_MMA(1, 0, At, B0); PG8_MMA(1, 1, At, B1); PG8_BAR; PG8_SCHED;
	s_add_i32 s38, s48, s43
	s_mov_b32 m0, s38
	ds_read_b128 v[188:191], v157 offset:49152
	ds_read_b128 v[192:195], v157 offset:50176
	ds_read_b128 v[196:199], v157 offset:51200
	ds_read_b128 v[200:203], v157 offset:52224
	ds_read_b128 v[204:207], v157 offset:53248
	ds_read_b128 v[208:211], v157 offset:54272
	ds_read_b128 v[212:215], v157 offset:55296
	ds_read_b128 v[216:219], v157 offset:56320
	v_lshl_add_u64 v[154:155], v[154:155], 0, s[10:11]
	global_load_lds_dwordx4 v[154:155], off
	s_add_i32 m0, s38, 0x2000
	s_add_u32 s36, s36, 0x40080
	v_lshl_add_u64 v[154:155], v[220:221], 0, s[10:11]
	s_addc_u32 s37, s37, 0
	s_add_i32 s38, s49, s43
	global_load_lds_dwordx4 v[154:155], off
	v_lshl_add_u64 v[154:155], s[36:37], 0, v[132:133]
	s_mov_b32 m0, s38
	s_nop 0
	global_load_lds_dwordx4 v[154:155], off
	v_lshl_add_u64 v[154:155], s[36:37], 0, v[128:129]
	s_add_i32 m0, s38, 0x2000
	s_nop 0
	global_load_lds_dwordx4 v[154:155], off
	v_lshl_add_u64 v[154:155], v[222:223], 0, s[10:11]
	s_mov_b32 m0, s52
	s_nop 0
	global_load_lds_dwordx4 v[154:155], off
	v_lshl_add_u64 v[154:155], v[224:225], 0, s[10:11]
	s_mov_b32 m0, s53
	s_nop 0
	global_load_lds_dwordx4 v[154:155], off
	s_waitcnt vmcnt(8)
	s_waitcnt lgkmcnt(0)
	s_barrier
	s_setprio 1
	s_waitcnt lgkmcnt(0)
	v_mfma_f32_16x16x32_bf16 v[60:63], v[144:147], v[188:191], v[60:63]
	v_mfma_f32_16x16x32_bf16 v[56:59], v[164:167], v[188:191], v[56:59]
	v_mfma_f32_16x16x32_bf16 v[44:47], v[144:147], v[196:199], v[44:47]
	v_mfma_f32_16x16x32_bf16 v[40:43], v[164:167], v[196:199], v[40:43]
	v_mfma_f32_16x16x32_bf16 v[28:31], v[144:147], v[204:207], v[28:31]
	v_mfma_f32_16x16x32_bf16 v[24:27], v[164:167], v[204:207], v[24:27]
	v_mfma_f32_16x16x32_bf16 v[12:15], v[144:147], v[212:215], v[12:15]
	v_mfma_f32_16x16x32_bf16 v[8:11], v[164:167], v[212:215], v[8:11]
	v_mfma_f32_16x16x32_bf16 v[60:63], v[160:163], v[192:195], v[60:63]
	v_mfma_f32_16x16x32_bf16 v[56:59], v[168:171], v[192:195], v[56:59]
	v_mfma_f32_16x16x32_bf16 v[44:47], v[160:163], v[200:203], v[44:47]
	v_mfma_f32_16x16x32_bf16 v[40:43], v[168:171], v[200:203], v[40:43]
	v_mfma_f32_16x16x32_bf16 v[28:31], v[160:163], v[208:211], v[28:31]
	v_mfma_f32_16x16x32_bf16 v[24:27], v[168:171], v[208:211], v[24:27]
	v_mfma_f32_16x16x32_bf16 v[12:15], v[160:163], v[216:219], v[12:15]
	v_mfma_f32_16x16x32_bf16 v[8:11], v[168:171], v[216:219], v[8:11]
	s_setprio 0
	s_setprio 1
	v_mfma_f32_16x16x32_bf16 v[52:55], v[172:175], v[188:191], v[52:55]
	v_mfma_f32_16x16x32_bf16 v[48:51], v[180:183], v[188:191], v[48:51]
	v_mfma_f32_16x16x32_bf16 v[36:39], v[172:175], v[196:199], v[36:39]
	v_mfma_f32_16x16x32_bf16 v[32:35], v[180:183], v[196:199], v[32:35]
	v_mfma_f32_16x16x32_bf16 v[20:23], v[172:175], v[204:207], v[20:23]
	v_mfma_f32_16x16x32_bf16 v[16:19], v[180:183], v[204:207], v[16:19]
	v_mfma_f32_16x16x32_bf16 v[4:7], v[172:175], v[212:215], v[4:7]
	v_mfma_f32_16x16x32_bf16 v[0:3], v[180:183], v[212:215], v[0:3]
	v_mfma_f32_16x16x32_bf16 v[52:55], v[176:179], v[192:195], v[52:55]
	v_mfma_f32_16x16x32_bf16 v[48:51], v[184:187], v[192:195], v[48:51]
	v_mfma_f32_16x16x32_bf16 v[36:39], v[176:179], v[200:203], v[36:39]
	v_mfma_f32_16x16x32_bf16 v[32:35], v[184:187], v[200:203], v[32:35]
	v_mfma_f32_16x16x32_bf16 v[20:23], v[176:179], v[208:211], v[20:23]
	v_mfma_f32_16x16x32_bf16 v[16:19], v[184:187], v[208:211], v[16:19]
	v_mfma_f32_16x16x32_bf16 v[4:7], v[176:179], v[216:219], v[4:7]
	v_mfma_f32_16x16x32_bf16 v[0:3], v[184:187], v[216:219], v[0:3]
	s_setprio 0
	s_barrier
	s_add_i32 s62, s62, 2
	s_add_u32 s34, s34, 0x100
	s_addc_u32 s35, s35, 0
	s_add_u32 s60, s60, 0x100
	s_addc_u32 s61, s61, 0
	s_cmp_gt_u32 s62, 13
	s_cbranch_scc0 .LBB0_1341
	s_and_b64 vcc, exec, s[16:17]
	s_cbranch_vccz .LBB0_1344
	s_barrier

; #define PG8_STAGE(bufoff, gbase, voff) do { _Pragma("unroll") for (int _i = 0; _i < 2; ++_i) \
;         __builtin_amdgcn_global_load_lds((const unsigned*)((const char*)(gbase) + (voff)[_i]), (PG8_LAS unsigned*)(lds + (bufoff) + ldsw + _i * 8192), 16, 0, 0); } while (0)
; #define PG8_LDA(dst, b, h) do { _Pragma("unroll") for (int m = 0; m < 4; ++m) _Pragma("unroll") for (int k = 0; k < 2; ++k) dst[m][k] = *(const PG8_LAS bf16x8*)(lds + PG8_SA(b, h) + aoff + m * 2048 + k * 1024); } while (0)
; #define PG8_LDB(dst, b, h) do { _Pragma("unroll") for (int n = 0; n < 2; ++n) _Pragma("unroll") for (int k = 0; k < 2; ++k) dst[n][k] = *(const PG8_LAS bf16x8*)(lds + PG8_SB(b, h) + boff + n * 2048 + k * 1024); } while (0)
; #define PG8_MMA(ai, bj, At, Bt) do { __builtin_amdgcn_s_setprio(1); _Pragma("unroll") for (int m = 0; m < 4; ++m) _Pragma("unroll") for (int n = 0; n < 2; ++n) _Pragma("unroll") for (int k = 0; k < 2; ++k) \
;         acc[ai][bj][m][n] = __builtin_amdgcn_mfma_f32_16x16x32_bf16(Bt[n][k], At[m][k], acc[ai][bj][m][n], 0, 0, 0); __builtin_amdgcn_s_setprio(0); } while (0)
; #define PG8_WAIT_V(n) asm volatile("s_waitcnt vmcnt(" #n ")" ::: "memory")
; #define PG8_WAIT_L(n) asm volatile("s_waitcnt lgkmcnt(" #n ")" ::: "memory")
; #define PG8_BAR __builtin_amdgcn_s_barrier()
; #define PG8_SCHED __builtin_amdgcn_sched_barrier(0)
;     ...
;             const bool last = (t == nt - 2);
;             const char* a1 = cA + (size_t)(t + 1) * kstep;
;             const char* a2 = last ? nA : cA + (size_t)(t + 2) * kstep; const char* b2 = last ? nB : cB + (size_t)(t + 2) * kstep;
;             const char* a3 = a2 + kstep; const char* b3 = b2 + kstep;
;             if (last && has_next) S.a_ready(nxt);
;             if constexpr (SP2) {
;             PG8_LDB(B0, 0, 0); PG8_LDB(B1, 0, 1); PG8_SCHED; PG8_LDA(At, 0, 0); PG8_STAGE(PG8_SA(1, 1), a1 + hstepA, voffA);
;             PG8_WAIT_V(8); PG8_WAIT_L(0); PG8_BAR; PG8_MMA(0, 0, At, B0); PG8_MMA(0, 1, At, B1); PG8_BAR; PG8_SCHED;
;             PG8_LDA(At, 0, 1); PG8_STAGE(PG8_SB(0, 0), b2, voffB); PG8_STAGE(PG8_SB(0, 1), b2 + hstepB, voffB); PG8_STAGE(PG8_SA(0, 0), a2, voffA);
.LBB0_1414:
	ds_read_b128 v[128:131], v163
	ds_read_b128 v[132:135], v163 offset:1024
	ds_read_b128 v[152:155], v163 offset:2048
	ds_read_b128 v[156:159], v163 offset:3072
	ds_read_b128 v[166:169], v164
	ds_read_b128 v[170:173], v164 offset:1024
	ds_read_b128 v[174:177], v164 offset:2048
	ds_read_b128 v[178:181], v164 offset:3072
	s_add_u32 s28, s26, 0xfff00080
	s_addc_u32 s29, s27, -1
	s_cmp_eq_u32 s52, 60
	s_cselect_b32 s35, s21, s29
	s_cselect_b32 s34, s48, s28
	s_cselect_b32 s29, s19, s51
	s_cselect_b32 s28, s49, s50
	v_lshl_add_u64 v[160:161], s[26:27], 0, v[144:145]
	s_add_i32 m0, s8, 0xc000
	ds_read_b128 v[182:185], v165
	ds_read_b128 v[186:189], v165 offset:1024
	ds_read_b128 v[190:193], v165 offset:2048
	ds_read_b128 v[194:197], v165 offset:3072
	ds_read_b128 v[198:201], v165 offset:4096
	ds_read_b128 v[202:205], v165 offset:5120
	ds_read_b128 v[206:209], v165 offset:6144
	ds_read_b128 v[210:213], v165 offset:7168
	global_load_lds_dwordx4 v[160:161], off
	v_lshl_add_u64 v[160:161], s[26:27], 0, v[146:147]
	s_add_i32 m0, s8, 0xe000
	s_nop 0
	global_load_lds_dwordx4 v[160:161], off
	s_waitcnt vmcnt(8)
	s_waitcnt lgkmcnt(0)
	s_barrier
	s_setprio 1
	s_waitcnt lgkmcnt(0)
	v_mfma_f32_16x16x32_bf16 v[124:127], v[128:131], v[182:185], v[124:127]
	v_mfma_f32_16x16x32_bf16 v[120:123], v[152:155], v[182:185], v[120:123]
	v_mfma_f32_16x16x32_bf16 v[108:111], v[128:131], v[190:193], v[108:111]
	v_mfma_f32_16x16x32_bf16 v[104:107], v[152:155], v[190:193], v[104:107]
	v_mfma_f32_16x16x32_bf16 v[92:95], v[128:131], v[198:201], v[92:95]
	v_mfma_f32_16x16x32_bf16 v[88:91], v[152:155], v[198:201], v[88:91]
	v_mfma_f32_16x16x32_bf16 v[76:79], v[128:131], v[206:209], v[76:79]
	v_mfma_f32_16x16x32_bf16 v[72:75], v[152:155], v[206:209], v[72:75]
	v_mfma_f32_16x16x32_bf16 v[124:127], v[132:135], v[186:189], v[124:127]
	v_mfma_f32_16x16x32_bf16 v[120:123], v[156:159], v[186:189], v[120:123]
	v_mfma_f32_16x16x32_bf16 v[108:111], v[132:135], v[194:197], v[108:111]
	v_mfma_f32_16x16x32_bf16 v[104:107], v[156:159], v[194:197], v[104:107]
	v_mfma_f32_16x16x32_bf16 v[92:95], v[132:135], v[202:205], v[92:95]
	v_mfma_f32_16x16x32_bf16 v[88:91], v[156:159], v[202:205], v[88:91]
	v_mfma_f32_16x16x32_bf16 v[76:79], v[132:135], v[210:213], v[76:79]
	v_mfma_f32_16x16x32_bf16 v[72:75], v[156:159], v[210:213], v[72:75]
	s_setprio 0
	s_setprio 1
	v_mfma_f32_16x16x32_bf16 v[116:119], v[166:169], v[182:185], v[116:119]
	v_mfma_f32_16x16x32_bf16 v[112:115], v[174:177], v[182:185], v[112:115]
	v_mfma_f32_16x16x32_bf16 v[100:103], v[166:169], v[190:193], v[100:103]
	v_mfma_f32_16x16x32_bf16 v[96:99], v[174:177], v[190:193], v[96:99]
	v_mfma_f32_16x16x32_bf16 v[84:87], v[166:169], v[198:201], v[84:87]
	v_mfma_f32_16x16x32_bf16 v[80:83], v[174:177], v[198:201], v[80:83]
	v_mfma_f32_16x16x32_bf16 v[68:71], v[166:169], v[206:209], v[68:71]
	v_mfma_f32_16x16x32_bf16 v[64:67], v[174:177], v[206:209], v[64:67]
	v_mfma_f32_16x16x32_bf16 v[116:119], v[170:173], v[186:189], v[116:119]
	v_mfma_f32_16x16x32_bf16 v[112:115], v[178:181], v[186:189], v[112:115]
	v_mfma_f32_16x16x32_bf16 v[100:103], v[170:173], v[194:197], v[100:103]
	v_mfma_f32_16x16x32_bf16 v[96:99], v[178:181], v[194:197], v[96:99]
	v_mfma_f32_16x16x32_bf16 v[84:87], v[170:173], v[202:205], v[84:87]
	v_mfma_f32_16x16x32_bf16 v[80:83], v[178:181], v[202:205], v[80:83]
	v_mfma_f32_16x16x32_bf16 v[68:71], v[170:173], v[210:213], v[68:71]
	v_mfma_f32_16x16x32_bf16 v[64:67], v[178:181], v[210:213], v[64:67]
	s_setprio 0
	s_barrier
	s_add_i32 s53, s46, s39
	s_mov_b32 m0, s53
	ds_read_b128 v[182:185], v165 offset:16384
	ds_read_b128 v[186:189], v165 offset:17408
	ds_read_b128 v[190:193], v165 offset:18432
	ds_read_b128 v[194:197], v165 offset:19456
	ds_read_b128 v[198:201], v165 offset:20480
	ds_read_b128 v[202:205], v165 offset:21504
	ds_read_b128 v[206:209], v165 offset:22528
	ds_read_b128 v[210:213], v165 offset:23552
	v_lshl_add_u64 v[160:161], s[28:29], 0, v[140:141]
	global_load_lds_dwordx4 v[160:161], off
	s_add_i32 m0, s53, 0x2000
	s_add_u32 s54, s28, 0x100000
	v_lshl_add_u64 v[214:215], s[28:29], 0, v[136:137]
	s_addc_u32 s55, s29, 0
	s_add_i32 s53, s47, s39
	global_load_lds_dwordx4 v[214:215], off
	v_lshl_add_u64 v[216:217], s[54:55], 0, v[140:141]
	s_mov_b32 m0, s53
	v_lshl_add_u64 v[218:219], s[34:35], 0, v[138:139]
	global_load_lds_dwordx4 v[216:217], off
	v_lshl_add_u64 v[216:217], s[54:55], 0, v[136:137]
	s_add_i32 m0, s53, 0x2000
	s_nop 0
	global_load_lds_dwordx4 v[216:217], off
	v_lshl_add_u64 v[216:217], s[34:35], 0, v[142:143]
	s_mov_b32 m0, s8
	s_nop 0
	global_load_lds_dwordx4 v[216:217], off
	s_mov_b32 m0, s13
	s_nop 0
	global_load_lds_dwordx4 v[218:219], off
	s_waitcnt vmcnt(8)
	s_waitcnt lgkmcnt(0)
	s_barrier
; #define PG8_STAGE(bufoff, gbase, voff) do { _Pragma("unroll") for (int _i = 0; _i < 2; ++_i) \
;         __builtin_amdgcn_global_load_lds((const unsigned*)((const char*)(gbase) + (voff)[_i]), (PG8_LAS unsigned*)(lds + (bufoff) + ldsw + _i * 8192), 16, 0, 0); } while (0)
; #define PG8_LDA(dst, b, h) do { _Pragma("unroll") for (int m = 0; m < 4; ++m) _Pragma("unroll") for (int k = 0; k < 2; ++k) dst[m][k] = *(const PG8_LAS bf16x8*)(lds + PG8_SA(b, h) + aoff + m * 2048 + k * 1024); } while (0)
; #define PG8_LDB(dst, b, h) do { _Pragma("unroll") for (int n = 0; n < 2; ++n) _Pragma("unroll") for (int k = 0; k < 2; ++k) dst[n][k] = *(const PG8_LAS bf16x8*)(lds + PG8_SB(b, h) + boff + n * 2048 + k * 1024); } while (0)
; #define PG8_MMA(ai, bj, At, Bt) do { __builtin_amdgcn_s_setprio(1); _Pragma("unroll") for (int m = 0; m < 4; ++m) _Pragma("unroll") for (int n = 0; n < 2; ++n) _Pragma("unroll") for (int k = 0; k < 2; ++k) \
;         acc[ai][bj][m][n] = __builtin_amdgcn_mfma_f32_16x16x32_bf16(Bt[n][k], At[m][k], acc[ai][bj][m][n], 0, 0, 0); __builtin_amdgcn_s_setprio(0); } while (0)
; #define PG8_WAIT_V(n) asm volatile("s_waitcnt vmcnt(" #n ")" ::: "memory")
; #define PG8_WAIT_L(n) asm volatile("s_waitcnt lgkmcnt(" #n ")" ::: "memory")
; #define PG8_BAR __builtin_amdgcn_s_barrier()
; #define PG8_SCHED __builtin_amdgcn_sched_barrier(0)
;     ...
;             PG8_WAIT_V(8); PG8_WAIT_L(0); PG8_BAR; PG8_MMA(1, 0, At, B0); PG8_MMA(1, 1, At, B1); PG8_BAR; PG8_SCHED;
;             PG8_LDB(B0, 1, 0); PG8_LDB(B1, 1, 1); PG8_SCHED; PG8_LDA(At, 1, 0); PG8_STAGE(PG8_SA(0, 1), a2 + hstepA, voffA);
;             PG8_WAIT_V(8); PG8_WAIT_L(0); PG8_BAR; PG8_MMA(0, 0, At, B0); PG8_MMA(0, 1, At, B1); PG8_BAR; PG8_SCHED;
	s_setprio 1
	s_waitcnt lgkmcnt(0)
	v_mfma_f32_16x16x32_bf16 v[60:63], v[128:131], v[182:185], v[60:63]
	v_mfma_f32_16x16x32_bf16 v[56:59], v[152:155], v[182:185], v[56:59]
	v_mfma_f32_16x16x32_bf16 v[48:51], v[128:131], v[190:193], v[48:51]
	v_mfma_f32_16x16x32_bf16 v[40:43], v[152:155], v[190:193], v[40:43]
	v_mfma_f32_16x16x32_bf16 v[32:35], v[128:131], v[198:201], v[32:35]
	v_mfma_f32_16x16x32_bf16 v[24:27], v[152:155], v[198:201], v[24:27]
	v_mfma_f32_16x16x32_bf16 v[16:19], v[128:131], v[206:209], v[16:19]
	v_mfma_f32_16x16x32_bf16 v[8:11], v[152:155], v[206:209], v[8:11]
	v_mfma_f32_16x16x32_bf16 v[60:63], v[132:135], v[186:189], v[60:63]
	v_mfma_f32_16x16x32_bf16 v[56:59], v[156:159], v[186:189], v[56:59]
	v_mfma_f32_16x16x32_bf16 v[48:51], v[132:135], v[194:197], v[48:51]
	v_mfma_f32_16x16x32_bf16 v[40:43], v[156:159], v[194:197], v[40:43]
	v_mfma_f32_16x16x32_bf16 v[32:35], v[132:135], v[202:205], v[32:35]
	v_mfma_f32_16x16x32_bf16 v[24:27], v[156:159], v[202:205], v[24:27]
	v_mfma_f32_16x16x32_bf16 v[16:19], v[132:135], v[210:213], v[16:19]
	v_mfma_f32_16x16x32_bf16 v[8:11], v[156:159], v[210:213], v[8:11]
	s_setprio 0
	s_setprio 1
	v_mfma_f32_16x16x32_bf16 v[52:55], v[166:169], v[182:185], v[52:55]
	v_mfma_f32_16x16x32_bf16 v[44:47], v[174:177], v[182:185], v[44:47]
	v_mfma_f32_16x16x32_bf16 v[36:39], v[166:169], v[190:193], v[36:39]
	v_mfma_f32_16x16x32_bf16 v[28:31], v[174:177], v[190:193], v[28:31]
	v_mfma_f32_16x16x32_bf16 v[20:23], v[166:169], v[198:201], v[20:23]
	v_mfma_f32_16x16x32_bf16 v[12:15], v[174:177], v[198:201], v[12:15]
	v_mfma_f32_16x16x32_bf16 v[4:7], v[166:169], v[206:209], v[4:7]
	v_mfma_f32_16x16x32_bf16 v[0:3], v[174:177], v[206:209], v[0:3]
	v_mfma_f32_16x16x32_bf16 v[52:55], v[170:173], v[186:189], v[52:55]
	v_mfma_f32_16x16x32_bf16 v[44:47], v[178:181], v[186:189], v[44:47]
	v_mfma_f32_16x16x32_bf16 v[36:39], v[170:173], v[194:197], v[36:39]
	v_mfma_f32_16x16x32_bf16 v[28:31], v[178:181], v[194:197], v[28:31]
	v_mfma_f32_16x16x32_bf16 v[20:23], v[170:173], v[202:205], v[20:23]
	v_mfma_f32_16x16x32_bf16 v[12:15], v[178:181], v[202:205], v[12:15]
	v_mfma_f32_16x16x32_bf16 v[4:7], v[170:173], v[210:213], v[4:7]
	v_mfma_f32_16x16x32_bf16 v[0:3], v[178:181], v[210:213], v[0:3]
	s_setprio 0
	s_barrier
	s_add_i32 s53, 0, 0x18000
	s_add_i32 s54, 0, 0x1c000
	v_add_u32_e32 v156, s53, v162
	v_add_u32_e32 v178, s54, v162
	ds_read_b128 v[128:131], v156
	ds_read_b128 v[132:135], v156 offset:1024
	ds_read_b128 v[152:155], v156 offset:2048
	ds_read_b128 v[156:159], v156 offset:3072
	ds_read_b128 v[166:169], v178
	ds_read_b128 v[170:173], v178 offset:1024
	ds_read_b128 v[174:177], v178 offset:2048
	ds_read_b128 v[178:181], v178 offset:3072
	s_add_u32 s34, s34, 0x100000
	s_addc_u32 s35, s35, 0
	s_mov_b32 m0, s40
	v_lshl_add_u64 v[220:221], s[34:35], 0, v[142:143]
	ds_read_b128 v[182:185], v165 offset:32768
	ds_read_b128 v[186:189], v165 offset:33792
	ds_read_b128 v[190:193], v165 offset:34816
	ds_read_b128 v[194:197], v165 offset:35840
	ds_read_b128 v[198:201], v165 offset:36864
	ds_read_b128 v[202:205], v165 offset:37888
	ds_read_b128 v[206:209], v165 offset:38912
	ds_read_b128 v[210:213], v165 offset:39936
	global_load_lds_dwordx4 v[220:221], off
	v_lshl_add_u64 v[220:221], s[34:35], 0, v[138:139]
	s_mov_b32 m0, s41
	s_nop 0
	global_load_lds_dwordx4 v[220:221], off
	s_waitcnt vmcnt(8)
	s_waitcnt lgkmcnt(0)
	s_barrier
	s_setprio 1
	s_waitcnt lgkmcnt(0)
	v_mfma_f32_16x16x32_bf16 v[124:127], v[128:131], v[182:185], v[124:127]
	v_mfma_f32_16x16x32_bf16 v[120:123], v[152:155], v[182:185], v[120:123]
	v_mfma_f32_16x16x32_bf16 v[108:111], v[128:131], v[190:193], v[108:111]
	v_mfma_f32_16x16x32_bf16 v[104:107], v[152:155], v[190:193], v[104:107]
	v_mfma_f32_16x16x32_bf16 v[92:95], v[128:131], v[198:201], v[92:95]
	v_mfma_f32_16x16x32_bf16 v[88:91], v[152:155], v[198:201], v[88:91]
	v_mfma_f32_16x16x32_bf16 v[76:79], v[128:131], v[206:209], v[76:79]
	v_mfma_f32_16x16x32_bf16 v[72:75], v[152:155], v[206:209], v[72:75]
	v_mfma_f32_16x16x32_bf16 v[124:127], v[132:135], v[186:189], v[124:127]
	v_mfma_f32_16x16x32_bf16 v[120:123], v[156:159], v[186:189], v[120:123]
	v_mfma_f32_16x16x32_bf16 v[108:111], v[132:135], v[194:197], v[108:111]
	v_mfma_f32_16x16x32_bf16 v[104:107], v[156:159], v[194:197], v[104:107]
	v_mfma_f32_16x16x32_bf16 v[92:95], v[132:135], v[202:205], v[92:95]
	v_mfma_f32_16x16x32_bf16 v[88:91], v[156:159], v[202:205], v[88:91]
	v_mfma_f32_16x16x32_bf16 v[76:79], v[132:135], v[210:213], v[76:79]
	v_mfma_f32_16x16x32_bf16 v[72:75], v[156:159], v[210:213], v[72:75]
	s_setprio 0
	s_setprio 1
	v_mfma_f32_16x16x32_bf16 v[116:119], v[166:169], v[182:185], v[116:119]
	v_mfma_f32_16x16x32_bf16 v[112:115], v[174:177], v[182:185], v[112:115]
	v_mfma_f32_16x16x32_bf16 v[100:103], v[166:169], v[190:193], v[100:103]
	v_mfma_f32_16x16x32_bf16 v[96:99], v[174:177], v[190:193], v[96:99]
	v_mfma_f32_16x16x32_bf16 v[84:87], v[166:169], v[198:201], v[84:87]
	v_mfma_f32_16x16x32_bf16 v[80:83], v[174:177], v[198:201], v[80:83]
	v_mfma_f32_16x16x32_bf16 v[68:71], v[166:169], v[206:209], v[68:71]
	v_mfma_f32_16x16x32_bf16 v[64:67], v[174:177], v[206:209], v[64:67]
	v_mfma_f32_16x16x32_bf16 v[116:119], v[170:173], v[186:189], v[116:119]
	v_mfma_f32_16x16x32_bf16 v[112:115], v[178:181], v[186:189], v[112:115]
	v_mfma_f32_16x16x32_bf16 v[100:103], v[170:173], v[194:197], v[100:103]
	v_mfma_f32_16x16x32_bf16 v[96:99], v[178:181], v[194:197], v[96:99]
	v_mfma_f32_16x16x32_bf16 v[84:87], v[170:173], v[202:205], v[84:87]
	v_mfma_f32_16x16x32_bf16 v[80:83], v[178:181], v[202:205], v[80:83]
	v_mfma_f32_16x16x32_bf16 v[68:71], v[170:173], v[210:213], v[68:71]
	v_mfma_f32_16x16x32_bf16 v[64:67], v[178:181], v[210:213], v[64:67]
	s_setprio 0
	s_barrier
; #define PG8_STAGE(bufoff, gbase, voff) do { _Pragma("unroll") for (int _i = 0; _i < 2; ++_i) \
;         __builtin_amdgcn_global_load_lds((const unsigned*)((const char*)(gbase) + (voff)[_i]), (PG8_LAS unsigned*)(lds + (bufoff) + ldsw + _i * 8192), 16, 0, 0); } while (0)
; #define PG8_LDA(dst, b, h) do { _Pragma("unroll") for (int m = 0; m < 4; ++m) _Pragma("unroll") for (int k = 0; k < 2; ++k) dst[m][k] = *(const PG8_LAS bf16x8*)(lds + PG8_SA(b, h) + aoff + m * 2048 + k * 1024); } while (0)
; #define PG8_MMA(ai, bj, At, Bt) do { __builtin_amdgcn_s_setprio(1); _Pragma("unroll") for (int m = 0; m < 4; ++m) _Pragma("unroll") for (int n = 0; n < 2; ++n) _Pragma("unroll") for (int k = 0; k < 2; ++k) \
;         acc[ai][bj][m][n] = __builtin_amdgcn_mfma_f32_16x16x32_bf16(Bt[n][k], At[m][k], acc[ai][bj][m][n], 0, 0, 0); __builtin_amdgcn_s_setprio(0); } while (0)
; #define PG8_WAIT_V(n) asm volatile("s_waitcnt vmcnt(" #n ")" ::: "memory")
; #define PG8_WAIT_L(n) asm volatile("s_waitcnt lgkmcnt(" #n ")" ::: "memory")
; #define PG8_BAR __builtin_amdgcn_s_barrier()
; #define PG8_SCHED __builtin_amdgcn_sched_barrier(0)
;     ...
;         for (int t = 0; t < nt; t += 2) {
;     ...
;             PG8_LDA(At, 1, 1); PG8_STAGE(PG8_SB(1, 0), b3, voffB); PG8_STAGE(PG8_SB(1, 1), b3 + hstepB, voffB); PG8_STAGE(PG8_SA(1, 0), a3, voffA);
;             PG8_WAIT_V(8); PG8_WAIT_L(0); PG8_BAR; PG8_MMA(1, 0, At, B0); PG8_MMA(1, 1, At, B1); PG8_BAR; PG8_SCHED;
	s_add_i32 s34, s53, s39
	s_mov_b32 m0, s34
	ds_read_b128 v[182:185], v165 offset:49152
	ds_read_b128 v[186:189], v165 offset:50176
	ds_read_b128 v[190:193], v165 offset:51200
	ds_read_b128 v[194:197], v165 offset:52224
	ds_read_b128 v[198:201], v165 offset:53248
	ds_read_b128 v[202:205], v165 offset:54272
	ds_read_b128 v[206:209], v165 offset:55296
	ds_read_b128 v[210:213], v165 offset:56320
	v_lshl_add_u64 v[160:161], v[160:161], 0, s[14:15]
	global_load_lds_dwordx4 v[160:161], off
	s_add_i32 m0, s34, 0x2000
	s_add_u32 s28, s28, 0x100080
	v_lshl_add_u64 v[160:161], v[214:215], 0, s[14:15]
	s_addc_u32 s29, s29, 0
	s_add_i32 s34, s54, s39
	global_load_lds_dwordx4 v[160:161], off
	v_lshl_add_u64 v[160:161], s[28:29], 0, v[140:141]
	s_mov_b32 m0, s34
	s_nop 0
	global_load_lds_dwordx4 v[160:161], off
	v_lshl_add_u64 v[160:161], s[28:29], 0, v[136:137]
	s_add_i32 m0, s34, 0x2000
	s_nop 0
	global_load_lds_dwordx4 v[160:161], off
	v_lshl_add_u64 v[160:161], v[216:217], 0, s[14:15]
	s_mov_b32 m0, s44
	s_nop 0
	global_load_lds_dwordx4 v[160:161], off
	v_lshl_add_u64 v[160:161], v[218:219], 0, s[14:15]
	s_mov_b32 m0, s45
	s_nop 0
	global_load_lds_dwordx4 v[160:161], off
	s_waitcnt vmcnt(8)
	s_waitcnt lgkmcnt(0)
	s_barrier
	s_setprio 1
	s_waitcnt lgkmcnt(0)
	v_mfma_f32_16x16x32_bf16 v[60:63], v[128:131], v[182:185], v[60:63]
	v_mfma_f32_16x16x32_bf16 v[56:59], v[152:155], v[182:185], v[56:59]
	v_mfma_f32_16x16x32_bf16 v[48:51], v[128:131], v[190:193], v[48:51]
	v_mfma_f32_16x16x32_bf16 v[40:43], v[152:155], v[190:193], v[40:43]
	v_mfma_f32_16x16x32_bf16 v[32:35], v[128:131], v[198:201], v[32:35]
	v_mfma_f32_16x16x32_bf16 v[24:27], v[152:155], v[198:201], v[24:27]
	v_mfma_f32_16x16x32_bf16 v[16:19], v[128:131], v[206:209], v[16:19]
	v_mfma_f32_16x16x32_bf16 v[8:11], v[152:155], v[206:209], v[8:11]
	v_mfma_f32_16x16x32_bf16 v[60:63], v[132:135], v[186:189], v[60:63]
	v_mfma_f32_16x16x32_bf16 v[56:59], v[156:159], v[186:189], v[56:59]
	v_mfma_f32_16x16x32_bf16 v[48:51], v[132:135], v[194:197], v[48:51]
	v_mfma_f32_16x16x32_bf16 v[40:43], v[156:159], v[194:197], v[40:43]
	v_mfma_f32_16x16x32_bf16 v[32:35], v[132:135], v[202:205], v[32:35]
	v_mfma_f32_16x16x32_bf16 v[24:27], v[156:159], v[202:205], v[24:27]
	v_mfma_f32_16x16x32_bf16 v[16:19], v[132:135], v[210:213], v[16:19]
	v_mfma_f32_16x16x32_bf16 v[8:11], v[156:159], v[210:213], v[8:11]
	s_setprio 0
	s_setprio 1
	v_mfma_f32_16x16x32_bf16 v[52:55], v[166:169], v[182:185], v[52:55]
	v_mfma_f32_16x16x32_bf16 v[44:47], v[174:177], v[182:185], v[44:47]
	v_mfma_f32_16x16x32_bf16 v[36:39], v[166:169], v[190:193], v[36:39]
	v_mfma_f32_16x16x32_bf16 v[28:31], v[174:177], v[190:193], v[28:31]
	v_mfma_f32_16x16x32_bf16 v[20:23], v[166:169], v[198:201], v[20:23]
	v_mfma_f32_16x16x32_bf16 v[12:15], v[174:177], v[198:201], v[12:15]
	v_mfma_f32_16x16x32_bf16 v[4:7], v[166:169], v[206:209], v[4:7]
	v_mfma_f32_16x16x32_bf16 v[0:3], v[174:177], v[206:209], v[0:3]
	v_mfma_f32_16x16x32_bf16 v[52:55], v[170:173], v[186:189], v[52:55]
	v_mfma_f32_16x16x32_bf16 v[44:47], v[178:181], v[186:189], v[44:47]
	v_mfma_f32_16x16x32_bf16 v[36:39], v[170:173], v[194:197], v[36:39]
	v_mfma_f32_16x16x32_bf16 v[28:31], v[178:181], v[194:197], v[28:31]
	v_mfma_f32_16x16x32_bf16 v[20:23], v[170:173], v[202:205], v[20:23]
	v_mfma_f32_16x16x32_bf16 v[12:15], v[178:181], v[202:205], v[12:15]
	v_mfma_f32_16x16x32_bf16 v[4:7], v[170:173], v[210:213], v[4:7]
	v_mfma_f32_16x16x32_bf16 v[0:3], v[178:181], v[210:213], v[0:3]
	s_setprio 0
	s_barrier
	s_add_i32 s52, s52, 2
	s_add_u32 s26, s26, 0x100
	s_addc_u32 s27, s27, 0
	s_add_u32 s50, s50, 0x100
	s_addc_u32 s51, s51, 0
	s_cmp_gt_u32 s52, 61
	s_cbranch_scc0 .LBB0_1414
	s_and_b64 vcc, exec, s[16:17]
	s_cbranch_vccz .LBB0_1417
	s_barrier
